# v25 + first-iteration fragment reads (14 of 16 ds_read_b128) issued at the K-loop exit / first entry so they overlap the unit epilogue
# speedup vs baseline: 1.0119x; 1.0056x over previous
.LBB0_208:
	s_lshl_b32 s16, s16, 5
	s_and_b32 s22, s16, 0x60
	s_mov_b64 s[16:17], 0x80
	s_add_i32 m0, s35, 0x18000
	v_lshl_add_u64 v[8:9], v[8:9], 0, s[16:17]
	s_lshl_b32 s19, s7, 13
	s_lshl_b32 s23, s22, 7
	s_waitcnt vmcnt(2)
	s_barrier
	global_load_lds_dwordx4 v[8:9], off
	v_lshl_add_u64 v[4:5], v[4:5], 0, s[16:17]
	s_add_i32 m0, s35, 0x1a000
	s_add_i32 s50, s35, 0x8000
	s_add_i32 s51, s35, 0xa000
	global_load_lds_dwordx4 v[4:5], off
	v_lshl_add_u64 v[4:5], v[6:7], 0, s[16:17]
	s_mov_b32 m0, s50
	s_add_u32 s20, s40, 0x80080
	global_load_lds_dwordx4 v[4:5], off
	v_lshl_add_u64 v[4:5], v[10:11], 0, s[16:17]
	s_mov_b32 m0, s51
	s_addc_u32 s21, s41, 0
	global_load_lds_dwordx4 v[4:5], off
	s_add_i32 m0, s35, 0x1c000
	v_lshl_add_u64 v[4:5], s[20:21], 0, v[132:133]
	global_load_lds_dwordx4 v[4:5], off
	v_lshl_add_u64 v[4:5], s[20:21], 0, v[136:137]
	s_add_i32 m0, s35, 0x1e000
	v_and_b32_e32 v3, 15, v0
	global_load_lds_dwordx4 v[4:5], off
	v_lshlrev_b32_e32 v4, 1, v15
	v_lshlrev_b32_e32 v5, 2, v0
	v_lshl_or_b32 v146, s7, 6, v3
	v_lshl_or_b32 v3, v3, 6, v4
	v_and_b32_e32 v5, 32, v5
	v_bitop3_b32 v6, v3, s19, v5 bitop3:0xde
	v_lshlrev_b32_e32 v3, 6, v0
	s_movk_i32 s7, 0x3c0
	v_readlane_b32 s21, v249, 0
	v_and_or_b32 v3, v3, s7, v4
	s_ashr_i32 s19, s21, 31
	v_bitop3_b32 v147, s23, v3, v5 bitop3:0xf6
	s_lshr_b32 s19, s19, 26
	v_mov_b32_e32 v3, v133
	s_add_i32 s19, s21, s19
	v_lshl_add_u64 v[138:139], s[78:79], 0, v[2:3]
	v_lshlrev_b32_e32 v2, 9, v0
	s_and_b32 s20, s19, 0xffffffc0
	v_and_b32_e32 v2, 0x30000, v2
	v_lshlrev_b32_e32 v3, 12, v14
	s_sub_i32 s52, s21, s20
	s_ashr_i32 s19, s19, 6
	v_or3_b32 v2, v12, v2, v3
	s_addk_i32 s52, 0x800
	s_lshl_b32 s53, s19, 3
	v_add_u32_e32 v140, v2, v13
	v_lshlrev_b32_e32 v2, 5, v16
	s_waitcnt vmcnt(6)
	s_cmpk_lt_u32 s18, 0x100
	v_and_b32_e32 v2, 0x70000, v2
	s_mov_b32 s7, 0
	s_cselect_b64 s[18:19], -1, 0
	v_or3_b32 v2, v12, v2, v3
	s_add_i32 s54, 0, 0x10000
	s_add_i32 s55, 0, 0x14000
	v_or_b32_e32 v148, s22, v15
	v_mov_b32_e32 v141, v133
	v_add_u32_e32 v142, v2, v13
	v_mov_b32_e32 v143, v133
	v_add_u32_e32 v149, s54, v147
	v_add_u32_e32 v150, s55, v147
	v_add_u32_e32 v151, 0, v6
	s_mov_b32 s56, 0xc000
	s_mov_b32 s57, 0xe000
	s_movk_i32 s58, 0x2c00
	s_mov_b32 s31, s7
	s_barrier
	ds_read_b128 v[160:163], v149 offset:2048
	ds_read_b128 v[164:167], v149 offset:3072
	ds_read_b128 v[168:171], v150
	ds_read_b128 v[172:175], v150 offset:1024
	ds_read_b128 v[176:179], v150 offset:2048
	ds_read_b128 v[180:183], v150 offset:3072
	ds_read_b128 v[184:187], v151
	ds_read_b128 v[188:191], v151 offset:1024
	ds_read_b128 v[196:199], v151 offset:2048
	ds_read_b128 v[200:203], v151 offset:3072
	ds_read_b128 v[204:207], v151 offset:4096
	ds_read_b128 v[208:211], v151 offset:5120
	ds_read_b128 v[212:215], v151 offset:6144
	ds_read_b128 v[216:219], v151 offset:7168
	s_branch .LBB0_211

.Lpeel_13:
	ds_read_b128 v[152:155], v149
	ds_read_b128 v[156:159], v149 offset:1024
	s_add_i32 s37, s25, 2
	s_add_u32 s40, s38, 0xfff80080
	s_addc_u32 s41, s39, -1
	s_cmp_eq_u32 s36, s25
	s_cselect_b32 s43, s27, s41
	s_cselect_b32 s42, s26, s40
	s_cselect_b32 s41, s29, s23
	s_cselect_b32 s40, s28, s21
	v_lshl_add_u64 v[144:145], s[38:39], 0, v[140:141]
	s_add_i32 m0, s35, 0xc000
	global_load_lds_dwordx4 v[144:145], off
	v_lshl_add_u64 v[144:145], s[38:39], 0, v[142:143]
	s_add_i32 m0, s35, 0xe000
	s_nop 0
	global_load_lds_dwordx4 v[144:145], off
	s_waitcnt vmcnt(8)
	s_waitcnt lgkmcnt(0)
	s_barrier
	s_setprio 1
	s_waitcnt lgkmcnt(0)
	v_mfma_f32_16x16x32_bf16 v[126:129], v[152:155], v[184:187], 0
	v_mfma_f32_16x16x32_bf16 v[122:125], v[160:163], v[184:187], 0
	v_mfma_f32_16x16x32_bf16 v[110:113], v[152:155], v[196:199], 0
	v_mfma_f32_16x16x32_bf16 v[106:109], v[160:163], v[196:199], 0
	v_mfma_f32_16x16x32_bf16 v[94:97], v[152:155], v[204:207], 0
	v_mfma_f32_16x16x32_bf16 v[90:93], v[160:163], v[204:207], 0
	v_mfma_f32_16x16x32_bf16 v[78:81], v[152:155], v[212:215], 0
	v_mfma_f32_16x16x32_bf16 v[74:77], v[160:163], v[212:215], 0
	v_mfma_f32_16x16x32_bf16 v[126:129], v[156:159], v[188:191], v[126:129]
	v_mfma_f32_16x16x32_bf16 v[122:125], v[164:167], v[188:191], v[122:125]
	v_mfma_f32_16x16x32_bf16 v[110:113], v[156:159], v[200:203], v[110:113]
	v_mfma_f32_16x16x32_bf16 v[106:109], v[164:167], v[200:203], v[106:109]
	v_mfma_f32_16x16x32_bf16 v[94:97], v[156:159], v[208:211], v[94:97]
	v_mfma_f32_16x16x32_bf16 v[90:93], v[164:167], v[208:211], v[90:93]
	v_mfma_f32_16x16x32_bf16 v[78:81], v[156:159], v[216:219], v[78:81]
	v_mfma_f32_16x16x32_bf16 v[74:77], v[164:167], v[216:219], v[74:77]
	s_setprio 0
	s_setprio 1
	v_mfma_f32_16x16x32_bf16 v[118:121], v[168:171], v[184:187], 0
	v_mfma_f32_16x16x32_bf16 v[114:117], v[176:179], v[184:187], 0
	v_mfma_f32_16x16x32_bf16 v[102:105], v[168:171], v[196:199], 0
	v_mfma_f32_16x16x32_bf16 v[98:101], v[176:179], v[196:199], 0
	v_mfma_f32_16x16x32_bf16 v[86:89], v[168:171], v[204:207], 0
	v_mfma_f32_16x16x32_bf16 v[82:85], v[176:179], v[204:207], 0
	v_mfma_f32_16x16x32_bf16 v[70:73], v[168:171], v[212:215], 0
	v_mfma_f32_16x16x32_bf16 v[66:69], v[176:179], v[212:215], 0
	v_mfma_f32_16x16x32_bf16 v[118:121], v[172:175], v[188:191], v[118:121]
	v_mfma_f32_16x16x32_bf16 v[114:117], v[180:183], v[188:191], v[114:117]
	v_mfma_f32_16x16x32_bf16 v[102:105], v[172:175], v[200:203], v[102:105]
	v_mfma_f32_16x16x32_bf16 v[98:101], v[180:183], v[200:203], v[98:101]
	v_mfma_f32_16x16x32_bf16 v[86:89], v[172:175], v[208:211], v[86:89]
	v_mfma_f32_16x16x32_bf16 v[82:85], v[180:183], v[208:211], v[82:85]
	v_mfma_f32_16x16x32_bf16 v[70:73], v[172:175], v[216:219], v[70:73]
	v_mfma_f32_16x16x32_bf16 v[66:69], v[180:183], v[216:219], v[66:69]
	s_setprio 0
	s_barrier
	s_add_i32 s25, s54, s33
	v_lshl_add_u64 v[144:145], s[40:41], 0, v[132:133]
	s_mov_b32 m0, s25
	ds_read_b128 v[184:187], v151 offset:16384
	ds_read_b128 v[188:191], v151 offset:17408
	ds_read_b128 v[196:199], v151 offset:18432
	ds_read_b128 v[200:203], v151 offset:19456
	ds_read_b128 v[204:207], v151 offset:20480
	ds_read_b128 v[208:211], v151 offset:21504
	ds_read_b128 v[212:215], v151 offset:22528
	ds_read_b128 v[216:219], v151 offset:23552
	global_load_lds_dwordx4 v[144:145], off
	s_add_i32 m0, s25, 0x2000
	s_add_u32 s44, s40, 0x80000
	v_lshl_add_u64 v[192:193], s[40:41], 0, v[136:137]
	s_addc_u32 s45, s41, 0
	s_add_i32 s25, s55, s33
	global_load_lds_dwordx4 v[192:193], off
	v_lshl_add_u64 v[220:221], s[44:45], 0, v[132:133]
	s_mov_b32 m0, s25
	v_lshl_add_u64 v[222:223], s[42:43], 0, v[134:135]
	global_load_lds_dwordx4 v[220:221], off
	v_lshl_add_u64 v[220:221], s[44:45], 0, v[136:137]
	s_add_i32 m0, s25, 0x2000
	s_nop 0
	global_load_lds_dwordx4 v[220:221], off
	v_lshl_add_u64 v[220:221], s[42:43], 0, v[130:131]
	s_mov_b32 m0, s35
	s_nop 0
	global_load_lds_dwordx4 v[220:221], off
	s_mov_b32 m0, s47
	s_nop 0
	global_load_lds_dwordx4 v[222:223], off
	s_waitcnt vmcnt(8)
	s_waitcnt lgkmcnt(0)
	s_barrier
	s_setprio 1
	s_waitcnt lgkmcnt(0)
	v_mfma_f32_16x16x32_bf16 v[62:65], v[152:155], v[184:187], 0
	v_mfma_f32_16x16x32_bf16 v[58:61], v[160:163], v[184:187], 0
	v_mfma_f32_16x16x32_bf16 v[46:49], v[152:155], v[196:199], 0
	v_mfma_f32_16x16x32_bf16 v[42:45], v[160:163], v[196:199], 0
	v_mfma_f32_16x16x32_bf16 v[30:33], v[152:155], v[204:207], 0
	v_mfma_f32_16x16x32_bf16 v[26:29], v[160:163], v[204:207], 0
	v_mfma_f32_16x16x32_bf16 v[14:17], v[152:155], v[212:215], 0
	v_mfma_f32_16x16x32_bf16 v[10:13], v[160:163], v[212:215], 0
	v_mfma_f32_16x16x32_bf16 v[62:65], v[156:159], v[188:191], v[62:65]
	v_mfma_f32_16x16x32_bf16 v[58:61], v[164:167], v[188:191], v[58:61]
	v_mfma_f32_16x16x32_bf16 v[46:49], v[156:159], v[200:203], v[46:49]
	v_mfma_f32_16x16x32_bf16 v[42:45], v[164:167], v[200:203], v[42:45]
	v_mfma_f32_16x16x32_bf16 v[30:33], v[156:159], v[208:211], v[30:33]
	v_mfma_f32_16x16x32_bf16 v[26:29], v[164:167], v[208:211], v[26:29]
	v_mfma_f32_16x16x32_bf16 v[14:17], v[156:159], v[216:219], v[14:17]
	v_mfma_f32_16x16x32_bf16 v[10:13], v[164:167], v[216:219], v[10:13]
	s_setprio 0
	s_setprio 1
	v_mfma_f32_16x16x32_bf16 v[54:57], v[168:171], v[184:187], 0
	v_mfma_f32_16x16x32_bf16 v[50:53], v[176:179], v[184:187], 0
	v_mfma_f32_16x16x32_bf16 v[38:41], v[168:171], v[196:199], 0
	v_mfma_f32_16x16x32_bf16 v[34:37], v[176:179], v[196:199], 0
	v_mfma_f32_16x16x32_bf16 v[22:25], v[168:171], v[204:207], 0
	v_mfma_f32_16x16x32_bf16 v[18:21], v[176:179], v[204:207], 0
	v_mfma_f32_16x16x32_bf16 v[6:9], v[168:171], v[212:215], 0
	v_mfma_f32_16x16x32_bf16 v[2:5], v[176:179], v[212:215], 0
	v_mfma_f32_16x16x32_bf16 v[54:57], v[172:175], v[188:191], v[54:57]
	v_mfma_f32_16x16x32_bf16 v[50:53], v[180:183], v[188:191], v[50:53]
	v_mfma_f32_16x16x32_bf16 v[38:41], v[172:175], v[200:203], v[38:41]
	v_mfma_f32_16x16x32_bf16 v[34:37], v[180:183], v[200:203], v[34:37]
	v_mfma_f32_16x16x32_bf16 v[22:25], v[172:175], v[208:211], v[22:25]
	v_mfma_f32_16x16x32_bf16 v[18:21], v[180:183], v[208:211], v[18:21]
	v_mfma_f32_16x16x32_bf16 v[6:9], v[172:175], v[216:219], v[6:9]
	v_mfma_f32_16x16x32_bf16 v[2:5], v[180:183], v[216:219], v[2:5]
	s_setprio 0
	s_barrier
	s_add_i32 s25, 0, 0x18000
	s_add_i32 s44, 0, 0x1c000
	v_add_u32_e32 v164, s25, v147
	v_add_u32_e32 v180, s44, v147
	ds_read_b128 v[152:155], v164
	ds_read_b128 v[156:159], v164 offset:1024
	ds_read_b128 v[160:163], v164 offset:2048
	ds_read_b128 v[164:167], v164 offset:3072
	ds_read_b128 v[168:171], v180
	ds_read_b128 v[172:175], v180 offset:1024
	ds_read_b128 v[176:179], v180 offset:2048
	ds_read_b128 v[180:183], v180 offset:3072
	s_add_u32 s42, s42, 0x80000
	s_addc_u32 s43, s43, 0
	s_mov_b32 m0, s48
	v_lshl_add_u64 v[224:225], s[42:43], 0, v[130:131]
	ds_read_b128 v[184:187], v151 offset:32768
	ds_read_b128 v[188:191], v151 offset:33792
	ds_read_b128 v[196:199], v151 offset:34816
	ds_read_b128 v[200:203], v151 offset:35840
	ds_read_b128 v[204:207], v151 offset:36864
	ds_read_b128 v[208:211], v151 offset:37888
	ds_read_b128 v[212:215], v151 offset:38912
	ds_read_b128 v[216:219], v151 offset:39936
	global_load_lds_dwordx4 v[224:225], off
	v_lshl_add_u64 v[224:225], s[42:43], 0, v[134:135]
	s_mov_b32 m0, s49
	s_nop 0
	global_load_lds_dwordx4 v[224:225], off
	s_waitcnt vmcnt(8)
	s_waitcnt lgkmcnt(0)
	s_barrier
	s_setprio 1
	s_waitcnt lgkmcnt(0)
	v_mfma_f32_16x16x32_bf16 v[126:129], v[152:155], v[184:187], v[126:129]
	v_mfma_f32_16x16x32_bf16 v[122:125], v[160:163], v[184:187], v[122:125]
	v_mfma_f32_16x16x32_bf16 v[110:113], v[152:155], v[196:199], v[110:113]
	v_mfma_f32_16x16x32_bf16 v[106:109], v[160:163], v[196:199], v[106:109]
	v_mfma_f32_16x16x32_bf16 v[94:97], v[152:155], v[204:207], v[94:97]
	v_mfma_f32_16x16x32_bf16 v[90:93], v[160:163], v[204:207], v[90:93]
	v_mfma_f32_16x16x32_bf16 v[78:81], v[152:155], v[212:215], v[78:81]
	v_mfma_f32_16x16x32_bf16 v[74:77], v[160:163], v[212:215], v[74:77]
	v_mfma_f32_16x16x32_bf16 v[126:129], v[156:159], v[188:191], v[126:129]
	v_mfma_f32_16x16x32_bf16 v[122:125], v[164:167], v[188:191], v[122:125]
	v_mfma_f32_16x16x32_bf16 v[110:113], v[156:159], v[200:203], v[110:113]
	v_mfma_f32_16x16x32_bf16 v[106:109], v[164:167], v[200:203], v[106:109]
	v_mfma_f32_16x16x32_bf16 v[94:97], v[156:159], v[208:211], v[94:97]
	v_mfma_f32_16x16x32_bf16 v[90:93], v[164:167], v[208:211], v[90:93]
	v_mfma_f32_16x16x32_bf16 v[78:81], v[156:159], v[216:219], v[78:81]
	v_mfma_f32_16x16x32_bf16 v[74:77], v[164:167], v[216:219], v[74:77]
	s_setprio 0
	s_setprio 1
	v_mfma_f32_16x16x32_bf16 v[118:121], v[168:171], v[184:187], v[118:121]
	v_mfma_f32_16x16x32_bf16 v[114:117], v[176:179], v[184:187], v[114:117]
	v_mfma_f32_16x16x32_bf16 v[102:105], v[168:171], v[196:199], v[102:105]
	v_mfma_f32_16x16x32_bf16 v[98:101], v[176:179], v[196:199], v[98:101]
	v_mfma_f32_16x16x32_bf16 v[86:89], v[168:171], v[204:207], v[86:89]
	v_mfma_f32_16x16x32_bf16 v[82:85], v[176:179], v[204:207], v[82:85]
	v_mfma_f32_16x16x32_bf16 v[70:73], v[168:171], v[212:215], v[70:73]
	v_mfma_f32_16x16x32_bf16 v[66:69], v[176:179], v[212:215], v[66:69]
	v_mfma_f32_16x16x32_bf16 v[118:121], v[172:175], v[188:191], v[118:121]
	v_mfma_f32_16x16x32_bf16 v[114:117], v[180:183], v[188:191], v[114:117]
	v_mfma_f32_16x16x32_bf16 v[102:105], v[172:175], v[200:203], v[102:105]
	v_mfma_f32_16x16x32_bf16 v[98:101], v[180:183], v[200:203], v[98:101]
	v_mfma_f32_16x16x32_bf16 v[86:89], v[172:175], v[208:211], v[86:89]
	v_mfma_f32_16x16x32_bf16 v[82:85], v[180:183], v[208:211], v[82:85]
	v_mfma_f32_16x16x32_bf16 v[70:73], v[172:175], v[216:219], v[70:73]
	v_mfma_f32_16x16x32_bf16 v[66:69], v[180:183], v[216:219], v[66:69]
	s_setprio 0
	s_barrier
	s_add_i32 s25, s25, s33
	v_lshl_add_u64 v[144:145], v[144:145], 0, s[16:17]
	s_mov_b32 m0, s25
	ds_read_b128 v[184:187], v151 offset:49152
	ds_read_b128 v[188:191], v151 offset:50176
	ds_read_b128 v[196:199], v151 offset:51200
	ds_read_b128 v[200:203], v151 offset:52224
	ds_read_b128 v[204:207], v151 offset:53248
	ds_read_b128 v[208:211], v151 offset:54272
	ds_read_b128 v[212:215], v151 offset:55296
	ds_read_b128 v[216:219], v151 offset:56320
	global_load_lds_dwordx4 v[144:145], off
	s_add_i32 m0, s25, 0x2000
	s_add_u32 s40, s40, 0x80080
	v_lshl_add_u64 v[144:145], v[192:193], 0, s[16:17]
	s_addc_u32 s41, s41, 0
	s_add_i32 s25, s44, s33
	global_load_lds_dwordx4 v[144:145], off
	v_lshl_add_u64 v[144:145], s[40:41], 0, v[132:133]
	s_mov_b32 m0, s25
	s_nop 0
	global_load_lds_dwordx4 v[144:145], off
	v_lshl_add_u64 v[144:145], s[40:41], 0, v[136:137]
	s_add_i32 m0, s25, 0x2000
	s_nop 0
	global_load_lds_dwordx4 v[144:145], off
	v_lshl_add_u64 v[144:145], v[220:221], 0, s[16:17]
	s_mov_b32 m0, s50
	s_nop 0
	global_load_lds_dwordx4 v[144:145], off
	v_lshl_add_u64 v[144:145], v[222:223], 0, s[16:17]
	s_mov_b32 m0, s51
	s_nop 0
	global_load_lds_dwordx4 v[144:145], off
	s_waitcnt vmcnt(8)
	s_waitcnt lgkmcnt(0)
	s_barrier
	s_setprio 1
	s_waitcnt lgkmcnt(0)
	v_mfma_f32_16x16x32_bf16 v[62:65], v[152:155], v[184:187], v[62:65]
	v_mfma_f32_16x16x32_bf16 v[58:61], v[160:163], v[184:187], v[58:61]
	v_mfma_f32_16x16x32_bf16 v[46:49], v[152:155], v[196:199], v[46:49]
	v_mfma_f32_16x16x32_bf16 v[42:45], v[160:163], v[196:199], v[42:45]
	v_mfma_f32_16x16x32_bf16 v[30:33], v[152:155], v[204:207], v[30:33]
	v_mfma_f32_16x16x32_bf16 v[26:29], v[160:163], v[204:207], v[26:29]
	v_mfma_f32_16x16x32_bf16 v[14:17], v[152:155], v[212:215], v[14:17]
	v_mfma_f32_16x16x32_bf16 v[10:13], v[160:163], v[212:215], v[10:13]
	v_mfma_f32_16x16x32_bf16 v[62:65], v[156:159], v[188:191], v[62:65]
	v_mfma_f32_16x16x32_bf16 v[58:61], v[164:167], v[188:191], v[58:61]
	v_mfma_f32_16x16x32_bf16 v[46:49], v[156:159], v[200:203], v[46:49]
	v_mfma_f32_16x16x32_bf16 v[42:45], v[164:167], v[200:203], v[42:45]
	v_mfma_f32_16x16x32_bf16 v[30:33], v[156:159], v[208:211], v[30:33]
	v_mfma_f32_16x16x32_bf16 v[26:29], v[164:167], v[208:211], v[26:29]
	v_mfma_f32_16x16x32_bf16 v[14:17], v[156:159], v[216:219], v[14:17]
	v_mfma_f32_16x16x32_bf16 v[10:13], v[164:167], v[216:219], v[10:13]
	s_setprio 0
	s_setprio 1
	v_mfma_f32_16x16x32_bf16 v[54:57], v[168:171], v[184:187], v[54:57]
	v_mfma_f32_16x16x32_bf16 v[50:53], v[176:179], v[184:187], v[50:53]
	v_mfma_f32_16x16x32_bf16 v[38:41], v[168:171], v[196:199], v[38:41]
	v_mfma_f32_16x16x32_bf16 v[34:37], v[176:179], v[196:199], v[34:37]
	v_mfma_f32_16x16x32_bf16 v[22:25], v[168:171], v[204:207], v[22:25]
	v_mfma_f32_16x16x32_bf16 v[18:21], v[176:179], v[204:207], v[18:21]
	v_mfma_f32_16x16x32_bf16 v[6:9], v[168:171], v[212:215], v[6:9]
	v_mfma_f32_16x16x32_bf16 v[2:5], v[176:179], v[212:215], v[2:5]
	v_mfma_f32_16x16x32_bf16 v[54:57], v[172:175], v[188:191], v[54:57]
	v_mfma_f32_16x16x32_bf16 v[50:53], v[180:183], v[188:191], v[50:53]
	v_mfma_f32_16x16x32_bf16 v[38:41], v[172:175], v[200:203], v[38:41]
	v_mfma_f32_16x16x32_bf16 v[34:37], v[180:183], v[200:203], v[34:37]
	v_mfma_f32_16x16x32_bf16 v[22:25], v[172:175], v[208:211], v[22:25]
	v_mfma_f32_16x16x32_bf16 v[18:21], v[180:183], v[208:211], v[18:21]
	v_mfma_f32_16x16x32_bf16 v[6:9], v[172:175], v[216:219], v[6:9]
	v_mfma_f32_16x16x32_bf16 v[2:5], v[180:183], v[216:219], v[2:5]
	s_setprio 0
	s_barrier
	s_add_u32 s38, s38, 0x100
	s_addc_u32 s39, s39, 0
	s_add_u32 s21, s21, 0x100
	s_addc_u32 s23, s23, 0
	s_cmp_ge_i32 s37, s62
	s_mov_b32 s25, s37
	s_cbranch_scc0 .LBB0_221
	s_branch .Lpeeldone_13

.Lpeeldone_13:
	ds_read_b128 v[160:163], v149 offset:2048
	ds_read_b128 v[164:167], v149 offset:3072
	ds_read_b128 v[168:171], v150
	ds_read_b128 v[172:175], v150 offset:1024
	ds_read_b128 v[176:179], v150 offset:2048
	ds_read_b128 v[180:183], v150 offset:3072
	ds_read_b128 v[184:187], v151
	ds_read_b128 v[188:191], v151 offset:1024
	ds_read_b128 v[196:199], v151 offset:2048
	ds_read_b128 v[200:203], v151 offset:3072
	ds_read_b128 v[204:207], v151 offset:4096
	ds_read_b128 v[208:211], v151 offset:5120
	ds_read_b128 v[212:215], v151 offset:6144
	ds_read_b128 v[216:219], v151 offset:7168
	s_and_b64 vcc, exec, s[18:19]
	s_cbranch_vccnz .LBB0_229
	s_cmp_gt_i32 s6, -1
	s_mov_b64 s[36:37], -1
	s_cbranch_scc1 .LBB0_230

.LBB0_535:
	s_lshl_b32 s6, s6, 5
	s_and_b32 s16, s6, 0x60
	s_mov_b64 s[6:7], 0x80
	s_add_i32 m0, s27, 0x18000
	v_lshl_add_u64 v[8:9], v[8:9], 0, s[6:7]
	s_lshl_b32 s11, s10, 13
	s_lshl_b32 s17, s16, 7
	s_waitcnt vmcnt(2)
	s_barrier
	global_load_lds_dwordx4 v[8:9], off
	v_lshl_add_u64 v[6:7], v[6:7], 0, s[6:7]
	s_add_i32 m0, s27, 0x1a000
	s_add_i32 s45, s27, 0x8000
	s_add_i32 s46, s27, 0xa000
	global_load_lds_dwordx4 v[6:7], off
	v_lshl_add_u64 v[2:3], v[2:3], 0, s[6:7]
	s_mov_b32 m0, s45
	s_add_u32 s12, s36, 0x80080
	global_load_lds_dwordx4 v[2:3], off
	v_lshl_add_u64 v[2:3], v[4:5], 0, s[6:7]
	s_mov_b32 m0, s46
	s_addc_u32 s13, s37, 0
	global_load_lds_dwordx4 v[2:3], off
	s_add_i32 m0, s27, 0x1c000
	v_lshl_add_u64 v[2:3], s[12:13], 0, v[134:135]
	global_load_lds_dwordx4 v[2:3], off
	v_lshl_add_u64 v[2:3], s[12:13], 0, v[130:131]
	s_add_i32 m0, s27, 0x1e000
	s_sext_i32_i8 s53, s8
	global_load_lds_dwordx4 v[2:3], off
	v_and_b32_e32 v2, 15, v0
	v_lshlrev_b32_e32 v3, 1, v13
	v_lshlrev_b32_e32 v4, 2, v0
	v_lshlrev_b32_e32 v5, 6, v0
	s_movk_i32 s8, 0x3c0
	v_lshl_or_b32 v142, s10, 6, v2
	v_lshl_or_b32 v2, v2, 6, v3
	v_and_b32_e32 v4, 32, v4
	v_and_or_b32 v3, v5, s8, v3
	v_bitop3_b32 v143, s17, v3, v4 bitop3:0xf6
	v_lshlrev_b32_e32 v3, 9, v0
	v_bitop3_b32 v2, v2, s11, v4 bitop3:0xde
	v_and_b32_e32 v3, 0x30000, v3
	v_lshlrev_b32_e32 v4, 12, v14
	v_or3_b32 v3, v11, v3, v4
	v_add_u32_e32 v138, v3, v12
	v_lshlrev_b32_e32 v3, 5, v10
	s_waitcnt vmcnt(6)
	s_cmpk_lt_u32 s9, 0x100
	v_and_b32_e32 v3, 0x70000, v3
	s_cselect_b64 s[8:9], -1, 0
	v_or3_b32 v3, v11, v3, v4
	s_add_i32 s47, 0, 0x10000
	s_add_i32 s48, 0, 0x14000
	v_or_b32_e32 v144, s16, v13
	v_mov_b32_e32 v139, v135
	v_add_u32_e32 v140, v3, v12
	v_mov_b32_e32 v141, v135
	v_add_u32_e32 v145, s47, v143
	v_add_u32_e32 v146, s48, v143
	v_add_u32_e32 v147, 0, v2
	s_mov_b64 s[10:11], 0x100000
	s_mov_b32 s49, 0x100000
	s_mov_b64 s[12:13], 0x120000
	s_mov_b32 s50, 0x120000
	s_mov_b64 s[16:17], 0x140000
	s_mov_b32 s51, 0x140000
	s_mov_b64 s[18:19], 0x160000
	s_mov_b32 s52, 0x160000
	s_barrier
	ds_read_b128 v[156:159], v145 offset:2048
	ds_read_b128 v[160:163], v145 offset:3072
	ds_read_b128 v[164:167], v146
	ds_read_b128 v[168:171], v146 offset:1024
	ds_read_b128 v[172:175], v146 offset:2048
	ds_read_b128 v[176:179], v146 offset:3072
	ds_read_b128 v[180:183], v147
	ds_read_b128 v[184:187], v147 offset:1024
	ds_read_b128 v[188:191], v147 offset:2048
	ds_read_b128 v[196:199], v147 offset:3072
	ds_read_b128 v[200:203], v147 offset:4096
	ds_read_b128 v[204:207], v147 offset:5120
	ds_read_b128 v[208:211], v147 offset:6144
	ds_read_b128 v[212:215], v147 offset:7168
	s_branch .LBB0_538

.Lpeel_11:
	ds_read_b128 v[148:151], v145
	ds_read_b128 v[152:155], v145 offset:1024
	s_add_u32 s36, s34, 0xfff80080
	s_addc_u32 s37, s35, -1
	s_cmp_eq_u32 s58, 28
	s_cselect_b32 s39, s21, s37
	s_cselect_b32 s38, s54, s36
	s_cselect_b32 s37, s23, s57
	s_cselect_b32 s36, s55, s56
	v_lshl_add_u64 v[192:193], s[34:35], 0, v[138:139]
	s_add_i32 m0, s27, 0xc000
	global_load_lds_dwordx4 v[192:193], off
	v_lshl_add_u64 v[192:193], s[34:35], 0, v[140:141]
	s_add_i32 m0, s27, 0xe000
	s_nop 0
	global_load_lds_dwordx4 v[192:193], off
	s_waitcnt vmcnt(8)
	s_waitcnt lgkmcnt(0)
	s_barrier
	s_setprio 1
	s_waitcnt lgkmcnt(0)
	v_mfma_f32_16x16x32_bf16 v[126:129], v[148:151], v[180:183], 0
	v_mfma_f32_16x16x32_bf16 v[122:125], v[156:159], v[180:183], 0
	v_mfma_f32_16x16x32_bf16 v[118:121], v[148:151], v[188:191], 0
	v_mfma_f32_16x16x32_bf16 v[114:117], v[156:159], v[188:191], 0
	v_mfma_f32_16x16x32_bf16 v[102:105], v[148:151], v[200:203], 0
	v_mfma_f32_16x16x32_bf16 v[98:101], v[156:159], v[200:203], 0
	v_mfma_f32_16x16x32_bf16 v[86:89], v[148:151], v[208:211], 0
	v_mfma_f32_16x16x32_bf16 v[82:85], v[156:159], v[208:211], 0
	v_mfma_f32_16x16x32_bf16 v[126:129], v[152:155], v[184:187], v[126:129]
	v_mfma_f32_16x16x32_bf16 v[122:125], v[160:163], v[184:187], v[122:125]
	v_mfma_f32_16x16x32_bf16 v[118:121], v[152:155], v[196:199], v[118:121]
	v_mfma_f32_16x16x32_bf16 v[114:117], v[160:163], v[196:199], v[114:117]
	v_mfma_f32_16x16x32_bf16 v[102:105], v[152:155], v[204:207], v[102:105]
	v_mfma_f32_16x16x32_bf16 v[98:101], v[160:163], v[204:207], v[98:101]
	v_mfma_f32_16x16x32_bf16 v[86:89], v[152:155], v[212:215], v[86:89]
	v_mfma_f32_16x16x32_bf16 v[82:85], v[160:163], v[212:215], v[82:85]
	s_setprio 0
	s_setprio 1
	v_mfma_f32_16x16x32_bf16 v[110:113], v[164:167], v[180:183], 0
	v_mfma_f32_16x16x32_bf16 v[106:109], v[172:175], v[180:183], 0
	v_mfma_f32_16x16x32_bf16 v[94:97], v[164:167], v[188:191], 0
	v_mfma_f32_16x16x32_bf16 v[90:93], v[172:175], v[188:191], 0
	v_mfma_f32_16x16x32_bf16 v[78:81], v[164:167], v[200:203], 0
	v_mfma_f32_16x16x32_bf16 v[74:77], v[172:175], v[200:203], 0
	v_mfma_f32_16x16x32_bf16 v[70:73], v[164:167], v[208:211], 0
	v_mfma_f32_16x16x32_bf16 v[66:69], v[172:175], v[208:211], 0
	v_mfma_f32_16x16x32_bf16 v[110:113], v[168:171], v[184:187], v[110:113]
	v_mfma_f32_16x16x32_bf16 v[106:109], v[176:179], v[184:187], v[106:109]
	v_mfma_f32_16x16x32_bf16 v[94:97], v[168:171], v[196:199], v[94:97]
	v_mfma_f32_16x16x32_bf16 v[90:93], v[176:179], v[196:199], v[90:93]
	v_mfma_f32_16x16x32_bf16 v[78:81], v[168:171], v[204:207], v[78:81]
	v_mfma_f32_16x16x32_bf16 v[74:77], v[176:179], v[204:207], v[74:77]
	v_mfma_f32_16x16x32_bf16 v[70:73], v[168:171], v[212:215], v[70:73]
	v_mfma_f32_16x16x32_bf16 v[66:69], v[176:179], v[212:215], v[66:69]
	s_setprio 0
	s_barrier
	s_add_i32 s59, s47, s33
	v_lshl_add_u64 v[192:193], s[36:37], 0, v[134:135]
	s_mov_b32 m0, s59
	ds_read_b128 v[180:183], v147 offset:16384
	ds_read_b128 v[184:187], v147 offset:17408
	ds_read_b128 v[188:191], v147 offset:18432
	ds_read_b128 v[196:199], v147 offset:19456
	ds_read_b128 v[200:203], v147 offset:20480
	ds_read_b128 v[204:207], v147 offset:21504
	ds_read_b128 v[208:211], v147 offset:22528
	ds_read_b128 v[212:215], v147 offset:23552
	global_load_lds_dwordx4 v[192:193], off
	s_add_i32 m0, s59, 0x2000
	s_add_u32 s60, s36, 0x80000
	v_lshl_add_u64 v[216:217], s[36:37], 0, v[130:131]
	s_addc_u32 s61, s37, 0
	s_add_i32 s59, s48, s33
	global_load_lds_dwordx4 v[216:217], off
	v_lshl_add_u64 v[218:219], s[60:61], 0, v[134:135]
	s_mov_b32 m0, s59
	v_lshl_add_u64 v[220:221], s[38:39], 0, v[132:133]
	global_load_lds_dwordx4 v[218:219], off
	v_lshl_add_u64 v[218:219], s[60:61], 0, v[130:131]
	s_add_i32 m0, s59, 0x2000
	s_nop 0
	global_load_lds_dwordx4 v[218:219], off
	v_lshl_add_u64 v[218:219], s[38:39], 0, v[136:137]
	s_mov_b32 m0, s27
	s_nop 0
	global_load_lds_dwordx4 v[218:219], off
	s_mov_b32 m0, s41
	s_nop 0
	global_load_lds_dwordx4 v[220:221], off
	s_waitcnt vmcnt(8)
	s_waitcnt lgkmcnt(0)
	s_barrier
	s_setprio 1
	s_waitcnt lgkmcnt(0)
	v_mfma_f32_16x16x32_bf16 v[62:65], v[148:151], v[180:183], 0
	v_mfma_f32_16x16x32_bf16 v[58:61], v[156:159], v[180:183], 0
	v_mfma_f32_16x16x32_bf16 v[54:57], v[148:151], v[188:191], 0
	v_mfma_f32_16x16x32_bf16 v[50:53], v[156:159], v[188:191], 0
	v_mfma_f32_16x16x32_bf16 v[38:41], v[148:151], v[200:203], 0
	v_mfma_f32_16x16x32_bf16 v[34:37], v[156:159], v[200:203], 0
	v_mfma_f32_16x16x32_bf16 v[22:25], v[148:151], v[208:211], 0
	v_mfma_f32_16x16x32_bf16 v[18:21], v[156:159], v[208:211], 0
	v_mfma_f32_16x16x32_bf16 v[62:65], v[152:155], v[184:187], v[62:65]
	v_mfma_f32_16x16x32_bf16 v[58:61], v[160:163], v[184:187], v[58:61]
	v_mfma_f32_16x16x32_bf16 v[54:57], v[152:155], v[196:199], v[54:57]
	v_mfma_f32_16x16x32_bf16 v[50:53], v[160:163], v[196:199], v[50:53]
	v_mfma_f32_16x16x32_bf16 v[38:41], v[152:155], v[204:207], v[38:41]
	v_mfma_f32_16x16x32_bf16 v[34:37], v[160:163], v[204:207], v[34:37]
	v_mfma_f32_16x16x32_bf16 v[22:25], v[152:155], v[212:215], v[22:25]
	v_mfma_f32_16x16x32_bf16 v[18:21], v[160:163], v[212:215], v[18:21]
	s_setprio 0
	s_setprio 1
	v_mfma_f32_16x16x32_bf16 v[46:49], v[164:167], v[180:183], 0
	v_mfma_f32_16x16x32_bf16 v[42:45], v[172:175], v[180:183], 0
	v_mfma_f32_16x16x32_bf16 v[30:33], v[164:167], v[188:191], 0
	v_mfma_f32_16x16x32_bf16 v[26:29], v[172:175], v[188:191], 0
	v_mfma_f32_16x16x32_bf16 v[14:17], v[164:167], v[200:203], 0
	v_mfma_f32_16x16x32_bf16 v[10:13], v[172:175], v[200:203], 0
	v_mfma_f32_16x16x32_bf16 v[6:9], v[164:167], v[208:211], 0
	v_mfma_f32_16x16x32_bf16 v[2:5], v[172:175], v[208:211], 0
	v_mfma_f32_16x16x32_bf16 v[46:49], v[168:171], v[184:187], v[46:49]
	v_mfma_f32_16x16x32_bf16 v[42:45], v[176:179], v[184:187], v[42:45]
	v_mfma_f32_16x16x32_bf16 v[30:33], v[168:171], v[196:199], v[30:33]
	v_mfma_f32_16x16x32_bf16 v[26:29], v[176:179], v[196:199], v[26:29]
	v_mfma_f32_16x16x32_bf16 v[14:17], v[168:171], v[204:207], v[14:17]
	v_mfma_f32_16x16x32_bf16 v[10:13], v[176:179], v[204:207], v[10:13]
	v_mfma_f32_16x16x32_bf16 v[6:9], v[168:171], v[212:215], v[6:9]
	v_mfma_f32_16x16x32_bf16 v[2:5], v[176:179], v[212:215], v[2:5]
	s_setprio 0
	s_barrier
	s_add_i32 s59, 0, 0x18000
	s_add_i32 s60, 0, 0x1c000
	v_add_u32_e32 v160, s59, v143
	v_add_u32_e32 v176, s60, v143
	ds_read_b128 v[148:151], v160
	ds_read_b128 v[152:155], v160 offset:1024
	ds_read_b128 v[156:159], v160 offset:2048
	ds_read_b128 v[160:163], v160 offset:3072
	ds_read_b128 v[164:167], v176
	ds_read_b128 v[168:171], v176 offset:1024
	ds_read_b128 v[172:175], v176 offset:2048
	ds_read_b128 v[176:179], v176 offset:3072
	s_add_u32 s38, s38, 0x80000
	s_addc_u32 s39, s39, 0
	s_mov_b32 m0, s42
	v_lshl_add_u64 v[222:223], s[38:39], 0, v[136:137]
	ds_read_b128 v[180:183], v147 offset:32768
	ds_read_b128 v[184:187], v147 offset:33792
	ds_read_b128 v[188:191], v147 offset:34816
	ds_read_b128 v[196:199], v147 offset:35840
	ds_read_b128 v[200:203], v147 offset:36864
	ds_read_b128 v[204:207], v147 offset:37888
	ds_read_b128 v[208:211], v147 offset:38912
	ds_read_b128 v[212:215], v147 offset:39936
	global_load_lds_dwordx4 v[222:223], off
	v_lshl_add_u64 v[222:223], s[38:39], 0, v[132:133]
	s_mov_b32 m0, s43
	s_nop 0
	global_load_lds_dwordx4 v[222:223], off
	s_waitcnt vmcnt(8)
	s_waitcnt lgkmcnt(0)
	s_barrier
	s_setprio 1
	s_waitcnt lgkmcnt(0)
	v_mfma_f32_16x16x32_bf16 v[126:129], v[148:151], v[180:183], v[126:129]
	v_mfma_f32_16x16x32_bf16 v[122:125], v[156:159], v[180:183], v[122:125]
	v_mfma_f32_16x16x32_bf16 v[118:121], v[148:151], v[188:191], v[118:121]
	v_mfma_f32_16x16x32_bf16 v[114:117], v[156:159], v[188:191], v[114:117]
	v_mfma_f32_16x16x32_bf16 v[102:105], v[148:151], v[200:203], v[102:105]
	v_mfma_f32_16x16x32_bf16 v[98:101], v[156:159], v[200:203], v[98:101]
	v_mfma_f32_16x16x32_bf16 v[86:89], v[148:151], v[208:211], v[86:89]
	v_mfma_f32_16x16x32_bf16 v[82:85], v[156:159], v[208:211], v[82:85]
	v_mfma_f32_16x16x32_bf16 v[126:129], v[152:155], v[184:187], v[126:129]
	v_mfma_f32_16x16x32_bf16 v[122:125], v[160:163], v[184:187], v[122:125]
	v_mfma_f32_16x16x32_bf16 v[118:121], v[152:155], v[196:199], v[118:121]
	v_mfma_f32_16x16x32_bf16 v[114:117], v[160:163], v[196:199], v[114:117]
	v_mfma_f32_16x16x32_bf16 v[102:105], v[152:155], v[204:207], v[102:105]
	v_mfma_f32_16x16x32_bf16 v[98:101], v[160:163], v[204:207], v[98:101]
	v_mfma_f32_16x16x32_bf16 v[86:89], v[152:155], v[212:215], v[86:89]
	v_mfma_f32_16x16x32_bf16 v[82:85], v[160:163], v[212:215], v[82:85]
	s_setprio 0
	s_setprio 1
	v_mfma_f32_16x16x32_bf16 v[110:113], v[164:167], v[180:183], v[110:113]
	v_mfma_f32_16x16x32_bf16 v[106:109], v[172:175], v[180:183], v[106:109]
	v_mfma_f32_16x16x32_bf16 v[94:97], v[164:167], v[188:191], v[94:97]
	v_mfma_f32_16x16x32_bf16 v[90:93], v[172:175], v[188:191], v[90:93]
	v_mfma_f32_16x16x32_bf16 v[78:81], v[164:167], v[200:203], v[78:81]
	v_mfma_f32_16x16x32_bf16 v[74:77], v[172:175], v[200:203], v[74:77]
	v_mfma_f32_16x16x32_bf16 v[70:73], v[164:167], v[208:211], v[70:73]
	v_mfma_f32_16x16x32_bf16 v[66:69], v[172:175], v[208:211], v[66:69]
	v_mfma_f32_16x16x32_bf16 v[110:113], v[168:171], v[184:187], v[110:113]
	v_mfma_f32_16x16x32_bf16 v[106:109], v[176:179], v[184:187], v[106:109]
	v_mfma_f32_16x16x32_bf16 v[94:97], v[168:171], v[196:199], v[94:97]
	v_mfma_f32_16x16x32_bf16 v[90:93], v[176:179], v[196:199], v[90:93]
	v_mfma_f32_16x16x32_bf16 v[78:81], v[168:171], v[204:207], v[78:81]
	v_mfma_f32_16x16x32_bf16 v[74:77], v[176:179], v[204:207], v[74:77]
	v_mfma_f32_16x16x32_bf16 v[70:73], v[168:171], v[212:215], v[70:73]
	v_mfma_f32_16x16x32_bf16 v[66:69], v[176:179], v[212:215], v[66:69]
	s_setprio 0
	s_barrier
	s_add_i32 s38, s59, s33
	v_lshl_add_u64 v[192:193], v[192:193], 0, s[6:7]
	s_mov_b32 m0, s38
	ds_read_b128 v[180:183], v147 offset:49152
	ds_read_b128 v[184:187], v147 offset:50176
	ds_read_b128 v[188:191], v147 offset:51200
	ds_read_b128 v[196:199], v147 offset:52224
	ds_read_b128 v[200:203], v147 offset:53248
	ds_read_b128 v[204:207], v147 offset:54272
	ds_read_b128 v[208:211], v147 offset:55296
	ds_read_b128 v[212:215], v147 offset:56320
	global_load_lds_dwordx4 v[192:193], off
	s_add_i32 m0, s38, 0x2000
	s_add_u32 s36, s36, 0x80080
	v_lshl_add_u64 v[192:193], v[216:217], 0, s[6:7]
	s_addc_u32 s37, s37, 0
	s_add_i32 s38, s60, s33
	global_load_lds_dwordx4 v[192:193], off
	v_lshl_add_u64 v[192:193], s[36:37], 0, v[134:135]
	s_mov_b32 m0, s38
	s_nop 0
	global_load_lds_dwordx4 v[192:193], off
	v_lshl_add_u64 v[192:193], s[36:37], 0, v[130:131]
	s_add_i32 m0, s38, 0x2000
	s_nop 0
	global_load_lds_dwordx4 v[192:193], off
	v_lshl_add_u64 v[192:193], v[218:219], 0, s[6:7]
	s_mov_b32 m0, s45
	s_nop 0
	global_load_lds_dwordx4 v[192:193], off
	v_lshl_add_u64 v[192:193], v[220:221], 0, s[6:7]
	s_mov_b32 m0, s46
	s_nop 0
	global_load_lds_dwordx4 v[192:193], off
	s_waitcnt vmcnt(8)
	s_waitcnt lgkmcnt(0)
	s_barrier
	s_setprio 1
	s_waitcnt lgkmcnt(0)
	v_mfma_f32_16x16x32_bf16 v[62:65], v[148:151], v[180:183], v[62:65]
	v_mfma_f32_16x16x32_bf16 v[58:61], v[156:159], v[180:183], v[58:61]
	v_mfma_f32_16x16x32_bf16 v[54:57], v[148:151], v[188:191], v[54:57]
	v_mfma_f32_16x16x32_bf16 v[50:53], v[156:159], v[188:191], v[50:53]
	v_mfma_f32_16x16x32_bf16 v[38:41], v[148:151], v[200:203], v[38:41]
	v_mfma_f32_16x16x32_bf16 v[34:37], v[156:159], v[200:203], v[34:37]
	v_mfma_f32_16x16x32_bf16 v[22:25], v[148:151], v[208:211], v[22:25]
	v_mfma_f32_16x16x32_bf16 v[18:21], v[156:159], v[208:211], v[18:21]
	v_mfma_f32_16x16x32_bf16 v[62:65], v[152:155], v[184:187], v[62:65]
	v_mfma_f32_16x16x32_bf16 v[58:61], v[160:163], v[184:187], v[58:61]
	v_mfma_f32_16x16x32_bf16 v[54:57], v[152:155], v[196:199], v[54:57]
	v_mfma_f32_16x16x32_bf16 v[50:53], v[160:163], v[196:199], v[50:53]
	v_mfma_f32_16x16x32_bf16 v[38:41], v[152:155], v[204:207], v[38:41]
	v_mfma_f32_16x16x32_bf16 v[34:37], v[160:163], v[204:207], v[34:37]
	v_mfma_f32_16x16x32_bf16 v[22:25], v[152:155], v[212:215], v[22:25]
	v_mfma_f32_16x16x32_bf16 v[18:21], v[160:163], v[212:215], v[18:21]
	s_setprio 0
	s_setprio 1
	v_mfma_f32_16x16x32_bf16 v[46:49], v[164:167], v[180:183], v[46:49]
	v_mfma_f32_16x16x32_bf16 v[42:45], v[172:175], v[180:183], v[42:45]
	v_mfma_f32_16x16x32_bf16 v[30:33], v[164:167], v[188:191], v[30:33]
	v_mfma_f32_16x16x32_bf16 v[26:29], v[172:175], v[188:191], v[26:29]
	v_mfma_f32_16x16x32_bf16 v[14:17], v[164:167], v[200:203], v[14:17]
	v_mfma_f32_16x16x32_bf16 v[10:13], v[172:175], v[200:203], v[10:13]
	v_mfma_f32_16x16x32_bf16 v[6:9], v[164:167], v[208:211], v[6:9]
	v_mfma_f32_16x16x32_bf16 v[2:5], v[172:175], v[208:211], v[2:5]
	v_mfma_f32_16x16x32_bf16 v[46:49], v[168:171], v[184:187], v[46:49]
	v_mfma_f32_16x16x32_bf16 v[42:45], v[176:179], v[184:187], v[42:45]
	v_mfma_f32_16x16x32_bf16 v[30:33], v[168:171], v[196:199], v[30:33]
	v_mfma_f32_16x16x32_bf16 v[26:29], v[176:179], v[196:199], v[26:29]
	v_mfma_f32_16x16x32_bf16 v[14:17], v[168:171], v[204:207], v[14:17]
	v_mfma_f32_16x16x32_bf16 v[10:13], v[176:179], v[204:207], v[10:13]
	v_mfma_f32_16x16x32_bf16 v[6:9], v[168:171], v[212:215], v[6:9]
	v_mfma_f32_16x16x32_bf16 v[2:5], v[176:179], v[212:215], v[2:5]
	s_setprio 0
	s_barrier
	s_add_i32 s58, s58, 2
	s_add_u32 s34, s34, 0x100
	s_addc_u32 s35, s35, 0
	s_add_u32 s56, s56, 0x100
	s_addc_u32 s57, s57, 0
	s_cmp_gt_u32 s58, 29
	s_cbranch_scc0 .LBB0_541
	s_branch .Lpeeldone_11

.Lpeeldone_11:
	ds_read_b128 v[156:159], v145 offset:2048
	ds_read_b128 v[160:163], v145 offset:3072
	ds_read_b128 v[164:167], v146
	ds_read_b128 v[168:171], v146 offset:1024
	ds_read_b128 v[172:175], v146 offset:2048
	ds_read_b128 v[176:179], v146 offset:3072
	ds_read_b128 v[180:183], v147
	ds_read_b128 v[184:187], v147 offset:1024
	ds_read_b128 v[188:191], v147 offset:2048
	ds_read_b128 v[196:199], v147 offset:3072
	ds_read_b128 v[200:203], v147 offset:4096
	ds_read_b128 v[204:207], v147 offset:5120
	ds_read_b128 v[208:211], v147 offset:6144
	ds_read_b128 v[212:215], v147 offset:7168
	s_and_b64 vcc, exec, s[8:9]
	s_cbranch_vccz .LBB0_544
	s_barrier

.LBB0_684:
	s_add_u32 s6, s82, 0x2bd00000
	s_addc_u32 s7, s83, 0
	s_lshl_b32 s8, s8, 5
	s_and_b32 s20, s8, 0x60
	s_mov_b64 s[8:9], 0x80
	s_add_i32 m0, s36, 0x18000
	v_lshl_add_u64 v[8:9], v[8:9], 0, s[8:9]
	s_lshl_b32 s13, s12, 13
	s_waitcnt vmcnt(2)
	s_barrier
	global_load_lds_dwordx4 v[8:9], off
	v_lshl_add_u64 v[6:7], v[6:7], 0, s[8:9]
	s_add_i32 m0, s36, 0x1a000
	s_add_i32 s41, s36, 0x8000
	s_add_i32 s42, s36, 0xa000
	global_load_lds_dwordx4 v[6:7], off
	v_lshl_add_u64 v[2:3], v[2:3], 0, s[8:9]
	s_mov_b32 m0, s41
	s_add_u32 s16, s28, 0x20080
	global_load_lds_dwordx4 v[2:3], off
	v_lshl_add_u64 v[2:3], v[4:5], 0, s[8:9]
	s_mov_b32 m0, s42
	s_addc_u32 s17, s29, 0
	global_load_lds_dwordx4 v[2:3], off
	s_add_i32 m0, s36, 0x1c000
	v_lshl_add_u64 v[2:3], s[16:17], 0, v[132:133]
	global_load_lds_dwordx4 v[2:3], off
	v_lshl_add_u64 v[2:3], s[16:17], 0, v[134:135]
	s_add_i32 m0, s36, 0x1e000
	v_lshlrev_b32_e32 v4, 10, v13
	global_load_lds_dwordx4 v[2:3], off
	v_lshlrev_b32_e32 v3, 2, v205
	v_lshl_or_b32 v2, v205, 6, v142
	v_and_b32_e32 v3, 32, v3
	v_bitop3_b32 v2, v2, s13, v3 bitop3:0xde
	v_lshlrev_b32_e32 v3, 7, v0
	v_and_b32_e32 v3, 0xc000, v3
	v_or3_b32 v3, v11, v3, v4
	v_add_u32_e32 v138, v3, v12
	v_lshlrev_b32_e32 v3, 3, v10
	s_waitcnt vmcnt(6)
	s_cmpk_lt_u32 s11, 0x100
	v_and_b32_e32 v3, 0x1c000, v3
	s_sext_i32_i8 s19, s10
	v_lshl_or_b32 v145, s20, 7, v143
	s_cselect_b64 s[10:11], -1, 0
	v_or3_b32 v3, v11, v3, v4
	s_add_i32 s43, 0, 0x10000
	s_add_i32 s44, 0, 0x14000
	v_lshl_or_b32 v144, s12, 6, v205
	v_or_b32_e32 v146, s20, v1
	v_mov_b32_e32 v139, v133
	v_add_u32_e32 v140, v3, v12
	v_mov_b32_e32 v141, v133
	v_add_u32_e32 v147, s43, v145
	v_add_u32_e32 v148, s44, v145
	v_add_u32_e32 v149, 0, v2
	s_movk_i32 s45, 0xc00
	s_barrier
	ds_read_b128 v[158:161], v147 offset:2048
	ds_read_b128 v[162:165], v147 offset:3072
	ds_read_b128 v[166:169], v148
	ds_read_b128 v[170:173], v148 offset:1024
	ds_read_b128 v[174:177], v148 offset:2048
	ds_read_b128 v[178:181], v148 offset:3072
	ds_read_b128 v[182:185], v149
	ds_read_b128 v[186:189], v149 offset:1024
	ds_read_b128 v[190:193], v149 offset:2048
	ds_read_b128 v[198:201], v149 offset:3072
	ds_read_b128 v[210:213], v149 offset:4096
	ds_read_b128 v[214:217], v149 offset:5120
	ds_read_b128 v[218:221], v149 offset:6144
	ds_read_b128 v[222:225], v149 offset:7168
	s_branch .LBB0_687

.Lpeel_10:
	ds_read_b128 v[150:153], v147
	ds_read_b128 v[154:157], v147 offset:1024
	s_add_u32 s28, s26, 0xfffe0080
	s_addc_u32 s29, s27, -1
	s_cmp_eq_u32 s50, 4
	s_cselect_b32 s31, s13, s29
	s_cselect_b32 s30, s46, s28
	s_cselect_b32 s29, s17, s49
	s_cselect_b32 s28, s47, s48
	v_lshl_add_u64 v[202:203], s[26:27], 0, v[138:139]
	s_add_i32 m0, s36, 0xc000
	global_load_lds_dwordx4 v[202:203], off
	v_lshl_add_u64 v[202:203], s[26:27], 0, v[140:141]
	s_add_i32 m0, s36, 0xe000
	s_nop 0
	global_load_lds_dwordx4 v[202:203], off
	s_waitcnt vmcnt(8)
	s_waitcnt lgkmcnt(0)
	s_barrier
	s_setprio 1
	s_waitcnt lgkmcnt(0)
	v_mfma_f32_16x16x32_bf16 v[126:129], v[150:153], v[182:185], 0
	v_mfma_f32_16x16x32_bf16 v[122:125], v[158:161], v[182:185], 0
	v_mfma_f32_16x16x32_bf16 v[118:121], v[150:153], v[190:193], 0
	v_mfma_f32_16x16x32_bf16 v[114:117], v[158:161], v[190:193], 0
	v_mfma_f32_16x16x32_bf16 v[102:105], v[150:153], v[210:213], 0
	v_mfma_f32_16x16x32_bf16 v[98:101], v[158:161], v[210:213], 0
	v_mfma_f32_16x16x32_bf16 v[86:89], v[150:153], v[218:221], 0
	v_mfma_f32_16x16x32_bf16 v[82:85], v[158:161], v[218:221], 0
	v_mfma_f32_16x16x32_bf16 v[126:129], v[154:157], v[186:189], v[126:129]
	v_mfma_f32_16x16x32_bf16 v[122:125], v[162:165], v[186:189], v[122:125]
	v_mfma_f32_16x16x32_bf16 v[118:121], v[154:157], v[198:201], v[118:121]
	v_mfma_f32_16x16x32_bf16 v[114:117], v[162:165], v[198:201], v[114:117]
	v_mfma_f32_16x16x32_bf16 v[102:105], v[154:157], v[214:217], v[102:105]
	v_mfma_f32_16x16x32_bf16 v[98:101], v[162:165], v[214:217], v[98:101]
	v_mfma_f32_16x16x32_bf16 v[86:89], v[154:157], v[222:225], v[86:89]
	v_mfma_f32_16x16x32_bf16 v[82:85], v[162:165], v[222:225], v[82:85]
	s_setprio 0
	s_setprio 1
	v_mfma_f32_16x16x32_bf16 v[110:113], v[166:169], v[182:185], 0
	v_mfma_f32_16x16x32_bf16 v[106:109], v[174:177], v[182:185], 0
	v_mfma_f32_16x16x32_bf16 v[94:97], v[166:169], v[190:193], 0
	v_mfma_f32_16x16x32_bf16 v[90:93], v[174:177], v[190:193], 0
	v_mfma_f32_16x16x32_bf16 v[78:81], v[166:169], v[210:213], 0
	v_mfma_f32_16x16x32_bf16 v[74:77], v[174:177], v[210:213], 0
	v_mfma_f32_16x16x32_bf16 v[70:73], v[166:169], v[218:221], 0
	v_mfma_f32_16x16x32_bf16 v[66:69], v[174:177], v[218:221], 0
	v_mfma_f32_16x16x32_bf16 v[110:113], v[170:173], v[186:189], v[110:113]
	v_mfma_f32_16x16x32_bf16 v[106:109], v[178:181], v[186:189], v[106:109]
	v_mfma_f32_16x16x32_bf16 v[94:97], v[170:173], v[198:201], v[94:97]
	v_mfma_f32_16x16x32_bf16 v[90:93], v[178:181], v[198:201], v[90:93]
	v_mfma_f32_16x16x32_bf16 v[78:81], v[170:173], v[214:217], v[78:81]
	v_mfma_f32_16x16x32_bf16 v[74:77], v[178:181], v[214:217], v[74:77]
	v_mfma_f32_16x16x32_bf16 v[70:73], v[170:173], v[222:225], v[70:73]
	v_mfma_f32_16x16x32_bf16 v[66:69], v[178:181], v[222:225], v[66:69]
	s_setprio 0
	s_barrier
	s_add_i32 s51, s43, s35
	v_lshl_add_u64 v[202:203], s[28:29], 0, v[132:133]
	s_mov_b32 m0, s51
	ds_read_b128 v[182:185], v149 offset:16384
	ds_read_b128 v[186:189], v149 offset:17408
	ds_read_b128 v[190:193], v149 offset:18432
	ds_read_b128 v[198:201], v149 offset:19456
	ds_read_b128 v[210:213], v149 offset:20480
	ds_read_b128 v[214:217], v149 offset:21504
	ds_read_b128 v[218:221], v149 offset:22528
	ds_read_b128 v[222:225], v149 offset:23552
	global_load_lds_dwordx4 v[202:203], off
	s_add_i32 m0, s51, 0x2000
	s_add_u32 s52, s28, 0x20000
	v_lshl_add_u64 v[206:207], s[28:29], 0, v[134:135]
	s_addc_u32 s53, s29, 0
	s_add_i32 s51, s44, s35
	global_load_lds_dwordx4 v[206:207], off
	v_lshl_add_u64 v[226:227], s[52:53], 0, v[132:133]
	s_mov_b32 m0, s51
	v_lshl_add_u64 v[228:229], s[30:31], 0, v[136:137]
	global_load_lds_dwordx4 v[226:227], off
	v_lshl_add_u64 v[226:227], s[52:53], 0, v[134:135]
	s_add_i32 m0, s51, 0x2000
	s_nop 0
	global_load_lds_dwordx4 v[226:227], off
	v_lshl_add_u64 v[226:227], s[30:31], 0, v[130:131]
	s_mov_b32 m0, s36
	s_nop 0
	global_load_lds_dwordx4 v[226:227], off
	s_mov_b32 m0, s37
	s_nop 0
	global_load_lds_dwordx4 v[228:229], off
	s_waitcnt vmcnt(8)
	s_waitcnt lgkmcnt(0)
	s_barrier
	s_setprio 1
	s_waitcnt lgkmcnt(0)
	v_mfma_f32_16x16x32_bf16 v[62:65], v[150:153], v[182:185], 0
	v_mfma_f32_16x16x32_bf16 v[58:61], v[158:161], v[182:185], 0
	v_mfma_f32_16x16x32_bf16 v[54:57], v[150:153], v[190:193], 0
	v_mfma_f32_16x16x32_bf16 v[50:53], v[158:161], v[190:193], 0
	v_mfma_f32_16x16x32_bf16 v[38:41], v[150:153], v[210:213], 0
	v_mfma_f32_16x16x32_bf16 v[34:37], v[158:161], v[210:213], 0
	v_mfma_f32_16x16x32_bf16 v[22:25], v[150:153], v[218:221], 0
	v_mfma_f32_16x16x32_bf16 v[18:21], v[158:161], v[218:221], 0
	v_mfma_f32_16x16x32_bf16 v[62:65], v[154:157], v[186:189], v[62:65]
	v_mfma_f32_16x16x32_bf16 v[58:61], v[162:165], v[186:189], v[58:61]
	v_mfma_f32_16x16x32_bf16 v[54:57], v[154:157], v[198:201], v[54:57]
	v_mfma_f32_16x16x32_bf16 v[50:53], v[162:165], v[198:201], v[50:53]
	v_mfma_f32_16x16x32_bf16 v[38:41], v[154:157], v[214:217], v[38:41]
	v_mfma_f32_16x16x32_bf16 v[34:37], v[162:165], v[214:217], v[34:37]
	v_mfma_f32_16x16x32_bf16 v[22:25], v[154:157], v[222:225], v[22:25]
	v_mfma_f32_16x16x32_bf16 v[18:21], v[162:165], v[222:225], v[18:21]
	s_setprio 0
	s_setprio 1
	v_mfma_f32_16x16x32_bf16 v[46:49], v[166:169], v[182:185], 0
	v_mfma_f32_16x16x32_bf16 v[42:45], v[174:177], v[182:185], 0
	v_mfma_f32_16x16x32_bf16 v[30:33], v[166:169], v[190:193], 0
	v_mfma_f32_16x16x32_bf16 v[26:29], v[174:177], v[190:193], 0
	v_mfma_f32_16x16x32_bf16 v[14:17], v[166:169], v[210:213], 0
	v_mfma_f32_16x16x32_bf16 v[10:13], v[174:177], v[210:213], 0
	v_mfma_f32_16x16x32_bf16 v[6:9], v[166:169], v[218:221], 0
	v_mfma_f32_16x16x32_bf16 v[2:5], v[174:177], v[218:221], 0
	v_mfma_f32_16x16x32_bf16 v[46:49], v[170:173], v[186:189], v[46:49]
	v_mfma_f32_16x16x32_bf16 v[42:45], v[178:181], v[186:189], v[42:45]
	v_mfma_f32_16x16x32_bf16 v[30:33], v[170:173], v[198:201], v[30:33]
	v_mfma_f32_16x16x32_bf16 v[26:29], v[178:181], v[198:201], v[26:29]
	v_mfma_f32_16x16x32_bf16 v[14:17], v[170:173], v[214:217], v[14:17]
	v_mfma_f32_16x16x32_bf16 v[10:13], v[178:181], v[214:217], v[10:13]
	v_mfma_f32_16x16x32_bf16 v[6:9], v[170:173], v[222:225], v[6:9]
	v_mfma_f32_16x16x32_bf16 v[2:5], v[178:181], v[222:225], v[2:5]
	s_setprio 0
	s_barrier
	s_add_i32 s51, 0, 0x18000
	s_add_i32 s52, 0, 0x1c000
	v_add_u32_e32 v162, s51, v145
	v_add_u32_e32 v178, s52, v145
	ds_read_b128 v[150:153], v162
	ds_read_b128 v[154:157], v162 offset:1024
	ds_read_b128 v[158:161], v162 offset:2048
	ds_read_b128 v[162:165], v162 offset:3072
	ds_read_b128 v[166:169], v178
	ds_read_b128 v[170:173], v178 offset:1024
	ds_read_b128 v[174:177], v178 offset:2048
	ds_read_b128 v[178:181], v178 offset:3072
	s_add_u32 s30, s30, 0x20000
	s_addc_u32 s31, s31, 0
	s_mov_b32 m0, s38
	v_lshl_add_u64 v[230:231], s[30:31], 0, v[130:131]
	ds_read_b128 v[182:185], v149 offset:32768
	ds_read_b128 v[186:189], v149 offset:33792
	ds_read_b128 v[190:193], v149 offset:34816
	ds_read_b128 v[198:201], v149 offset:35840
	ds_read_b128 v[210:213], v149 offset:36864
	ds_read_b128 v[214:217], v149 offset:37888
	ds_read_b128 v[218:221], v149 offset:38912
	ds_read_b128 v[222:225], v149 offset:39936
	global_load_lds_dwordx4 v[230:231], off
	v_lshl_add_u64 v[230:231], s[30:31], 0, v[136:137]
	s_mov_b32 m0, s39
	s_nop 0
	global_load_lds_dwordx4 v[230:231], off
	s_waitcnt vmcnt(8)
	s_waitcnt lgkmcnt(0)
	s_barrier
	s_setprio 1
	s_waitcnt lgkmcnt(0)
	v_mfma_f32_16x16x32_bf16 v[126:129], v[150:153], v[182:185], v[126:129]
	v_mfma_f32_16x16x32_bf16 v[122:125], v[158:161], v[182:185], v[122:125]
	v_mfma_f32_16x16x32_bf16 v[118:121], v[150:153], v[190:193], v[118:121]
	v_mfma_f32_16x16x32_bf16 v[114:117], v[158:161], v[190:193], v[114:117]
	v_mfma_f32_16x16x32_bf16 v[102:105], v[150:153], v[210:213], v[102:105]
	v_mfma_f32_16x16x32_bf16 v[98:101], v[158:161], v[210:213], v[98:101]
	v_mfma_f32_16x16x32_bf16 v[86:89], v[150:153], v[218:221], v[86:89]
	v_mfma_f32_16x16x32_bf16 v[82:85], v[158:161], v[218:221], v[82:85]
	v_mfma_f32_16x16x32_bf16 v[126:129], v[154:157], v[186:189], v[126:129]
	v_mfma_f32_16x16x32_bf16 v[122:125], v[162:165], v[186:189], v[122:125]
	v_mfma_f32_16x16x32_bf16 v[118:121], v[154:157], v[198:201], v[118:121]
	v_mfma_f32_16x16x32_bf16 v[114:117], v[162:165], v[198:201], v[114:117]
	v_mfma_f32_16x16x32_bf16 v[102:105], v[154:157], v[214:217], v[102:105]
	v_mfma_f32_16x16x32_bf16 v[98:101], v[162:165], v[214:217], v[98:101]
	v_mfma_f32_16x16x32_bf16 v[86:89], v[154:157], v[222:225], v[86:89]
	v_mfma_f32_16x16x32_bf16 v[82:85], v[162:165], v[222:225], v[82:85]
	s_setprio 0
	s_setprio 1
	v_mfma_f32_16x16x32_bf16 v[110:113], v[166:169], v[182:185], v[110:113]
	v_mfma_f32_16x16x32_bf16 v[106:109], v[174:177], v[182:185], v[106:109]
	v_mfma_f32_16x16x32_bf16 v[94:97], v[166:169], v[190:193], v[94:97]
	v_mfma_f32_16x16x32_bf16 v[90:93], v[174:177], v[190:193], v[90:93]
	v_mfma_f32_16x16x32_bf16 v[78:81], v[166:169], v[210:213], v[78:81]
	v_mfma_f32_16x16x32_bf16 v[74:77], v[174:177], v[210:213], v[74:77]
	v_mfma_f32_16x16x32_bf16 v[70:73], v[166:169], v[218:221], v[70:73]
	v_mfma_f32_16x16x32_bf16 v[66:69], v[174:177], v[218:221], v[66:69]
	v_mfma_f32_16x16x32_bf16 v[110:113], v[170:173], v[186:189], v[110:113]
	v_mfma_f32_16x16x32_bf16 v[106:109], v[178:181], v[186:189], v[106:109]
	v_mfma_f32_16x16x32_bf16 v[94:97], v[170:173], v[198:201], v[94:97]
	v_mfma_f32_16x16x32_bf16 v[90:93], v[178:181], v[198:201], v[90:93]
	v_mfma_f32_16x16x32_bf16 v[78:81], v[170:173], v[214:217], v[78:81]
	v_mfma_f32_16x16x32_bf16 v[74:77], v[178:181], v[214:217], v[74:77]
	v_mfma_f32_16x16x32_bf16 v[70:73], v[170:173], v[222:225], v[70:73]
	v_mfma_f32_16x16x32_bf16 v[66:69], v[178:181], v[222:225], v[66:69]
	s_setprio 0
	s_barrier
	s_add_i32 s30, s51, s35
	v_lshl_add_u64 v[202:203], v[202:203], 0, s[8:9]
	s_mov_b32 m0, s30
	ds_read_b128 v[182:185], v149 offset:49152
	ds_read_b128 v[186:189], v149 offset:50176
	ds_read_b128 v[190:193], v149 offset:51200
	ds_read_b128 v[198:201], v149 offset:52224
	ds_read_b128 v[210:213], v149 offset:53248
	ds_read_b128 v[214:217], v149 offset:54272
	ds_read_b128 v[218:221], v149 offset:55296
	ds_read_b128 v[222:225], v149 offset:56320
	global_load_lds_dwordx4 v[202:203], off
	s_add_i32 m0, s30, 0x2000
	s_add_u32 s28, s28, 0x20080
	v_lshl_add_u64 v[202:203], v[206:207], 0, s[8:9]
	s_addc_u32 s29, s29, 0
	s_add_i32 s30, s52, s35
	global_load_lds_dwordx4 v[202:203], off
	v_lshl_add_u64 v[202:203], s[28:29], 0, v[132:133]
	s_mov_b32 m0, s30
	s_nop 0
	global_load_lds_dwordx4 v[202:203], off
	v_lshl_add_u64 v[202:203], s[28:29], 0, v[134:135]
	s_add_i32 m0, s30, 0x2000
	s_nop 0
	global_load_lds_dwordx4 v[202:203], off
	v_lshl_add_u64 v[202:203], v[226:227], 0, s[8:9]
	s_mov_b32 m0, s41
	s_nop 0
	global_load_lds_dwordx4 v[202:203], off
	v_lshl_add_u64 v[202:203], v[228:229], 0, s[8:9]
	s_mov_b32 m0, s42
	s_nop 0
	global_load_lds_dwordx4 v[202:203], off
	s_waitcnt vmcnt(8)
	s_waitcnt lgkmcnt(0)
	s_barrier
	s_setprio 1
	s_waitcnt lgkmcnt(0)
	v_mfma_f32_16x16x32_bf16 v[62:65], v[150:153], v[182:185], v[62:65]
	v_mfma_f32_16x16x32_bf16 v[58:61], v[158:161], v[182:185], v[58:61]
	v_mfma_f32_16x16x32_bf16 v[54:57], v[150:153], v[190:193], v[54:57]
	v_mfma_f32_16x16x32_bf16 v[50:53], v[158:161], v[190:193], v[50:53]
	v_mfma_f32_16x16x32_bf16 v[38:41], v[150:153], v[210:213], v[38:41]
	v_mfma_f32_16x16x32_bf16 v[34:37], v[158:161], v[210:213], v[34:37]
	v_mfma_f32_16x16x32_bf16 v[22:25], v[150:153], v[218:221], v[22:25]
	v_mfma_f32_16x16x32_bf16 v[18:21], v[158:161], v[218:221], v[18:21]
	v_mfma_f32_16x16x32_bf16 v[62:65], v[154:157], v[186:189], v[62:65]
	v_mfma_f32_16x16x32_bf16 v[58:61], v[162:165], v[186:189], v[58:61]
	v_mfma_f32_16x16x32_bf16 v[54:57], v[154:157], v[198:201], v[54:57]
	v_mfma_f32_16x16x32_bf16 v[50:53], v[162:165], v[198:201], v[50:53]
	v_mfma_f32_16x16x32_bf16 v[38:41], v[154:157], v[214:217], v[38:41]
	v_mfma_f32_16x16x32_bf16 v[34:37], v[162:165], v[214:217], v[34:37]
	v_mfma_f32_16x16x32_bf16 v[22:25], v[154:157], v[222:225], v[22:25]
	v_mfma_f32_16x16x32_bf16 v[18:21], v[162:165], v[222:225], v[18:21]
	s_setprio 0
	s_setprio 1
	v_mfma_f32_16x16x32_bf16 v[46:49], v[166:169], v[182:185], v[46:49]
	v_mfma_f32_16x16x32_bf16 v[42:45], v[174:177], v[182:185], v[42:45]
	v_mfma_f32_16x16x32_bf16 v[30:33], v[166:169], v[190:193], v[30:33]
	v_mfma_f32_16x16x32_bf16 v[26:29], v[174:177], v[190:193], v[26:29]
	v_mfma_f32_16x16x32_bf16 v[14:17], v[166:169], v[210:213], v[14:17]
	v_mfma_f32_16x16x32_bf16 v[10:13], v[174:177], v[210:213], v[10:13]
	v_mfma_f32_16x16x32_bf16 v[6:9], v[166:169], v[218:221], v[6:9]
	v_mfma_f32_16x16x32_bf16 v[2:5], v[174:177], v[218:221], v[2:5]
	v_mfma_f32_16x16x32_bf16 v[46:49], v[170:173], v[186:189], v[46:49]
	v_mfma_f32_16x16x32_bf16 v[42:45], v[178:181], v[186:189], v[42:45]
	v_mfma_f32_16x16x32_bf16 v[30:33], v[170:173], v[198:201], v[30:33]
	v_mfma_f32_16x16x32_bf16 v[26:29], v[178:181], v[198:201], v[26:29]
	v_mfma_f32_16x16x32_bf16 v[14:17], v[170:173], v[214:217], v[14:17]
	v_mfma_f32_16x16x32_bf16 v[10:13], v[178:181], v[214:217], v[10:13]
	v_mfma_f32_16x16x32_bf16 v[6:9], v[170:173], v[222:225], v[6:9]
	v_mfma_f32_16x16x32_bf16 v[2:5], v[178:181], v[222:225], v[2:5]
	s_setprio 0
	s_barrier
	s_add_i32 s50, s50, 2
	s_add_u32 s26, s26, 0x100
	s_addc_u32 s27, s27, 0
	s_add_u32 s48, s48, 0x100
	s_addc_u32 s49, s49, 0
	s_cmp_gt_u32 s50, 5
	s_cbranch_scc0 .LBB0_690
	s_branch .Lpeeldone_10

.Lpeeldone_10:
	ds_read_b128 v[158:161], v147 offset:2048
	ds_read_b128 v[162:165], v147 offset:3072
	ds_read_b128 v[166:169], v148
	ds_read_b128 v[170:173], v148 offset:1024
	ds_read_b128 v[174:177], v148 offset:2048
	ds_read_b128 v[178:181], v148 offset:3072
	ds_read_b128 v[182:185], v149
	ds_read_b128 v[186:189], v149 offset:1024
	ds_read_b128 v[190:193], v149 offset:2048
	ds_read_b128 v[198:201], v149 offset:3072
	ds_read_b128 v[210:213], v149 offset:4096
	ds_read_b128 v[214:217], v149 offset:5120
	ds_read_b128 v[218:221], v149 offset:6144
	ds_read_b128 v[222:225], v149 offset:7168
	s_and_b64 vcc, exec, s[10:11]
	s_cbranch_vccz .LBB0_693
	s_barrier

.LBB0_704:
	s_lshl_b32 s6, s6, 5
	s_and_b32 s16, s6, 0x60
	s_mov_b64 s[6:7], 0x80
	s_add_i32 m0, s27, 0x18000
	v_lshl_add_u64 v[8:9], v[8:9], 0, s[6:7]
	s_lshl_b32 s11, s10, 13
	s_waitcnt vmcnt(2)
	s_barrier
	global_load_lds_dwordx4 v[8:9], off
	v_lshl_add_u64 v[6:7], v[6:7], 0, s[6:7]
	s_add_i32 m0, s27, 0x1a000
	s_add_i32 s46, s27, 0x8000
	s_add_i32 s47, s27, 0xa000
	global_load_lds_dwordx4 v[6:7], off
	v_lshl_add_u64 v[2:3], v[2:3], 0, s[6:7]
	s_mov_b32 m0, s46
	s_add_u32 s12, s36, 0x20080
	global_load_lds_dwordx4 v[2:3], off
	v_lshl_add_u64 v[2:3], v[4:5], 0, s[6:7]
	s_mov_b32 m0, s47
	s_addc_u32 s13, s37, 0
	global_load_lds_dwordx4 v[2:3], off
	s_add_i32 m0, s27, 0x1c000
	v_lshl_add_u64 v[2:3], s[12:13], 0, v[132:133]
	global_load_lds_dwordx4 v[2:3], off
	v_lshl_add_u64 v[2:3], s[12:13], 0, v[134:135]
	s_add_i32 m0, s27, 0x1e000
	s_cmpk_lt_u32 s9, 0x100
	global_load_lds_dwordx4 v[2:3], off
	v_lshlrev_b32_e32 v3, 2, v205
	v_lshl_or_b32 v2, v205, 6, v142
	v_and_b32_e32 v3, 32, v3
	s_waitcnt vmcnt(6)
	s_sext_i32_i8 s54, s8
	v_bitop3_b32 v2, v2, s11, v3 bitop3:0xde
	v_lshl_or_b32 v139, s16, 7, v143
	s_cselect_b64 s[8:9], -1, 0
	s_add_i32 s48, 0, 0x10000
	s_add_i32 s49, 0, 0x14000
	v_lshl_or_b32 v138, s10, 6, v205
	v_or_b32_e32 v1, s16, v1
	v_add_u32_e32 v140, s48, v139
	v_add_u32_e32 v141, s49, v139
	v_add_u32_e32 v142, 0, v2
	s_mov_b64 s[10:11], 0x80000
	s_mov_b32 s50, 0x80000
	s_mov_b64 s[12:13], 0x90000
	s_mov_b32 s51, 0x90000
	s_mov_b64 s[16:17], 0xa0000
	s_mov_b32 s52, 0xa0000
	s_mov_b64 s[18:19], 0xb0000
	s_mov_b32 s53, 0xb0000
	s_barrier
	ds_read_b128 v[152:155], v140 offset:2048
	ds_read_b128 v[156:159], v140 offset:3072
	ds_read_b128 v[160:163], v141
	ds_read_b128 v[164:167], v141 offset:1024
	ds_read_b128 v[168:171], v141 offset:2048
	ds_read_b128 v[172:175], v141 offset:3072
	ds_read_b128 v[176:179], v142
	ds_read_b128 v[180:183], v142 offset:1024
	ds_read_b128 v[184:187], v142 offset:2048
	ds_read_b128 v[188:191], v142 offset:3072
	ds_read_b128 v[198:201], v142 offset:4096
	ds_read_b128 v[210:213], v142 offset:5120
	ds_read_b128 v[214:217], v142 offset:6144
	ds_read_b128 v[218:221], v142 offset:7168
	s_branch .LBB0_707

.Lpeel_9:
	ds_read_b128 v[144:147], v140
	ds_read_b128 v[148:151], v140 offset:1024
	s_add_u32 s36, s34, 0xfffe0080
	s_addc_u32 s37, s35, -1
	s_cmp_eq_u32 s59, 4
	s_cselect_b32 s39, s21, s37
	s_cselect_b32 s38, s55, s36
	s_cselect_b32 s37, s25, s58
	s_cselect_b32 s36, s56, s57
	v_lshl_add_u64 v[192:193], s[34:35], 0, v[130:131]
	s_add_i32 m0, s27, 0xc000
	global_load_lds_dwordx4 v[192:193], off
	v_lshl_add_u64 v[192:193], s[34:35], 0, v[136:137]
	s_add_i32 m0, s27, 0xe000
	s_nop 0
	global_load_lds_dwordx4 v[192:193], off
	s_waitcnt vmcnt(8)
	s_waitcnt lgkmcnt(0)
	s_barrier
	s_setprio 1
	s_waitcnt lgkmcnt(0)
	v_mfma_f32_16x16x32_bf16 v[126:129], v[144:147], v[176:179], 0
	v_mfma_f32_16x16x32_bf16 v[122:125], v[152:155], v[176:179], 0
	v_mfma_f32_16x16x32_bf16 v[118:121], v[144:147], v[184:187], 0
	v_mfma_f32_16x16x32_bf16 v[114:117], v[152:155], v[184:187], 0
	v_mfma_f32_16x16x32_bf16 v[102:105], v[144:147], v[198:201], 0
	v_mfma_f32_16x16x32_bf16 v[98:101], v[152:155], v[198:201], 0
	v_mfma_f32_16x16x32_bf16 v[86:89], v[144:147], v[214:217], 0
	v_mfma_f32_16x16x32_bf16 v[82:85], v[152:155], v[214:217], 0
	v_mfma_f32_16x16x32_bf16 v[126:129], v[148:151], v[180:183], v[126:129]
	v_mfma_f32_16x16x32_bf16 v[122:125], v[156:159], v[180:183], v[122:125]
	v_mfma_f32_16x16x32_bf16 v[118:121], v[148:151], v[188:191], v[118:121]
	v_mfma_f32_16x16x32_bf16 v[114:117], v[156:159], v[188:191], v[114:117]
	v_mfma_f32_16x16x32_bf16 v[102:105], v[148:151], v[210:213], v[102:105]
	v_mfma_f32_16x16x32_bf16 v[98:101], v[156:159], v[210:213], v[98:101]
	v_mfma_f32_16x16x32_bf16 v[86:89], v[148:151], v[218:221], v[86:89]
	v_mfma_f32_16x16x32_bf16 v[82:85], v[156:159], v[218:221], v[82:85]
	s_setprio 0
	s_setprio 1
	v_mfma_f32_16x16x32_bf16 v[110:113], v[160:163], v[176:179], 0
	v_mfma_f32_16x16x32_bf16 v[106:109], v[168:171], v[176:179], 0
	v_mfma_f32_16x16x32_bf16 v[94:97], v[160:163], v[184:187], 0
	v_mfma_f32_16x16x32_bf16 v[90:93], v[168:171], v[184:187], 0
	v_mfma_f32_16x16x32_bf16 v[78:81], v[160:163], v[198:201], 0
	v_mfma_f32_16x16x32_bf16 v[74:77], v[168:171], v[198:201], 0
	v_mfma_f32_16x16x32_bf16 v[70:73], v[160:163], v[214:217], 0
	v_mfma_f32_16x16x32_bf16 v[66:69], v[168:171], v[214:217], 0
	v_mfma_f32_16x16x32_bf16 v[110:113], v[164:167], v[180:183], v[110:113]
	v_mfma_f32_16x16x32_bf16 v[106:109], v[172:175], v[180:183], v[106:109]
	v_mfma_f32_16x16x32_bf16 v[94:97], v[164:167], v[188:191], v[94:97]
	v_mfma_f32_16x16x32_bf16 v[90:93], v[172:175], v[188:191], v[90:93]
	v_mfma_f32_16x16x32_bf16 v[78:81], v[164:167], v[210:213], v[78:81]
	v_mfma_f32_16x16x32_bf16 v[74:77], v[172:175], v[210:213], v[74:77]
	v_mfma_f32_16x16x32_bf16 v[70:73], v[164:167], v[218:221], v[70:73]
	v_mfma_f32_16x16x32_bf16 v[66:69], v[172:175], v[218:221], v[66:69]
	s_setprio 0
	s_barrier
	s_add_i32 s60, s48, s41
	v_lshl_add_u64 v[192:193], s[36:37], 0, v[132:133]
	s_mov_b32 m0, s60
	ds_read_b128 v[176:179], v142 offset:16384
	ds_read_b128 v[180:183], v142 offset:17408
	ds_read_b128 v[184:187], v142 offset:18432
	ds_read_b128 v[188:191], v142 offset:19456
	ds_read_b128 v[198:201], v142 offset:20480
	ds_read_b128 v[210:213], v142 offset:21504
	ds_read_b128 v[214:217], v142 offset:22528
	ds_read_b128 v[218:221], v142 offset:23552
	global_load_lds_dwordx4 v[192:193], off
	s_add_i32 m0, s60, 0x2000
	s_add_u32 s60, s36, 0x20000
	v_lshl_add_u64 v[202:203], s[36:37], 0, v[134:135]
	s_addc_u32 s61, s37, 0
	s_add_i32 s62, s49, s41
	global_load_lds_dwordx4 v[202:203], off
	v_lshl_add_u64 v[206:207], s[60:61], 0, v[132:133]
	s_mov_b32 m0, s62
	v_lshl_add_u64 v[222:223], s[38:39], 0, v[136:137]
	global_load_lds_dwordx4 v[206:207], off
	v_lshl_add_u64 v[206:207], s[60:61], 0, v[134:135]
	s_add_i32 m0, s62, 0x2000
	s_nop 0
	global_load_lds_dwordx4 v[206:207], off
	v_lshl_add_u64 v[206:207], s[38:39], 0, v[130:131]
	s_mov_b32 m0, s27
	s_nop 0
	global_load_lds_dwordx4 v[206:207], off
	s_mov_b32 m0, s42
	s_nop 0
	global_load_lds_dwordx4 v[222:223], off
	s_waitcnt vmcnt(8)
	s_waitcnt lgkmcnt(0)
	s_barrier
	s_setprio 1
	s_waitcnt lgkmcnt(0)
	v_mfma_f32_16x16x32_bf16 v[62:65], v[144:147], v[176:179], 0
	v_mfma_f32_16x16x32_bf16 v[58:61], v[152:155], v[176:179], 0
	v_mfma_f32_16x16x32_bf16 v[54:57], v[144:147], v[184:187], 0
	v_mfma_f32_16x16x32_bf16 v[50:53], v[152:155], v[184:187], 0
	v_mfma_f32_16x16x32_bf16 v[38:41], v[144:147], v[198:201], 0
	v_mfma_f32_16x16x32_bf16 v[34:37], v[152:155], v[198:201], 0
	v_mfma_f32_16x16x32_bf16 v[22:25], v[144:147], v[214:217], 0
	v_mfma_f32_16x16x32_bf16 v[18:21], v[152:155], v[214:217], 0
	v_mfma_f32_16x16x32_bf16 v[62:65], v[148:151], v[180:183], v[62:65]
	v_mfma_f32_16x16x32_bf16 v[58:61], v[156:159], v[180:183], v[58:61]
	v_mfma_f32_16x16x32_bf16 v[54:57], v[148:151], v[188:191], v[54:57]
	v_mfma_f32_16x16x32_bf16 v[50:53], v[156:159], v[188:191], v[50:53]
	v_mfma_f32_16x16x32_bf16 v[38:41], v[148:151], v[210:213], v[38:41]
	v_mfma_f32_16x16x32_bf16 v[34:37], v[156:159], v[210:213], v[34:37]
	v_mfma_f32_16x16x32_bf16 v[22:25], v[148:151], v[218:221], v[22:25]
	v_mfma_f32_16x16x32_bf16 v[18:21], v[156:159], v[218:221], v[18:21]
	s_setprio 0
	s_setprio 1
	v_mfma_f32_16x16x32_bf16 v[46:49], v[160:163], v[176:179], 0
	v_mfma_f32_16x16x32_bf16 v[42:45], v[168:171], v[176:179], 0
	v_mfma_f32_16x16x32_bf16 v[30:33], v[160:163], v[184:187], 0
	v_mfma_f32_16x16x32_bf16 v[26:29], v[168:171], v[184:187], 0
	v_mfma_f32_16x16x32_bf16 v[14:17], v[160:163], v[198:201], 0
	v_mfma_f32_16x16x32_bf16 v[10:13], v[168:171], v[198:201], 0
	v_mfma_f32_16x16x32_bf16 v[6:9], v[160:163], v[214:217], 0
	v_mfma_f32_16x16x32_bf16 v[2:5], v[168:171], v[214:217], 0
	v_mfma_f32_16x16x32_bf16 v[46:49], v[164:167], v[180:183], v[46:49]
	v_mfma_f32_16x16x32_bf16 v[42:45], v[172:175], v[180:183], v[42:45]
	v_mfma_f32_16x16x32_bf16 v[30:33], v[164:167], v[188:191], v[30:33]
	v_mfma_f32_16x16x32_bf16 v[26:29], v[172:175], v[188:191], v[26:29]
	v_mfma_f32_16x16x32_bf16 v[14:17], v[164:167], v[210:213], v[14:17]
	v_mfma_f32_16x16x32_bf16 v[10:13], v[172:175], v[210:213], v[10:13]
	v_mfma_f32_16x16x32_bf16 v[6:9], v[164:167], v[218:221], v[6:9]
	v_mfma_f32_16x16x32_bf16 v[2:5], v[172:175], v[218:221], v[2:5]
	s_setprio 0
	s_barrier
	s_add_i32 s60, 0, 0x18000
	v_add_u32_e32 v143, s60, v139
	s_add_i32 s61, 0, 0x1c000
	ds_read_b128 v[144:147], v143
	ds_read_b128 v[148:151], v143 offset:1024
	ds_read_b128 v[152:155], v143 offset:2048
	ds_read_b128 v[156:159], v143 offset:3072
	v_add_u32_e32 v143, s61, v139
	ds_read_b128 v[160:163], v143
	ds_read_b128 v[164:167], v143 offset:1024
	ds_read_b128 v[168:171], v143 offset:2048
	ds_read_b128 v[172:175], v143 offset:3072
	s_add_u32 s38, s38, 0x20000
	s_addc_u32 s39, s39, 0
	s_mov_b32 m0, s43
	v_lshl_add_u64 v[224:225], s[38:39], 0, v[130:131]
	ds_read_b128 v[176:179], v142 offset:32768
	ds_read_b128 v[180:183], v142 offset:33792
	ds_read_b128 v[184:187], v142 offset:34816
	ds_read_b128 v[188:191], v142 offset:35840
	ds_read_b128 v[198:201], v142 offset:36864
	ds_read_b128 v[210:213], v142 offset:37888
	ds_read_b128 v[214:217], v142 offset:38912
	ds_read_b128 v[218:221], v142 offset:39936
	global_load_lds_dwordx4 v[224:225], off
	v_lshl_add_u64 v[224:225], s[38:39], 0, v[136:137]
	s_mov_b32 m0, s44
	s_nop 0
	global_load_lds_dwordx4 v[224:225], off
	s_waitcnt vmcnt(8)
	s_waitcnt lgkmcnt(0)
	s_barrier
	s_setprio 1
	s_waitcnt lgkmcnt(0)
	v_mfma_f32_16x16x32_bf16 v[126:129], v[144:147], v[176:179], v[126:129]
	v_mfma_f32_16x16x32_bf16 v[122:125], v[152:155], v[176:179], v[122:125]
	v_mfma_f32_16x16x32_bf16 v[118:121], v[144:147], v[184:187], v[118:121]
	v_mfma_f32_16x16x32_bf16 v[114:117], v[152:155], v[184:187], v[114:117]
	v_mfma_f32_16x16x32_bf16 v[102:105], v[144:147], v[198:201], v[102:105]
	v_mfma_f32_16x16x32_bf16 v[98:101], v[152:155], v[198:201], v[98:101]
	v_mfma_f32_16x16x32_bf16 v[86:89], v[144:147], v[214:217], v[86:89]
	v_mfma_f32_16x16x32_bf16 v[82:85], v[152:155], v[214:217], v[82:85]
	v_mfma_f32_16x16x32_bf16 v[126:129], v[148:151], v[180:183], v[126:129]
	v_mfma_f32_16x16x32_bf16 v[122:125], v[156:159], v[180:183], v[122:125]
	v_mfma_f32_16x16x32_bf16 v[118:121], v[148:151], v[188:191], v[118:121]
	v_mfma_f32_16x16x32_bf16 v[114:117], v[156:159], v[188:191], v[114:117]
	v_mfma_f32_16x16x32_bf16 v[102:105], v[148:151], v[210:213], v[102:105]
	v_mfma_f32_16x16x32_bf16 v[98:101], v[156:159], v[210:213], v[98:101]
	v_mfma_f32_16x16x32_bf16 v[86:89], v[148:151], v[218:221], v[86:89]
	v_mfma_f32_16x16x32_bf16 v[82:85], v[156:159], v[218:221], v[82:85]
	s_setprio 0
	s_setprio 1
	v_mfma_f32_16x16x32_bf16 v[110:113], v[160:163], v[176:179], v[110:113]
	v_mfma_f32_16x16x32_bf16 v[106:109], v[168:171], v[176:179], v[106:109]
	v_mfma_f32_16x16x32_bf16 v[94:97], v[160:163], v[184:187], v[94:97]
	v_mfma_f32_16x16x32_bf16 v[90:93], v[168:171], v[184:187], v[90:93]
	v_mfma_f32_16x16x32_bf16 v[78:81], v[160:163], v[198:201], v[78:81]
	v_mfma_f32_16x16x32_bf16 v[74:77], v[168:171], v[198:201], v[74:77]
	v_mfma_f32_16x16x32_bf16 v[70:73], v[160:163], v[214:217], v[70:73]
	v_mfma_f32_16x16x32_bf16 v[66:69], v[168:171], v[214:217], v[66:69]
	v_mfma_f32_16x16x32_bf16 v[110:113], v[164:167], v[180:183], v[110:113]
	v_mfma_f32_16x16x32_bf16 v[106:109], v[172:175], v[180:183], v[106:109]
	v_mfma_f32_16x16x32_bf16 v[94:97], v[164:167], v[188:191], v[94:97]
	v_mfma_f32_16x16x32_bf16 v[90:93], v[172:175], v[188:191], v[90:93]
	v_mfma_f32_16x16x32_bf16 v[78:81], v[164:167], v[210:213], v[78:81]
	v_mfma_f32_16x16x32_bf16 v[74:77], v[172:175], v[210:213], v[74:77]
	v_mfma_f32_16x16x32_bf16 v[70:73], v[164:167], v[218:221], v[70:73]
	v_mfma_f32_16x16x32_bf16 v[66:69], v[172:175], v[218:221], v[66:69]
	s_setprio 0
	s_barrier
	s_add_i32 s38, s60, s41
	v_lshl_add_u64 v[192:193], v[192:193], 0, s[6:7]
	s_mov_b32 m0, s38
	ds_read_b128 v[176:179], v142 offset:49152
	ds_read_b128 v[180:183], v142 offset:50176
	ds_read_b128 v[184:187], v142 offset:51200
	ds_read_b128 v[188:191], v142 offset:52224
	ds_read_b128 v[198:201], v142 offset:53248
	ds_read_b128 v[210:213], v142 offset:54272
	ds_read_b128 v[214:217], v142 offset:55296
	ds_read_b128 v[218:221], v142 offset:56320
	global_load_lds_dwordx4 v[192:193], off
	s_add_i32 m0, s38, 0x2000
	s_add_u32 s36, s36, 0x20080
	v_lshl_add_u64 v[192:193], v[202:203], 0, s[6:7]
	s_addc_u32 s37, s37, 0
	s_add_i32 s38, s61, s41
	global_load_lds_dwordx4 v[192:193], off
	v_lshl_add_u64 v[192:193], s[36:37], 0, v[132:133]
	s_mov_b32 m0, s38
	s_nop 0
	global_load_lds_dwordx4 v[192:193], off
	v_lshl_add_u64 v[192:193], s[36:37], 0, v[134:135]
	s_add_i32 m0, s38, 0x2000
	s_nop 0
	global_load_lds_dwordx4 v[192:193], off
	v_lshl_add_u64 v[192:193], v[206:207], 0, s[6:7]
	s_mov_b32 m0, s46
	s_nop 0
	global_load_lds_dwordx4 v[192:193], off
	v_lshl_add_u64 v[192:193], v[222:223], 0, s[6:7]
	s_mov_b32 m0, s47
	s_nop 0
	global_load_lds_dwordx4 v[192:193], off
	s_waitcnt vmcnt(8)
	s_waitcnt lgkmcnt(0)
	s_barrier
	s_setprio 1
	s_waitcnt lgkmcnt(0)
	v_mfma_f32_16x16x32_bf16 v[62:65], v[144:147], v[176:179], v[62:65]
	v_mfma_f32_16x16x32_bf16 v[58:61], v[152:155], v[176:179], v[58:61]
	v_mfma_f32_16x16x32_bf16 v[54:57], v[144:147], v[184:187], v[54:57]
	v_mfma_f32_16x16x32_bf16 v[50:53], v[152:155], v[184:187], v[50:53]
	v_mfma_f32_16x16x32_bf16 v[38:41], v[144:147], v[198:201], v[38:41]
	v_mfma_f32_16x16x32_bf16 v[34:37], v[152:155], v[198:201], v[34:37]
	v_mfma_f32_16x16x32_bf16 v[22:25], v[144:147], v[214:217], v[22:25]
	v_mfma_f32_16x16x32_bf16 v[18:21], v[152:155], v[214:217], v[18:21]
	v_mfma_f32_16x16x32_bf16 v[62:65], v[148:151], v[180:183], v[62:65]
	v_mfma_f32_16x16x32_bf16 v[58:61], v[156:159], v[180:183], v[58:61]
	v_mfma_f32_16x16x32_bf16 v[54:57], v[148:151], v[188:191], v[54:57]
	v_mfma_f32_16x16x32_bf16 v[50:53], v[156:159], v[188:191], v[50:53]
	v_mfma_f32_16x16x32_bf16 v[38:41], v[148:151], v[210:213], v[38:41]
	v_mfma_f32_16x16x32_bf16 v[34:37], v[156:159], v[210:213], v[34:37]
	v_mfma_f32_16x16x32_bf16 v[22:25], v[148:151], v[218:221], v[22:25]
	v_mfma_f32_16x16x32_bf16 v[18:21], v[156:159], v[218:221], v[18:21]
	s_setprio 0
	s_setprio 1
	v_mfma_f32_16x16x32_bf16 v[46:49], v[160:163], v[176:179], v[46:49]
	v_mfma_f32_16x16x32_bf16 v[42:45], v[168:171], v[176:179], v[42:45]
	v_mfma_f32_16x16x32_bf16 v[30:33], v[160:163], v[184:187], v[30:33]
	v_mfma_f32_16x16x32_bf16 v[26:29], v[168:171], v[184:187], v[26:29]
	v_mfma_f32_16x16x32_bf16 v[14:17], v[160:163], v[198:201], v[14:17]
	v_mfma_f32_16x16x32_bf16 v[10:13], v[168:171], v[198:201], v[10:13]
	v_mfma_f32_16x16x32_bf16 v[6:9], v[160:163], v[214:217], v[6:9]
	v_mfma_f32_16x16x32_bf16 v[2:5], v[168:171], v[214:217], v[2:5]
	v_mfma_f32_16x16x32_bf16 v[46:49], v[164:167], v[180:183], v[46:49]
	v_mfma_f32_16x16x32_bf16 v[42:45], v[172:175], v[180:183], v[42:45]
	v_mfma_f32_16x16x32_bf16 v[30:33], v[164:167], v[188:191], v[30:33]
	v_mfma_f32_16x16x32_bf16 v[26:29], v[172:175], v[188:191], v[26:29]
	v_mfma_f32_16x16x32_bf16 v[14:17], v[164:167], v[210:213], v[14:17]
	v_mfma_f32_16x16x32_bf16 v[10:13], v[172:175], v[210:213], v[10:13]
	v_mfma_f32_16x16x32_bf16 v[6:9], v[164:167], v[218:221], v[6:9]
	v_mfma_f32_16x16x32_bf16 v[2:5], v[172:175], v[218:221], v[2:5]
	s_setprio 0
	s_barrier
	s_add_i32 s59, s59, 2
	s_add_u32 s34, s34, 0x100
	s_addc_u32 s35, s35, 0
	s_add_u32 s57, s57, 0x100
	s_addc_u32 s58, s58, 0
	s_cmp_gt_u32 s59, 5
	s_cbranch_scc0 .LBB0_714
	s_branch .Lpeeldone_9

.Lpeeldone_9:
	ds_read_b128 v[152:155], v140 offset:2048
	ds_read_b128 v[156:159], v140 offset:3072
	ds_read_b128 v[160:163], v141
	ds_read_b128 v[164:167], v141 offset:1024
	ds_read_b128 v[168:171], v141 offset:2048
	ds_read_b128 v[172:175], v141 offset:3072
	ds_read_b128 v[176:179], v142
	ds_read_b128 v[180:183], v142 offset:1024
	ds_read_b128 v[184:187], v142 offset:2048
	ds_read_b128 v[188:191], v142 offset:3072
	ds_read_b128 v[198:201], v142 offset:4096
	ds_read_b128 v[210:213], v142 offset:5120
	ds_read_b128 v[214:217], v142 offset:6144
	ds_read_b128 v[218:221], v142 offset:7168
	s_and_b64 vcc, exec, s[8:9]
	s_cbranch_vccz .LBB0_717
	s_barrier

.LBB0_1110:
	s_add_u32 s10, s82, 0x27100000
	s_addc_u32 s11, s83, 0
	s_add_u32 s51, s82, 0x20a000
	s_addc_u32 s52, s83, 0
	s_lshl_b32 s0, s12, 5
	s_mov_b64 s[12:13], 0x80
	s_and_b32 s17, s0, 0x60
	s_add_i32 m0, s27, 0x18000
	v_lshl_add_u64 v[10:11], v[10:11], 0, s[12:13]
	s_lshl_b32 s15, s7, 13
	s_lshl_b32 s18, s17, 7
	s_waitcnt vmcnt(2)
	s_barrier
	global_load_lds_dwordx4 v[10:11], off
	v_lshl_add_u64 v[6:7], v[6:7], 0, s[12:13]
	s_add_i32 m0, s27, 0x1a000
	s_add_i32 s53, s27, 0x8000
	s_add_i32 s54, s27, 0xa000
	global_load_lds_dwordx4 v[6:7], off
	v_lshl_add_u64 v[6:7], v[8:9], 0, s[12:13]
	s_mov_b32 m0, s53
	s_add_u32 s0, s36, 0x80080
	global_load_lds_dwordx4 v[6:7], off
	v_lshl_add_u64 v[4:5], v[4:5], 0, s[12:13]
	s_mov_b32 m0, s54
	s_addc_u32 s1, s37, 0
	global_load_lds_dwordx4 v[4:5], off
	s_add_i32 m0, s27, 0x1c000
	v_lshl_add_u64 v[4:5], s[0:1], 0, v[148:149]
	global_load_lds_dwordx4 v[4:5], off
	v_lshl_add_u64 v[4:5], s[0:1], 0, v[152:153]
	s_add_i32 m0, s27, 0x1e000
	v_lshlrev_b32_e32 v3, 1, v15
	global_load_lds_dwordx4 v[4:5], off
	v_lshl_or_b32 v4, v205, 6, v3
	v_and_b32_e32 v5, 32, v196
	v_bitop3_b32 v4, v4, s15, v5 bitop3:0xde
	s_movk_i32 s0, 0x3c0
	v_readlane_b32 s15, v249, 0
	v_and_or_b32 v3, v209, s0, v3
	s_ashr_i32 s0, s15, 31
	v_bitop3_b32 v168, s18, v3, v5 bitop3:0xf6
	s_lshr_b32 s0, s0, 25
	v_mov_b32_e32 v3, v149
	s_add_i32 s0, s15, s0
	v_lshl_add_u64 v[154:155], s[78:79], 0, v[2:3]
	v_lshlrev_b32_e32 v2, 9, v0
	s_and_b32 s1, s0, 0xffffff80
	v_and_b32_e32 v2, 0x30000, v2
	v_lshlrev_b32_e32 v3, 12, v14
	s_sub_i32 s60, s15, s1
	s_ashr_i32 s0, s0, 7
	v_or3_b32 v2, v12, v2, v3
	s_addk_i32 s60, 0x100
	s_lshl_b32 s61, s0, 4
	v_add_u32_e32 v156, v2, v13
	v_lshlrev_b32_e32 v2, 5, v16
	s_waitcnt vmcnt(6)
	s_cmpk_lt_u32 s14, 0x100
	v_and_b32_e32 v2, 0x70000, v2
	v_lshl_or_b32 v1, s7, 6, v205
	s_mov_b32 s7, 0
	s_cselect_b64 s[14:15], -1, 0
	s_lshr_b32 s0, s16, 2
	v_or3_b32 v2, v12, v2, v3
	s_add_i32 s63, 0, 0x10000
	s_add_i32 s64, 0, 0x14000
	s_mov_b32 s55, 0x18000
	s_mov_b32 s56, 0x1a000
	s_mov_b32 s57, 0x8000
	s_mov_b32 s58, 0xa000
	s_mov_b32 s59, 0x1c000
	s_xor_b32 s62, s0, 1
	v_or_b32_e32 v169, s17, v15
	v_mov_b32_e32 v157, v149
	v_add_u32_e32 v158, v2, v13
	v_mov_b32_e32 v159, v149
	s_mov_b64 s[30:31], -1
	v_add_u32_e32 v170, s63, v168
	v_add_u32_e32 v171, s64, v168
	v_add_u32_e32 v172, 0, v4
	s_mov_b32 s65, 0xc000
	s_mov_b32 s66, 0xe000
	s_mov_b32 s17, s7
	s_barrier
	ds_read_b128 v[218:221], v172 offset:6144
	ds_read_b128 v[222:225], v172 offset:7168
	s_branch .LBB0_1113

.Lpeel_8:
	ds_read_b128 v[130:133], v170
	ds_read_b128 v[134:137], v170 offset:1024
	ds_read_b128 v[138:141], v170 offset:2048
	ds_read_b128 v[142:145], v170 offset:3072
	ds_read_b128 v[160:163], v171
	ds_read_b128 v[164:167], v171 offset:1024
	ds_read_b128 v[174:177], v171 offset:2048
	ds_read_b128 v[178:181], v171 offset:3072
	s_add_i32 s31, s21, 2
	s_add_u32 s36, s34, 0xfff80080
	s_addc_u32 s37, s35, -1
	s_cmp_eq_u32 s30, s21
	s_cselect_b32 s39, s23, s37
	s_cselect_b32 s38, s22, s36
	s_cselect_b32 s37, s25, s19
	s_cselect_b32 s36, s24, s17
	v_lshl_add_u64 v[202:203], s[34:35], 0, v[156:157]
	s_add_i32 m0, s27, 0xc000
	ds_read_b128 v[182:185], v172
	ds_read_b128 v[186:189], v172 offset:1024
	ds_read_b128 v[190:193], v172 offset:2048
	ds_read_b128 v[198:201], v172 offset:3072
	ds_read_b128 v[210:213], v172 offset:4096
	ds_read_b128 v[214:217], v172 offset:5120
	global_load_lds_dwordx4 v[202:203], off
	v_lshl_add_u64 v[202:203], s[34:35], 0, v[158:159]
	s_add_i32 m0, s27, 0xe000
	s_nop 0
	global_load_lds_dwordx4 v[202:203], off
	s_waitcnt vmcnt(8)
	s_waitcnt lgkmcnt(0)
	s_barrier
	s_setprio 1
	s_waitcnt lgkmcnt(0)
	v_mfma_f32_16x16x32_bf16 v[126:129], v[130:133], v[182:185], 0
	v_mfma_f32_16x16x32_bf16 v[122:125], v[138:141], v[182:185], 0
	v_mfma_f32_16x16x32_bf16 v[118:121], v[130:133], v[190:193], 0
	v_mfma_f32_16x16x32_bf16 v[110:113], v[138:141], v[190:193], 0
	v_mfma_f32_16x16x32_bf16 v[94:97], v[130:133], v[210:213], 0
	v_mfma_f32_16x16x32_bf16 v[90:93], v[138:141], v[210:213], 0
	v_mfma_f32_16x16x32_bf16 v[78:81], v[130:133], v[218:221], 0
	v_mfma_f32_16x16x32_bf16 v[74:77], v[138:141], v[218:221], 0
	v_mfma_f32_16x16x32_bf16 v[126:129], v[134:137], v[186:189], v[126:129]
	v_mfma_f32_16x16x32_bf16 v[122:125], v[142:145], v[186:189], v[122:125]
	v_mfma_f32_16x16x32_bf16 v[118:121], v[134:137], v[198:201], v[118:121]
	v_mfma_f32_16x16x32_bf16 v[110:113], v[142:145], v[198:201], v[110:113]
	v_mfma_f32_16x16x32_bf16 v[94:97], v[134:137], v[214:217], v[94:97]
	v_mfma_f32_16x16x32_bf16 v[90:93], v[142:145], v[214:217], v[90:93]
	v_mfma_f32_16x16x32_bf16 v[78:81], v[134:137], v[222:225], v[78:81]
	v_mfma_f32_16x16x32_bf16 v[74:77], v[142:145], v[222:225], v[74:77]
	s_setprio 0
	s_setprio 1
	v_mfma_f32_16x16x32_bf16 v[114:117], v[160:163], v[182:185], 0
	v_mfma_f32_16x16x32_bf16 v[106:109], v[174:177], v[182:185], 0
	v_mfma_f32_16x16x32_bf16 v[102:105], v[160:163], v[190:193], 0
	v_mfma_f32_16x16x32_bf16 v[98:101], v[174:177], v[190:193], 0
	v_mfma_f32_16x16x32_bf16 v[86:89], v[160:163], v[210:213], 0
	v_mfma_f32_16x16x32_bf16 v[82:85], v[174:177], v[210:213], 0
	v_mfma_f32_16x16x32_bf16 v[70:73], v[160:163], v[218:221], 0
	v_mfma_f32_16x16x32_bf16 v[66:69], v[174:177], v[218:221], 0
	v_mfma_f32_16x16x32_bf16 v[114:117], v[164:167], v[186:189], v[114:117]
	v_mfma_f32_16x16x32_bf16 v[106:109], v[178:181], v[186:189], v[106:109]
	v_mfma_f32_16x16x32_bf16 v[102:105], v[164:167], v[198:201], v[102:105]
	v_mfma_f32_16x16x32_bf16 v[98:101], v[178:181], v[198:201], v[98:101]
	v_mfma_f32_16x16x32_bf16 v[86:89], v[164:167], v[214:217], v[86:89]
	v_mfma_f32_16x16x32_bf16 v[82:85], v[178:181], v[214:217], v[82:85]
	v_mfma_f32_16x16x32_bf16 v[70:73], v[164:167], v[222:225], v[70:73]
	v_mfma_f32_16x16x32_bf16 v[66:69], v[178:181], v[222:225], v[66:69]
	s_setprio 0
	s_barrier
	s_add_i32 s21, s63, s33
	v_lshl_add_u64 v[202:203], s[36:37], 0, v[148:149]
	s_mov_b32 m0, s21
	ds_read_b128 v[182:185], v172 offset:16384
	ds_read_b128 v[186:189], v172 offset:17408
	ds_read_b128 v[190:193], v172 offset:18432
	ds_read_b128 v[198:201], v172 offset:19456
	ds_read_b128 v[210:213], v172 offset:20480
	ds_read_b128 v[214:217], v172 offset:21504
	ds_read_b128 v[218:221], v172 offset:22528
	ds_read_b128 v[222:225], v172 offset:23552
	global_load_lds_dwordx4 v[202:203], off
	s_add_i32 m0, s21, 0x2000
	s_add_u32 s40, s36, 0x80000
	v_lshl_add_u64 v[206:207], s[36:37], 0, v[152:153]
	s_addc_u32 s41, s37, 0
	s_add_i32 s21, s64, s33
	global_load_lds_dwordx4 v[206:207], off
	v_lshl_add_u64 v[226:227], s[40:41], 0, v[148:149]
	s_mov_b32 m0, s21
	v_lshl_add_u64 v[228:229], s[38:39], 0, v[150:151]
	global_load_lds_dwordx4 v[226:227], off
	v_lshl_add_u64 v[226:227], s[40:41], 0, v[152:153]
	s_add_i32 m0, s21, 0x2000
	s_nop 0
	global_load_lds_dwordx4 v[226:227], off
	v_lshl_add_u64 v[226:227], s[38:39], 0, v[146:147]
	s_mov_b32 m0, s27
	s_nop 0
	global_load_lds_dwordx4 v[226:227], off
	s_mov_b32 m0, s29
	s_nop 0
	global_load_lds_dwordx4 v[228:229], off
	s_waitcnt vmcnt(8)
	s_waitcnt lgkmcnt(0)
	s_barrier
	s_setprio 1
	s_waitcnt lgkmcnt(0)
	v_mfma_f32_16x16x32_bf16 v[62:65], v[130:133], v[182:185], 0
	v_mfma_f32_16x16x32_bf16 v[58:61], v[138:141], v[182:185], 0
	v_mfma_f32_16x16x32_bf16 v[46:49], v[130:133], v[190:193], 0
	v_mfma_f32_16x16x32_bf16 v[42:45], v[138:141], v[190:193], 0
	v_mfma_f32_16x16x32_bf16 v[30:33], v[130:133], v[210:213], 0
	v_mfma_f32_16x16x32_bf16 v[26:29], v[138:141], v[210:213], 0
	v_mfma_f32_16x16x32_bf16 v[14:17], v[130:133], v[218:221], 0
	v_mfma_f32_16x16x32_bf16 v[10:13], v[138:141], v[218:221], 0
	v_mfma_f32_16x16x32_bf16 v[62:65], v[134:137], v[186:189], v[62:65]
	v_mfma_f32_16x16x32_bf16 v[58:61], v[142:145], v[186:189], v[58:61]
	v_mfma_f32_16x16x32_bf16 v[46:49], v[134:137], v[198:201], v[46:49]
	v_mfma_f32_16x16x32_bf16 v[42:45], v[142:145], v[198:201], v[42:45]
	v_mfma_f32_16x16x32_bf16 v[30:33], v[134:137], v[214:217], v[30:33]
	v_mfma_f32_16x16x32_bf16 v[26:29], v[142:145], v[214:217], v[26:29]
	v_mfma_f32_16x16x32_bf16 v[14:17], v[134:137], v[222:225], v[14:17]
	v_mfma_f32_16x16x32_bf16 v[10:13], v[142:145], v[222:225], v[10:13]
	s_setprio 0
	s_setprio 1
	v_mfma_f32_16x16x32_bf16 v[54:57], v[160:163], v[182:185], 0
	v_mfma_f32_16x16x32_bf16 v[50:53], v[174:177], v[182:185], 0
	v_mfma_f32_16x16x32_bf16 v[38:41], v[160:163], v[190:193], 0
	v_mfma_f32_16x16x32_bf16 v[34:37], v[174:177], v[190:193], 0
	v_mfma_f32_16x16x32_bf16 v[22:25], v[160:163], v[210:213], 0
	v_mfma_f32_16x16x32_bf16 v[18:21], v[174:177], v[210:213], 0
	v_mfma_f32_16x16x32_bf16 v[6:9], v[160:163], v[218:221], 0
	v_mfma_f32_16x16x32_bf16 v[2:5], v[174:177], v[218:221], 0
	v_mfma_f32_16x16x32_bf16 v[54:57], v[164:167], v[186:189], v[54:57]
	v_mfma_f32_16x16x32_bf16 v[50:53], v[178:181], v[186:189], v[50:53]
	v_mfma_f32_16x16x32_bf16 v[38:41], v[164:167], v[198:201], v[38:41]
	v_mfma_f32_16x16x32_bf16 v[34:37], v[178:181], v[198:201], v[34:37]
	v_mfma_f32_16x16x32_bf16 v[22:25], v[164:167], v[214:217], v[22:25]
	v_mfma_f32_16x16x32_bf16 v[18:21], v[178:181], v[214:217], v[18:21]
	v_mfma_f32_16x16x32_bf16 v[6:9], v[164:167], v[222:225], v[6:9]
	v_mfma_f32_16x16x32_bf16 v[2:5], v[178:181], v[222:225], v[2:5]
	s_setprio 0
	s_barrier
	s_add_i32 s21, 0, 0x18000
	s_add_i32 s40, 0, 0x1c000
	v_add_u32_e32 v142, s21, v168
	v_add_u32_e32 v173, s40, v168
	ds_read_b128 v[130:133], v142
	ds_read_b128 v[134:137], v142 offset:1024
	ds_read_b128 v[138:141], v142 offset:2048
	ds_read_b128 v[142:145], v142 offset:3072
	ds_read_b128 v[160:163], v173
	ds_read_b128 v[164:167], v173 offset:1024
	ds_read_b128 v[174:177], v173 offset:2048
	ds_read_b128 v[178:181], v173 offset:3072
	s_add_u32 s38, s38, 0x80000
	s_addc_u32 s39, s39, 0
	s_mov_b32 m0, s42
	v_lshl_add_u64 v[230:231], s[38:39], 0, v[146:147]
	ds_read_b128 v[182:185], v172 offset:32768
	ds_read_b128 v[186:189], v172 offset:33792
	ds_read_b128 v[190:193], v172 offset:34816
	ds_read_b128 v[198:201], v172 offset:35840
	ds_read_b128 v[210:213], v172 offset:36864
	ds_read_b128 v[214:217], v172 offset:37888
	ds_read_b128 v[218:221], v172 offset:38912
	ds_read_b128 v[222:225], v172 offset:39936
	global_load_lds_dwordx4 v[230:231], off
	v_lshl_add_u64 v[230:231], s[38:39], 0, v[150:151]
	s_mov_b32 m0, s43
	s_nop 0
	global_load_lds_dwordx4 v[230:231], off
	s_waitcnt vmcnt(8)
	s_waitcnt lgkmcnt(0)
	s_barrier
	s_setprio 1
	s_waitcnt lgkmcnt(0)
	v_mfma_f32_16x16x32_bf16 v[126:129], v[130:133], v[182:185], v[126:129]
	v_mfma_f32_16x16x32_bf16 v[122:125], v[138:141], v[182:185], v[122:125]
	v_mfma_f32_16x16x32_bf16 v[118:121], v[130:133], v[190:193], v[118:121]
	v_mfma_f32_16x16x32_bf16 v[110:113], v[138:141], v[190:193], v[110:113]
	v_mfma_f32_16x16x32_bf16 v[94:97], v[130:133], v[210:213], v[94:97]
	v_mfma_f32_16x16x32_bf16 v[90:93], v[138:141], v[210:213], v[90:93]
	v_mfma_f32_16x16x32_bf16 v[78:81], v[130:133], v[218:221], v[78:81]
	v_mfma_f32_16x16x32_bf16 v[74:77], v[138:141], v[218:221], v[74:77]
	v_mfma_f32_16x16x32_bf16 v[126:129], v[134:137], v[186:189], v[126:129]
	v_mfma_f32_16x16x32_bf16 v[122:125], v[142:145], v[186:189], v[122:125]
	v_mfma_f32_16x16x32_bf16 v[118:121], v[134:137], v[198:201], v[118:121]
	v_mfma_f32_16x16x32_bf16 v[110:113], v[142:145], v[198:201], v[110:113]
	v_mfma_f32_16x16x32_bf16 v[94:97], v[134:137], v[214:217], v[94:97]
	v_mfma_f32_16x16x32_bf16 v[90:93], v[142:145], v[214:217], v[90:93]
	v_mfma_f32_16x16x32_bf16 v[78:81], v[134:137], v[222:225], v[78:81]
	v_mfma_f32_16x16x32_bf16 v[74:77], v[142:145], v[222:225], v[74:77]
	s_setprio 0
	s_setprio 1
	v_mfma_f32_16x16x32_bf16 v[114:117], v[160:163], v[182:185], v[114:117]
	v_mfma_f32_16x16x32_bf16 v[106:109], v[174:177], v[182:185], v[106:109]
	v_mfma_f32_16x16x32_bf16 v[102:105], v[160:163], v[190:193], v[102:105]
	v_mfma_f32_16x16x32_bf16 v[98:101], v[174:177], v[190:193], v[98:101]
	v_mfma_f32_16x16x32_bf16 v[86:89], v[160:163], v[210:213], v[86:89]
	v_mfma_f32_16x16x32_bf16 v[82:85], v[174:177], v[210:213], v[82:85]
	v_mfma_f32_16x16x32_bf16 v[70:73], v[160:163], v[218:221], v[70:73]
	v_mfma_f32_16x16x32_bf16 v[66:69], v[174:177], v[218:221], v[66:69]
	v_mfma_f32_16x16x32_bf16 v[114:117], v[164:167], v[186:189], v[114:117]
	v_mfma_f32_16x16x32_bf16 v[106:109], v[178:181], v[186:189], v[106:109]
	v_mfma_f32_16x16x32_bf16 v[102:105], v[164:167], v[198:201], v[102:105]
	v_mfma_f32_16x16x32_bf16 v[98:101], v[178:181], v[198:201], v[98:101]
	v_mfma_f32_16x16x32_bf16 v[86:89], v[164:167], v[214:217], v[86:89]
	v_mfma_f32_16x16x32_bf16 v[82:85], v[178:181], v[214:217], v[82:85]
	v_mfma_f32_16x16x32_bf16 v[70:73], v[164:167], v[222:225], v[70:73]
	v_mfma_f32_16x16x32_bf16 v[66:69], v[178:181], v[222:225], v[66:69]
	s_setprio 0
	s_barrier
	s_add_i32 s21, s21, s33
	v_lshl_add_u64 v[202:203], v[202:203], 0, s[12:13]
	s_mov_b32 m0, s21
	ds_read_b128 v[182:185], v172 offset:49152
	ds_read_b128 v[186:189], v172 offset:50176
	ds_read_b128 v[190:193], v172 offset:51200
	ds_read_b128 v[198:201], v172 offset:52224
	ds_read_b128 v[210:213], v172 offset:53248
	ds_read_b128 v[214:217], v172 offset:54272
	ds_read_b128 v[218:221], v172 offset:55296
	ds_read_b128 v[222:225], v172 offset:56320
	global_load_lds_dwordx4 v[202:203], off
	s_add_i32 m0, s21, 0x2000
	s_add_u32 s36, s36, 0x80080
	v_lshl_add_u64 v[202:203], v[206:207], 0, s[12:13]
	s_addc_u32 s37, s37, 0
	s_add_i32 s21, s40, s33
	global_load_lds_dwordx4 v[202:203], off
	v_lshl_add_u64 v[202:203], s[36:37], 0, v[148:149]
	s_mov_b32 m0, s21
	s_nop 0
	global_load_lds_dwordx4 v[202:203], off
	v_lshl_add_u64 v[202:203], s[36:37], 0, v[152:153]
	s_add_i32 m0, s21, 0x2000
	s_nop 0
	global_load_lds_dwordx4 v[202:203], off
	v_lshl_add_u64 v[202:203], v[226:227], 0, s[12:13]
	s_mov_b32 m0, s53
	s_nop 0
	global_load_lds_dwordx4 v[202:203], off
	v_lshl_add_u64 v[202:203], v[228:229], 0, s[12:13]
	s_mov_b32 m0, s54
	s_nop 0
	global_load_lds_dwordx4 v[202:203], off
	s_waitcnt vmcnt(8)
	s_waitcnt lgkmcnt(0)
	s_barrier
	s_setprio 1
	s_waitcnt lgkmcnt(0)
	v_mfma_f32_16x16x32_bf16 v[62:65], v[130:133], v[182:185], v[62:65]
	v_mfma_f32_16x16x32_bf16 v[58:61], v[138:141], v[182:185], v[58:61]
	v_mfma_f32_16x16x32_bf16 v[46:49], v[130:133], v[190:193], v[46:49]
	v_mfma_f32_16x16x32_bf16 v[42:45], v[138:141], v[190:193], v[42:45]
	v_mfma_f32_16x16x32_bf16 v[30:33], v[130:133], v[210:213], v[30:33]
	v_mfma_f32_16x16x32_bf16 v[26:29], v[138:141], v[210:213], v[26:29]
	v_mfma_f32_16x16x32_bf16 v[14:17], v[130:133], v[218:221], v[14:17]
	v_mfma_f32_16x16x32_bf16 v[10:13], v[138:141], v[218:221], v[10:13]
	v_mfma_f32_16x16x32_bf16 v[62:65], v[134:137], v[186:189], v[62:65]
	v_mfma_f32_16x16x32_bf16 v[58:61], v[142:145], v[186:189], v[58:61]
	v_mfma_f32_16x16x32_bf16 v[46:49], v[134:137], v[198:201], v[46:49]
	v_mfma_f32_16x16x32_bf16 v[42:45], v[142:145], v[198:201], v[42:45]
	v_mfma_f32_16x16x32_bf16 v[30:33], v[134:137], v[214:217], v[30:33]
	v_mfma_f32_16x16x32_bf16 v[26:29], v[142:145], v[214:217], v[26:29]
	v_mfma_f32_16x16x32_bf16 v[14:17], v[134:137], v[222:225], v[14:17]
	v_mfma_f32_16x16x32_bf16 v[10:13], v[142:145], v[222:225], v[10:13]
	s_setprio 0
	s_setprio 1
	v_mfma_f32_16x16x32_bf16 v[54:57], v[160:163], v[182:185], v[54:57]
	v_mfma_f32_16x16x32_bf16 v[50:53], v[174:177], v[182:185], v[50:53]
	v_mfma_f32_16x16x32_bf16 v[38:41], v[160:163], v[190:193], v[38:41]
	v_mfma_f32_16x16x32_bf16 v[34:37], v[174:177], v[190:193], v[34:37]
	v_mfma_f32_16x16x32_bf16 v[22:25], v[160:163], v[210:213], v[22:25]
	v_mfma_f32_16x16x32_bf16 v[18:21], v[174:177], v[210:213], v[18:21]
	v_mfma_f32_16x16x32_bf16 v[6:9], v[160:163], v[218:221], v[6:9]
	v_mfma_f32_16x16x32_bf16 v[2:5], v[174:177], v[218:221], v[2:5]
	v_mfma_f32_16x16x32_bf16 v[54:57], v[164:167], v[186:189], v[54:57]
	v_mfma_f32_16x16x32_bf16 v[50:53], v[178:181], v[186:189], v[50:53]
	v_mfma_f32_16x16x32_bf16 v[38:41], v[164:167], v[198:201], v[38:41]
	v_mfma_f32_16x16x32_bf16 v[34:37], v[178:181], v[198:201], v[34:37]
	v_mfma_f32_16x16x32_bf16 v[22:25], v[164:167], v[214:217], v[22:25]
	v_mfma_f32_16x16x32_bf16 v[18:21], v[178:181], v[214:217], v[18:21]
	v_mfma_f32_16x16x32_bf16 v[6:9], v[164:167], v[222:225], v[6:9]
	v_mfma_f32_16x16x32_bf16 v[2:5], v[178:181], v[222:225], v[2:5]
	s_setprio 0
	s_barrier
	s_add_u32 s34, s34, 0x100
	s_addc_u32 s35, s35, 0
	s_add_u32 s17, s17, 0x100
	s_addc_u32 s19, s19, 0
	s_cmp_ge_i32 s31, s69
	s_mov_b32 s21, s31
	s_cbranch_scc0 .LBB0_1122
	s_branch .Lpeeldone_8

.Lpeeldone_8:
	ds_read_b128 v[218:221], v172 offset:6144
	ds_read_b128 v[222:225], v172 offset:7168
	s_and_b64 vcc, exec, s[14:15]
	s_cbranch_vccnz .LBB0_1130
	s_cmp_gt_i32 s6, -1
	s_mov_b64 s[30:31], -1
	s_cbranch_scc1 .LBB0_1131

.LBB0_1302:
	s_lshl_b32 s10, s10, 5
	s_and_b32 s16, s10, 0x60
	s_mov_b64 s[10:11], 0x80
	s_add_i32 m0, s27, 0x18000
	v_lshl_add_u64 v[10:11], v[10:11], 0, s[10:11]
	s_lshl_b32 s13, s7, 13
	s_lshl_b32 s17, s16, 7
	s_waitcnt vmcnt(2)
	s_barrier
	global_load_lds_dwordx4 v[10:11], off
	v_lshl_add_u64 v[6:7], v[6:7], 0, s[10:11]
	s_add_i32 m0, s27, 0x1a000
	s_add_i32 s51, s27, 0x8000
	s_add_i32 s52, s27, 0xa000
	global_load_lds_dwordx4 v[6:7], off
	v_lshl_add_u64 v[6:7], v[8:9], 0, s[10:11]
	s_mov_b32 m0, s51
	s_add_u32 s14, s34, 0x80080
	global_load_lds_dwordx4 v[6:7], off
	v_lshl_add_u64 v[4:5], v[4:5], 0, s[10:11]
	s_mov_b32 m0, s52
	s_addc_u32 s15, s35, 0
	global_load_lds_dwordx4 v[4:5], off
	s_add_i32 m0, s27, 0x1c000
	v_lshl_add_u64 v[4:5], s[14:15], 0, v[132:133]
	global_load_lds_dwordx4 v[4:5], off
	v_lshl_add_u64 v[4:5], s[14:15], 0, v[136:137]
	s_add_i32 m0, s27, 0x1e000
	v_lshlrev_b32_e32 v3, 1, v15
	global_load_lds_dwordx4 v[4:5], off
	v_lshl_or_b32 v1, s7, 6, v205
	v_lshl_or_b32 v4, v205, 6, v3
	v_and_b32_e32 v5, 32, v196
	s_movk_i32 s7, 0x3c0
	v_readlane_b32 s15, v249, 0
	v_bitop3_b32 v4, v4, s13, v5 bitop3:0xde
	v_and_or_b32 v3, v209, s7, v3
	s_ashr_i32 s13, s15, 31
	v_bitop3_b32 v146, s17, v3, v5 bitop3:0xf6
	s_lshr_b32 s13, s13, 26
	v_mov_b32_e32 v3, v133
	s_add_i32 s13, s15, s13
	v_lshl_add_u64 v[138:139], s[78:79], 0, v[2:3]
	v_lshlrev_b32_e32 v2, 9, v0
	s_and_b32 s14, s13, 0xffffffc0
	v_and_b32_e32 v2, 0x30000, v2
	v_lshlrev_b32_e32 v3, 12, v14
	s_sub_i32 s58, s15, s14
	s_ashr_i32 s13, s13, 6
	v_or3_b32 v2, v12, v2, v3
	s_addk_i32 s58, 0x800
	s_lshl_b32 s59, s13, 3
	v_add_u32_e32 v140, v2, v13
	v_lshlrev_b32_e32 v2, 5, v16
	s_waitcnt vmcnt(6)
	s_cmpk_lt_u32 s12, 0x100
	v_and_b32_e32 v2, 0x70000, v2
	s_mov_b32 s7, 0
	s_cselect_b64 s[12:13], -1, 0
	v_or3_b32 v2, v12, v2, v3
	s_add_i32 s60, 0, 0x10000
	s_add_i32 s61, 0, 0x14000
	s_mov_b32 s53, 0x18000
	s_mov_b32 s54, 0x1a000
	s_mov_b32 s55, 0x8000
	s_mov_b32 s56, 0xa000
	s_mov_b32 s57, 0x1c000
	v_or_b32_e32 v147, s16, v15
	v_mov_b32_e32 v141, v133
	v_add_u32_e32 v142, v2, v13
	v_mov_b32_e32 v143, v133
	v_add_u32_e32 v148, s60, v146
	v_add_u32_e32 v149, s61, v146
	v_add_u32_e32 v150, 0, v4
	s_mov_b32 s62, 0xc000
	s_mov_b32 s63, 0xe000
	s_movk_i32 s64, 0x2c00
	s_mov_b32 s25, s7
	s_barrier
	ds_read_b128 v[160:163], v148 offset:2048
	ds_read_b128 v[164:167], v148 offset:3072
	ds_read_b128 v[168:171], v149
	ds_read_b128 v[172:175], v149 offset:1024
	ds_read_b128 v[176:179], v149 offset:2048
	ds_read_b128 v[180:183], v149 offset:3072
	ds_read_b128 v[184:187], v150
	ds_read_b128 v[188:191], v150 offset:1024
	ds_read_b128 v[198:201], v150 offset:2048
	ds_read_b128 v[210:213], v150 offset:3072
	ds_read_b128 v[214:217], v150 offset:4096
	ds_read_b128 v[218:221], v150 offset:5120
	ds_read_b128 v[222:225], v150 offset:6144
	ds_read_b128 v[226:229], v150 offset:7168
	s_branch .LBB0_1305

.Lpeel_7:
	ds_read_b128 v[152:155], v148
	ds_read_b128 v[156:159], v148 offset:1024
	s_add_i32 s29, s19, 2
	s_add_u32 s34, s30, 0xfff80080
	s_addc_u32 s35, s31, -1
	s_cmp_eq_u32 s28, s19
	s_cselect_b32 s37, s21, s35
	s_cselect_b32 s36, s20, s34
	s_cselect_b32 s35, s23, s17
	s_cselect_b32 s34, s22, s15
	v_lshl_add_u64 v[144:145], s[30:31], 0, v[140:141]
	s_add_i32 m0, s27, 0xc000
	global_load_lds_dwordx4 v[144:145], off
	v_lshl_add_u64 v[144:145], s[30:31], 0, v[142:143]
	s_add_i32 m0, s27, 0xe000
	s_nop 0
	global_load_lds_dwordx4 v[144:145], off
	s_waitcnt vmcnt(8)
	s_waitcnt lgkmcnt(0)
	s_barrier
	s_setprio 1
	s_waitcnt lgkmcnt(0)
	v_mfma_f32_16x16x32_bf16 v[126:129], v[152:155], v[184:187], 0
	v_mfma_f32_16x16x32_bf16 v[122:125], v[160:163], v[184:187], 0
	v_mfma_f32_16x16x32_bf16 v[110:113], v[152:155], v[198:201], 0
	v_mfma_f32_16x16x32_bf16 v[106:109], v[160:163], v[198:201], 0
	v_mfma_f32_16x16x32_bf16 v[94:97], v[152:155], v[214:217], 0
	v_mfma_f32_16x16x32_bf16 v[90:93], v[160:163], v[214:217], 0
	v_mfma_f32_16x16x32_bf16 v[78:81], v[152:155], v[222:225], 0
	v_mfma_f32_16x16x32_bf16 v[74:77], v[160:163], v[222:225], 0
	v_mfma_f32_16x16x32_bf16 v[126:129], v[156:159], v[188:191], v[126:129]
	v_mfma_f32_16x16x32_bf16 v[122:125], v[164:167], v[188:191], v[122:125]
	v_mfma_f32_16x16x32_bf16 v[110:113], v[156:159], v[210:213], v[110:113]
	v_mfma_f32_16x16x32_bf16 v[106:109], v[164:167], v[210:213], v[106:109]
	v_mfma_f32_16x16x32_bf16 v[94:97], v[156:159], v[218:221], v[94:97]
	v_mfma_f32_16x16x32_bf16 v[90:93], v[164:167], v[218:221], v[90:93]
	v_mfma_f32_16x16x32_bf16 v[78:81], v[156:159], v[226:229], v[78:81]
	v_mfma_f32_16x16x32_bf16 v[74:77], v[164:167], v[226:229], v[74:77]
	s_setprio 0
	s_setprio 1
	v_mfma_f32_16x16x32_bf16 v[118:121], v[168:171], v[184:187], 0
	v_mfma_f32_16x16x32_bf16 v[114:117], v[176:179], v[184:187], 0
	v_mfma_f32_16x16x32_bf16 v[102:105], v[168:171], v[198:201], 0
	v_mfma_f32_16x16x32_bf16 v[98:101], v[176:179], v[198:201], 0
	v_mfma_f32_16x16x32_bf16 v[86:89], v[168:171], v[214:217], 0
	v_mfma_f32_16x16x32_bf16 v[82:85], v[176:179], v[214:217], 0
	v_mfma_f32_16x16x32_bf16 v[70:73], v[168:171], v[222:225], 0
	v_mfma_f32_16x16x32_bf16 v[66:69], v[176:179], v[222:225], 0
	v_mfma_f32_16x16x32_bf16 v[118:121], v[172:175], v[188:191], v[118:121]
	v_mfma_f32_16x16x32_bf16 v[114:117], v[180:183], v[188:191], v[114:117]
	v_mfma_f32_16x16x32_bf16 v[102:105], v[172:175], v[210:213], v[102:105]
	v_mfma_f32_16x16x32_bf16 v[98:101], v[180:183], v[210:213], v[98:101]
	v_mfma_f32_16x16x32_bf16 v[86:89], v[172:175], v[218:221], v[86:89]
	v_mfma_f32_16x16x32_bf16 v[82:85], v[180:183], v[218:221], v[82:85]
	v_mfma_f32_16x16x32_bf16 v[70:73], v[172:175], v[226:229], v[70:73]
	v_mfma_f32_16x16x32_bf16 v[66:69], v[180:183], v[226:229], v[66:69]
	s_setprio 0
	s_barrier
	s_add_i32 s19, s60, s33
	v_lshl_add_u64 v[144:145], s[34:35], 0, v[132:133]
	s_mov_b32 m0, s19
	ds_read_b128 v[184:187], v150 offset:16384
	ds_read_b128 v[188:191], v150 offset:17408
	ds_read_b128 v[198:201], v150 offset:18432
	ds_read_b128 v[210:213], v150 offset:19456
	ds_read_b128 v[214:217], v150 offset:20480
	ds_read_b128 v[218:221], v150 offset:21504
	ds_read_b128 v[222:225], v150 offset:22528
	ds_read_b128 v[226:229], v150 offset:23552
	global_load_lds_dwordx4 v[144:145], off
	s_add_i32 m0, s19, 0x2000
	s_add_u32 s38, s34, 0x80000
	v_lshl_add_u64 v[192:193], s[34:35], 0, v[136:137]
	s_addc_u32 s39, s35, 0
	s_add_i32 s19, s61, s33
	global_load_lds_dwordx4 v[192:193], off
	v_lshl_add_u64 v[202:203], s[38:39], 0, v[132:133]
	s_mov_b32 m0, s19
	v_lshl_add_u64 v[206:207], s[36:37], 0, v[134:135]
	global_load_lds_dwordx4 v[202:203], off
	v_lshl_add_u64 v[202:203], s[38:39], 0, v[136:137]
	s_add_i32 m0, s19, 0x2000
	s_nop 0
	global_load_lds_dwordx4 v[202:203], off
	v_lshl_add_u64 v[202:203], s[36:37], 0, v[130:131]
	s_mov_b32 m0, s27
	s_nop 0
	global_load_lds_dwordx4 v[202:203], off
	s_mov_b32 m0, s41
	s_nop 0
	global_load_lds_dwordx4 v[206:207], off
	s_waitcnt vmcnt(8)
	s_waitcnt lgkmcnt(0)
	s_barrier
	s_setprio 1
	s_waitcnt lgkmcnt(0)
	v_mfma_f32_16x16x32_bf16 v[62:65], v[152:155], v[184:187], 0
	v_mfma_f32_16x16x32_bf16 v[58:61], v[160:163], v[184:187], 0
	v_mfma_f32_16x16x32_bf16 v[46:49], v[152:155], v[198:201], 0
	v_mfma_f32_16x16x32_bf16 v[42:45], v[160:163], v[198:201], 0
	v_mfma_f32_16x16x32_bf16 v[30:33], v[152:155], v[214:217], 0
	v_mfma_f32_16x16x32_bf16 v[26:29], v[160:163], v[214:217], 0
	v_mfma_f32_16x16x32_bf16 v[14:17], v[152:155], v[222:225], 0
	v_mfma_f32_16x16x32_bf16 v[10:13], v[160:163], v[222:225], 0
	v_mfma_f32_16x16x32_bf16 v[62:65], v[156:159], v[188:191], v[62:65]
	v_mfma_f32_16x16x32_bf16 v[58:61], v[164:167], v[188:191], v[58:61]
	v_mfma_f32_16x16x32_bf16 v[46:49], v[156:159], v[210:213], v[46:49]
	v_mfma_f32_16x16x32_bf16 v[42:45], v[164:167], v[210:213], v[42:45]
	v_mfma_f32_16x16x32_bf16 v[30:33], v[156:159], v[218:221], v[30:33]
	v_mfma_f32_16x16x32_bf16 v[26:29], v[164:167], v[218:221], v[26:29]
	v_mfma_f32_16x16x32_bf16 v[14:17], v[156:159], v[226:229], v[14:17]
	v_mfma_f32_16x16x32_bf16 v[10:13], v[164:167], v[226:229], v[10:13]
	s_setprio 0
	s_setprio 1
	v_mfma_f32_16x16x32_bf16 v[54:57], v[168:171], v[184:187], 0
	v_mfma_f32_16x16x32_bf16 v[50:53], v[176:179], v[184:187], 0
	v_mfma_f32_16x16x32_bf16 v[38:41], v[168:171], v[198:201], 0
	v_mfma_f32_16x16x32_bf16 v[34:37], v[176:179], v[198:201], 0
	v_mfma_f32_16x16x32_bf16 v[22:25], v[168:171], v[214:217], 0
	v_mfma_f32_16x16x32_bf16 v[18:21], v[176:179], v[214:217], 0
	v_mfma_f32_16x16x32_bf16 v[6:9], v[168:171], v[222:225], 0
	v_mfma_f32_16x16x32_bf16 v[2:5], v[176:179], v[222:225], 0
	v_mfma_f32_16x16x32_bf16 v[54:57], v[172:175], v[188:191], v[54:57]
	v_mfma_f32_16x16x32_bf16 v[50:53], v[180:183], v[188:191], v[50:53]
	v_mfma_f32_16x16x32_bf16 v[38:41], v[172:175], v[210:213], v[38:41]
	v_mfma_f32_16x16x32_bf16 v[34:37], v[180:183], v[210:213], v[34:37]
	v_mfma_f32_16x16x32_bf16 v[22:25], v[172:175], v[218:221], v[22:25]
	v_mfma_f32_16x16x32_bf16 v[18:21], v[180:183], v[218:221], v[18:21]
	v_mfma_f32_16x16x32_bf16 v[6:9], v[172:175], v[226:229], v[6:9]
	v_mfma_f32_16x16x32_bf16 v[2:5], v[180:183], v[226:229], v[2:5]
	s_setprio 0
	s_barrier
	s_add_i32 s19, 0, 0x18000
	v_add_u32_e32 v151, s19, v146
	s_add_i32 s38, 0, 0x1c000
	ds_read_b128 v[152:155], v151
	ds_read_b128 v[156:159], v151 offset:1024
	ds_read_b128 v[160:163], v151 offset:2048
	ds_read_b128 v[164:167], v151 offset:3072
	v_add_u32_e32 v151, s38, v146
	ds_read_b128 v[168:171], v151
	ds_read_b128 v[172:175], v151 offset:1024
	ds_read_b128 v[176:179], v151 offset:2048
	ds_read_b128 v[180:183], v151 offset:3072
	s_add_u32 s36, s36, 0x80000
	s_addc_u32 s37, s37, 0
	s_mov_b32 m0, s42
	v_lshl_add_u64 v[230:231], s[36:37], 0, v[130:131]
	ds_read_b128 v[184:187], v150 offset:32768
	ds_read_b128 v[188:191], v150 offset:33792
	ds_read_b128 v[198:201], v150 offset:34816
	ds_read_b128 v[210:213], v150 offset:35840
	ds_read_b128 v[214:217], v150 offset:36864
	ds_read_b128 v[218:221], v150 offset:37888
	ds_read_b128 v[222:225], v150 offset:38912
	ds_read_b128 v[226:229], v150 offset:39936
	global_load_lds_dwordx4 v[230:231], off
	v_lshl_add_u64 v[230:231], s[36:37], 0, v[134:135]
	s_mov_b32 m0, s43
	s_nop 0
	global_load_lds_dwordx4 v[230:231], off
	s_waitcnt vmcnt(8)
	s_waitcnt lgkmcnt(0)
	s_barrier
	s_setprio 1
	s_waitcnt lgkmcnt(0)
	v_mfma_f32_16x16x32_bf16 v[126:129], v[152:155], v[184:187], v[126:129]
	v_mfma_f32_16x16x32_bf16 v[122:125], v[160:163], v[184:187], v[122:125]
	v_mfma_f32_16x16x32_bf16 v[110:113], v[152:155], v[198:201], v[110:113]
	v_mfma_f32_16x16x32_bf16 v[106:109], v[160:163], v[198:201], v[106:109]
	v_mfma_f32_16x16x32_bf16 v[94:97], v[152:155], v[214:217], v[94:97]
	v_mfma_f32_16x16x32_bf16 v[90:93], v[160:163], v[214:217], v[90:93]
	v_mfma_f32_16x16x32_bf16 v[78:81], v[152:155], v[222:225], v[78:81]
	v_mfma_f32_16x16x32_bf16 v[74:77], v[160:163], v[222:225], v[74:77]
	v_mfma_f32_16x16x32_bf16 v[126:129], v[156:159], v[188:191], v[126:129]
	v_mfma_f32_16x16x32_bf16 v[122:125], v[164:167], v[188:191], v[122:125]
	v_mfma_f32_16x16x32_bf16 v[110:113], v[156:159], v[210:213], v[110:113]
	v_mfma_f32_16x16x32_bf16 v[106:109], v[164:167], v[210:213], v[106:109]
	v_mfma_f32_16x16x32_bf16 v[94:97], v[156:159], v[218:221], v[94:97]
	v_mfma_f32_16x16x32_bf16 v[90:93], v[164:167], v[218:221], v[90:93]
	v_mfma_f32_16x16x32_bf16 v[78:81], v[156:159], v[226:229], v[78:81]
	v_mfma_f32_16x16x32_bf16 v[74:77], v[164:167], v[226:229], v[74:77]
	s_setprio 0
	s_setprio 1
	v_mfma_f32_16x16x32_bf16 v[118:121], v[168:171], v[184:187], v[118:121]
	v_mfma_f32_16x16x32_bf16 v[114:117], v[176:179], v[184:187], v[114:117]
	v_mfma_f32_16x16x32_bf16 v[102:105], v[168:171], v[198:201], v[102:105]
	v_mfma_f32_16x16x32_bf16 v[98:101], v[176:179], v[198:201], v[98:101]
	v_mfma_f32_16x16x32_bf16 v[86:89], v[168:171], v[214:217], v[86:89]
	v_mfma_f32_16x16x32_bf16 v[82:85], v[176:179], v[214:217], v[82:85]
	v_mfma_f32_16x16x32_bf16 v[70:73], v[168:171], v[222:225], v[70:73]
	v_mfma_f32_16x16x32_bf16 v[66:69], v[176:179], v[222:225], v[66:69]
	v_mfma_f32_16x16x32_bf16 v[118:121], v[172:175], v[188:191], v[118:121]
	v_mfma_f32_16x16x32_bf16 v[114:117], v[180:183], v[188:191], v[114:117]
	v_mfma_f32_16x16x32_bf16 v[102:105], v[172:175], v[210:213], v[102:105]
	v_mfma_f32_16x16x32_bf16 v[98:101], v[180:183], v[210:213], v[98:101]
	v_mfma_f32_16x16x32_bf16 v[86:89], v[172:175], v[218:221], v[86:89]
	v_mfma_f32_16x16x32_bf16 v[82:85], v[180:183], v[218:221], v[82:85]
	v_mfma_f32_16x16x32_bf16 v[70:73], v[172:175], v[226:229], v[70:73]
	v_mfma_f32_16x16x32_bf16 v[66:69], v[180:183], v[226:229], v[66:69]
	s_setprio 0
	s_barrier
	s_add_i32 s19, s19, s33
	v_lshl_add_u64 v[144:145], v[144:145], 0, s[10:11]
	s_mov_b32 m0, s19
	ds_read_b128 v[184:187], v150 offset:49152
	ds_read_b128 v[188:191], v150 offset:50176
	ds_read_b128 v[198:201], v150 offset:51200
	ds_read_b128 v[210:213], v150 offset:52224
	ds_read_b128 v[214:217], v150 offset:53248
	ds_read_b128 v[218:221], v150 offset:54272
	ds_read_b128 v[222:225], v150 offset:55296
	ds_read_b128 v[226:229], v150 offset:56320
	global_load_lds_dwordx4 v[144:145], off
	s_add_i32 m0, s19, 0x2000
	s_add_u32 s34, s34, 0x80080
	v_lshl_add_u64 v[144:145], v[192:193], 0, s[10:11]
	s_addc_u32 s35, s35, 0
	s_add_i32 s19, s38, s33
	global_load_lds_dwordx4 v[144:145], off
	v_lshl_add_u64 v[144:145], s[34:35], 0, v[132:133]
	s_mov_b32 m0, s19
	s_nop 0
	global_load_lds_dwordx4 v[144:145], off
	v_lshl_add_u64 v[144:145], s[34:35], 0, v[136:137]
	s_add_i32 m0, s19, 0x2000
	s_nop 0
	global_load_lds_dwordx4 v[144:145], off
	v_lshl_add_u64 v[144:145], v[202:203], 0, s[10:11]
	s_mov_b32 m0, s51
	s_nop 0
	global_load_lds_dwordx4 v[144:145], off
	v_lshl_add_u64 v[144:145], v[206:207], 0, s[10:11]
	s_mov_b32 m0, s52
	s_nop 0
	global_load_lds_dwordx4 v[144:145], off
	s_waitcnt vmcnt(8)
	s_waitcnt lgkmcnt(0)
	s_barrier
	s_setprio 1
	s_waitcnt lgkmcnt(0)
	v_mfma_f32_16x16x32_bf16 v[62:65], v[152:155], v[184:187], v[62:65]
	v_mfma_f32_16x16x32_bf16 v[58:61], v[160:163], v[184:187], v[58:61]
	v_mfma_f32_16x16x32_bf16 v[46:49], v[152:155], v[198:201], v[46:49]
	v_mfma_f32_16x16x32_bf16 v[42:45], v[160:163], v[198:201], v[42:45]
	v_mfma_f32_16x16x32_bf16 v[30:33], v[152:155], v[214:217], v[30:33]
	v_mfma_f32_16x16x32_bf16 v[26:29], v[160:163], v[214:217], v[26:29]
	v_mfma_f32_16x16x32_bf16 v[14:17], v[152:155], v[222:225], v[14:17]
	v_mfma_f32_16x16x32_bf16 v[10:13], v[160:163], v[222:225], v[10:13]
	v_mfma_f32_16x16x32_bf16 v[62:65], v[156:159], v[188:191], v[62:65]
	v_mfma_f32_16x16x32_bf16 v[58:61], v[164:167], v[188:191], v[58:61]
	v_mfma_f32_16x16x32_bf16 v[46:49], v[156:159], v[210:213], v[46:49]
	v_mfma_f32_16x16x32_bf16 v[42:45], v[164:167], v[210:213], v[42:45]
	v_mfma_f32_16x16x32_bf16 v[30:33], v[156:159], v[218:221], v[30:33]
	v_mfma_f32_16x16x32_bf16 v[26:29], v[164:167], v[218:221], v[26:29]
	v_mfma_f32_16x16x32_bf16 v[14:17], v[156:159], v[226:229], v[14:17]
	v_mfma_f32_16x16x32_bf16 v[10:13], v[164:167], v[226:229], v[10:13]
	s_setprio 0
	s_setprio 1
	v_mfma_f32_16x16x32_bf16 v[54:57], v[168:171], v[184:187], v[54:57]
	v_mfma_f32_16x16x32_bf16 v[50:53], v[176:179], v[184:187], v[50:53]
	v_mfma_f32_16x16x32_bf16 v[38:41], v[168:171], v[198:201], v[38:41]
	v_mfma_f32_16x16x32_bf16 v[34:37], v[176:179], v[198:201], v[34:37]
	v_mfma_f32_16x16x32_bf16 v[22:25], v[168:171], v[214:217], v[22:25]
	v_mfma_f32_16x16x32_bf16 v[18:21], v[176:179], v[214:217], v[18:21]
	v_mfma_f32_16x16x32_bf16 v[6:9], v[168:171], v[222:225], v[6:9]
	v_mfma_f32_16x16x32_bf16 v[2:5], v[176:179], v[222:225], v[2:5]
	v_mfma_f32_16x16x32_bf16 v[54:57], v[172:175], v[188:191], v[54:57]
	v_mfma_f32_16x16x32_bf16 v[50:53], v[180:183], v[188:191], v[50:53]
	v_mfma_f32_16x16x32_bf16 v[38:41], v[172:175], v[210:213], v[38:41]
	v_mfma_f32_16x16x32_bf16 v[34:37], v[180:183], v[210:213], v[34:37]
	v_mfma_f32_16x16x32_bf16 v[22:25], v[172:175], v[218:221], v[22:25]
	v_mfma_f32_16x16x32_bf16 v[18:21], v[180:183], v[218:221], v[18:21]
	v_mfma_f32_16x16x32_bf16 v[6:9], v[172:175], v[226:229], v[6:9]
	v_mfma_f32_16x16x32_bf16 v[2:5], v[180:183], v[226:229], v[2:5]
	s_setprio 0
	s_barrier
	s_add_u32 s30, s30, 0x100
	s_addc_u32 s31, s31, 0
	s_add_u32 s15, s15, 0x100
	s_addc_u32 s17, s17, 0
	s_cmp_ge_i32 s29, s68
	s_mov_b32 s19, s29
	s_cbranch_scc0 .LBB0_1315
	s_branch .Lpeeldone_7

.Lpeeldone_7:
	ds_read_b128 v[160:163], v148 offset:2048
	ds_read_b128 v[164:167], v148 offset:3072
	ds_read_b128 v[168:171], v149
	ds_read_b128 v[172:175], v149 offset:1024
	ds_read_b128 v[176:179], v149 offset:2048
	ds_read_b128 v[180:183], v149 offset:3072
	ds_read_b128 v[184:187], v150
	ds_read_b128 v[188:191], v150 offset:1024
	ds_read_b128 v[198:201], v150 offset:2048
	ds_read_b128 v[210:213], v150 offset:3072
	ds_read_b128 v[214:217], v150 offset:4096
	ds_read_b128 v[218:221], v150 offset:5120
	ds_read_b128 v[222:225], v150 offset:6144
	ds_read_b128 v[226:229], v150 offset:7168
	s_and_b64 vcc, exec, s[12:13]
	s_cbranch_vccnz .LBB0_1323
	s_cmp_gt_i32 s6, -1
	s_mov_b64 s[28:29], -1
	s_cbranch_scc1 .LBB0_1324

.LBB0_1960:
	s_lshl_b32 s10, s10, 5
	s_and_b32 s20, s10, 0x60
	s_mov_b64 s[10:11], 0x80
	s_add_i32 m0, s15, 0x18000
	v_lshl_add_u64 v[10:11], v[10:11], 0, s[10:11]
	s_lshl_b32 s13, s7, 13
	s_lshl_b32 s17, s20, 7
	s_waitcnt vmcnt(2)
	s_barrier
	global_load_lds_dwordx4 v[10:11], off
	v_lshl_add_u64 v[6:7], v[6:7], 0, s[10:11]
	s_add_i32 m0, s15, 0x1a000
	s_add_i32 s51, s15, 0x8000
	s_add_i32 s52, s15, 0xa000
	global_load_lds_dwordx4 v[6:7], off
	v_lshl_add_u64 v[6:7], v[8:9], 0, s[10:11]
	s_mov_b32 m0, s51
	s_add_u32 s18, s34, 0x80080
	global_load_lds_dwordx4 v[6:7], off
	v_lshl_add_u64 v[4:5], v[4:5], 0, s[10:11]
	s_mov_b32 m0, s52
	s_addc_u32 s19, s35, 0
	global_load_lds_dwordx4 v[4:5], off
	s_add_i32 m0, s15, 0x1c000
	v_lshl_add_u64 v[4:5], s[18:19], 0, v[132:133]
	global_load_lds_dwordx4 v[4:5], off
	v_lshl_add_u64 v[4:5], s[18:19], 0, v[136:137]
	s_add_i32 m0, s15, 0x1e000
	v_lshlrev_b32_e32 v3, 1, v15
	global_load_lds_dwordx4 v[4:5], off
	v_lshl_or_b32 v1, s7, 6, v205
	v_lshl_or_b32 v4, v205, 6, v3
	v_and_b32_e32 v5, 32, v196
	s_movk_i32 s7, 0x3c0
	v_readlane_b32 s18, v249, 0
	v_bitop3_b32 v4, v4, s13, v5 bitop3:0xde
	v_and_or_b32 v3, v209, s7, v3
	s_ashr_i32 s13, s18, 31
	v_bitop3_b32 v144, s17, v3, v5 bitop3:0xf6
	s_lshr_b32 s13, s13, 26
	v_mov_b32_e32 v3, v133
	s_add_i32 s13, s18, s13
	v_lshl_add_u64 v[138:139], s[72:73], 0, v[2:3]
	v_lshlrev_b32_e32 v2, 9, v0
	s_and_b32 s17, s13, 0xffffffc0
	v_and_b32_e32 v2, 0x30000, v2
	v_lshlrev_b32_e32 v3, 12, v14
	s_sub_i32 s58, s18, s17
	s_ashr_i32 s13, s13, 6
	v_or3_b32 v2, v12, v2, v3
	s_addk_i32 s58, 0x200
	s_lshl_b32 s59, s13, 3
	v_add_u32_e32 v140, v2, v13
	v_lshlrev_b32_e32 v2, 5, v16
	s_waitcnt vmcnt(6)
	s_cmpk_lt_u32 s16, 0x100
	v_and_b32_e32 v2, 0x70000, v2
	s_mov_b32 s7, 0
	s_cselect_b64 s[16:17], -1, 0
	v_or3_b32 v2, v12, v2, v3
	s_add_i32 s60, 0, 0x10000
	s_add_i32 s61, 0, 0x14000
	s_mov_b32 s53, 0x18000
	s_mov_b32 s54, 0x1a000
	s_mov_b32 s55, 0x8000
	s_mov_b32 s56, 0xa000
	s_mov_b32 s57, 0x1c000
	v_or_b32_e32 v145, s20, v15
	v_mov_b32_e32 v141, v133
	v_add_u32_e32 v142, v2, v13
	v_mov_b32_e32 v143, v133
	v_add_u32_e32 v146, s60, v144
	v_add_u32_e32 v147, s61, v144
	v_add_u32_e32 v148, 0, v4
	s_mov_b32 s62, 0xc000
	s_mov_b32 s63, 0xe000
	s_movk_i32 s64, 0x1800
	s_mov_b32 s13, s7
	s_barrier
	ds_read_b128 v[150:153], v146
	ds_read_b128 v[154:157], v146 offset:1024
	ds_read_b128 v[158:161], v146 offset:2048
	ds_read_b128 v[162:165], v146 offset:3072
	ds_read_b128 v[166:169], v147
	ds_read_b128 v[170:173], v147 offset:1024
	ds_read_b128 v[174:177], v147 offset:2048
	ds_read_b128 v[178:181], v147 offset:3072
	ds_read_b128 v[182:185], v148
	ds_read_b128 v[186:189], v148 offset:1024
	ds_read_b128 v[190:193], v148 offset:2048
	ds_read_b128 v[198:201], v148 offset:3072
	ds_read_b128 v[210:213], v148 offset:4096
	ds_read_b128 v[214:217], v148 offset:5120
	ds_read_b128 v[218:221], v148 offset:6144
	ds_read_b128 v[222:225], v148 offset:7168
	s_branch .LBB0_1963

.Lpeel_3:
	s_add_i32 s29, s23, 2
	s_add_u32 s34, s30, 0xfff80080
	s_addc_u32 s35, s31, -1
	s_cmp_eq_u32 s28, s23
	s_cselect_b32 s37, s25, s35
	s_cselect_b32 s36, s24, s34
	s_cselect_b32 s35, s27, s21
	s_cselect_b32 s34, s26, s19
	v_lshl_add_u64 v[202:203], s[30:31], 0, v[140:141]
	s_add_i32 m0, s15, 0xc000
	global_load_lds_dwordx4 v[202:203], off
	v_lshl_add_u64 v[202:203], s[30:31], 0, v[142:143]
	s_add_i32 m0, s15, 0xe000
	s_nop 0
	global_load_lds_dwordx4 v[202:203], off
	s_waitcnt vmcnt(8)
	s_waitcnt lgkmcnt(0)
	s_barrier
	s_setprio 1
	s_waitcnt lgkmcnt(0)
	v_mfma_f32_16x16x32_bf16 v[126:129], v[150:153], v[182:185], 0
	v_mfma_f32_16x16x32_bf16 v[122:125], v[158:161], v[182:185], 0
	v_mfma_f32_16x16x32_bf16 v[118:121], v[150:153], v[190:193], 0
	v_mfma_f32_16x16x32_bf16 v[114:117], v[158:161], v[190:193], 0
	v_mfma_f32_16x16x32_bf16 v[110:113], v[150:153], v[210:213], 0
	v_mfma_f32_16x16x32_bf16 v[106:109], v[158:161], v[210:213], 0
	v_mfma_f32_16x16x32_bf16 v[102:105], v[150:153], v[218:221], 0
	v_mfma_f32_16x16x32_bf16 v[98:101], v[158:161], v[218:221], 0
	v_mfma_f32_16x16x32_bf16 v[126:129], v[154:157], v[186:189], v[126:129]
	v_mfma_f32_16x16x32_bf16 v[122:125], v[162:165], v[186:189], v[122:125]
	v_mfma_f32_16x16x32_bf16 v[118:121], v[154:157], v[198:201], v[118:121]
	v_mfma_f32_16x16x32_bf16 v[114:117], v[162:165], v[198:201], v[114:117]
	v_mfma_f32_16x16x32_bf16 v[110:113], v[154:157], v[214:217], v[110:113]
	v_mfma_f32_16x16x32_bf16 v[106:109], v[162:165], v[214:217], v[106:109]
	v_mfma_f32_16x16x32_bf16 v[102:105], v[154:157], v[222:225], v[102:105]
	v_mfma_f32_16x16x32_bf16 v[98:101], v[162:165], v[222:225], v[98:101]
	s_setprio 0
	s_setprio 1
	v_mfma_f32_16x16x32_bf16 v[94:97], v[166:169], v[182:185], 0
	v_mfma_f32_16x16x32_bf16 v[90:93], v[174:177], v[182:185], 0
	v_mfma_f32_16x16x32_bf16 v[86:89], v[166:169], v[190:193], 0
	v_mfma_f32_16x16x32_bf16 v[82:85], v[174:177], v[190:193], 0
	v_mfma_f32_16x16x32_bf16 v[78:81], v[166:169], v[210:213], 0
	v_mfma_f32_16x16x32_bf16 v[74:77], v[174:177], v[210:213], 0
	v_mfma_f32_16x16x32_bf16 v[70:73], v[166:169], v[218:221], 0
	v_mfma_f32_16x16x32_bf16 v[66:69], v[174:177], v[218:221], 0
	v_mfma_f32_16x16x32_bf16 v[94:97], v[170:173], v[186:189], v[94:97]
	v_mfma_f32_16x16x32_bf16 v[90:93], v[178:181], v[186:189], v[90:93]
	v_mfma_f32_16x16x32_bf16 v[86:89], v[170:173], v[198:201], v[86:89]
	v_mfma_f32_16x16x32_bf16 v[82:85], v[178:181], v[198:201], v[82:85]
	v_mfma_f32_16x16x32_bf16 v[78:81], v[170:173], v[214:217], v[78:81]
	v_mfma_f32_16x16x32_bf16 v[74:77], v[178:181], v[214:217], v[74:77]
	v_mfma_f32_16x16x32_bf16 v[70:73], v[170:173], v[222:225], v[70:73]
	v_mfma_f32_16x16x32_bf16 v[66:69], v[178:181], v[222:225], v[66:69]
	s_setprio 0
	s_barrier
	s_add_i32 s23, s60, s33
	v_lshl_add_u64 v[202:203], s[34:35], 0, v[132:133]
	s_mov_b32 m0, s23
	ds_read_b128 v[182:185], v148 offset:16384
	ds_read_b128 v[186:189], v148 offset:17408
	ds_read_b128 v[190:193], v148 offset:18432
	ds_read_b128 v[198:201], v148 offset:19456
	ds_read_b128 v[210:213], v148 offset:20480
	ds_read_b128 v[214:217], v148 offset:21504
	ds_read_b128 v[218:221], v148 offset:22528
	ds_read_b128 v[222:225], v148 offset:23552
	global_load_lds_dwordx4 v[202:203], off
	s_add_i32 m0, s23, 0x2000
	s_add_u32 s38, s34, 0x80000
	v_lshl_add_u64 v[206:207], s[34:35], 0, v[136:137]
	s_addc_u32 s39, s35, 0
	s_add_i32 s23, s61, s33
	global_load_lds_dwordx4 v[206:207], off
	v_lshl_add_u64 v[226:227], s[38:39], 0, v[132:133]
	s_mov_b32 m0, s23
	v_lshl_add_u64 v[228:229], s[36:37], 0, v[134:135]
	global_load_lds_dwordx4 v[226:227], off
	v_lshl_add_u64 v[226:227], s[38:39], 0, v[136:137]
	s_add_i32 m0, s23, 0x2000
	s_nop 0
	global_load_lds_dwordx4 v[226:227], off
	v_lshl_add_u64 v[226:227], s[36:37], 0, v[130:131]
	s_mov_b32 m0, s15
	s_nop 0
	global_load_lds_dwordx4 v[226:227], off
	s_mov_b32 m0, s41
	s_nop 0
	global_load_lds_dwordx4 v[228:229], off
	s_waitcnt vmcnt(8)
	s_waitcnt lgkmcnt(0)
	s_barrier
	s_setprio 1
	s_waitcnt lgkmcnt(0)
	v_mfma_f32_16x16x32_bf16 v[62:65], v[150:153], v[182:185], 0
	v_mfma_f32_16x16x32_bf16 v[58:61], v[158:161], v[182:185], 0
	v_mfma_f32_16x16x32_bf16 v[54:57], v[150:153], v[190:193], 0
	v_mfma_f32_16x16x32_bf16 v[50:53], v[158:161], v[190:193], 0
	v_mfma_f32_16x16x32_bf16 v[46:49], v[150:153], v[210:213], 0
	v_mfma_f32_16x16x32_bf16 v[42:45], v[158:161], v[210:213], 0
	v_mfma_f32_16x16x32_bf16 v[38:41], v[150:153], v[218:221], 0
	v_mfma_f32_16x16x32_bf16 v[34:37], v[158:161], v[218:221], 0
	v_mfma_f32_16x16x32_bf16 v[62:65], v[154:157], v[186:189], v[62:65]
	v_mfma_f32_16x16x32_bf16 v[58:61], v[162:165], v[186:189], v[58:61]
	v_mfma_f32_16x16x32_bf16 v[54:57], v[154:157], v[198:201], v[54:57]
	v_mfma_f32_16x16x32_bf16 v[50:53], v[162:165], v[198:201], v[50:53]
	v_mfma_f32_16x16x32_bf16 v[46:49], v[154:157], v[214:217], v[46:49]
	v_mfma_f32_16x16x32_bf16 v[42:45], v[162:165], v[214:217], v[42:45]
	v_mfma_f32_16x16x32_bf16 v[38:41], v[154:157], v[222:225], v[38:41]
	v_mfma_f32_16x16x32_bf16 v[34:37], v[162:165], v[222:225], v[34:37]
	s_setprio 0
	s_setprio 1
	v_mfma_f32_16x16x32_bf16 v[30:33], v[166:169], v[182:185], 0
	v_mfma_f32_16x16x32_bf16 v[26:29], v[174:177], v[182:185], 0
	v_mfma_f32_16x16x32_bf16 v[22:25], v[166:169], v[190:193], 0
	v_mfma_f32_16x16x32_bf16 v[18:21], v[174:177], v[190:193], 0
	v_mfma_f32_16x16x32_bf16 v[14:17], v[166:169], v[210:213], 0
	v_mfma_f32_16x16x32_bf16 v[10:13], v[174:177], v[210:213], 0
	v_mfma_f32_16x16x32_bf16 v[6:9], v[166:169], v[218:221], 0
	v_mfma_f32_16x16x32_bf16 v[2:5], v[174:177], v[218:221], 0
	v_mfma_f32_16x16x32_bf16 v[30:33], v[170:173], v[186:189], v[30:33]
	v_mfma_f32_16x16x32_bf16 v[26:29], v[178:181], v[186:189], v[26:29]
	v_mfma_f32_16x16x32_bf16 v[22:25], v[170:173], v[198:201], v[22:25]
	v_mfma_f32_16x16x32_bf16 v[18:21], v[178:181], v[198:201], v[18:21]
	v_mfma_f32_16x16x32_bf16 v[14:17], v[170:173], v[214:217], v[14:17]
	v_mfma_f32_16x16x32_bf16 v[10:13], v[178:181], v[214:217], v[10:13]
	v_mfma_f32_16x16x32_bf16 v[6:9], v[170:173], v[222:225], v[6:9]
	v_mfma_f32_16x16x32_bf16 v[2:5], v[178:181], v[222:225], v[2:5]
	s_setprio 0
	s_barrier
	s_add_i32 s23, 0, 0x18000
	v_add_u32_e32 v149, s23, v144
	s_add_i32 s38, 0, 0x1c000
	ds_read_b128 v[150:153], v149
	ds_read_b128 v[154:157], v149 offset:1024
	ds_read_b128 v[158:161], v149 offset:2048
	ds_read_b128 v[162:165], v149 offset:3072
	v_add_u32_e32 v149, s38, v144
	ds_read_b128 v[166:169], v149
	ds_read_b128 v[170:173], v149 offset:1024
	ds_read_b128 v[174:177], v149 offset:2048
	ds_read_b128 v[178:181], v149 offset:3072
	s_add_u32 s36, s36, 0x80000
	s_addc_u32 s37, s37, 0
	s_mov_b32 m0, s42
	v_lshl_add_u64 v[230:231], s[36:37], 0, v[130:131]
	ds_read_b128 v[182:185], v148 offset:32768
	ds_read_b128 v[186:189], v148 offset:33792
	ds_read_b128 v[190:193], v148 offset:34816
	ds_read_b128 v[198:201], v148 offset:35840
	ds_read_b128 v[210:213], v148 offset:36864
	ds_read_b128 v[214:217], v148 offset:37888
	ds_read_b128 v[218:221], v148 offset:38912
	ds_read_b128 v[222:225], v148 offset:39936
	global_load_lds_dwordx4 v[230:231], off
	v_lshl_add_u64 v[230:231], s[36:37], 0, v[134:135]
	s_mov_b32 m0, s43
	s_nop 0
	global_load_lds_dwordx4 v[230:231], off
	s_waitcnt vmcnt(8)
	s_waitcnt lgkmcnt(0)
	s_barrier
	s_setprio 1
	s_waitcnt lgkmcnt(0)
	v_mfma_f32_16x16x32_bf16 v[126:129], v[150:153], v[182:185], v[126:129]
	v_mfma_f32_16x16x32_bf16 v[122:125], v[158:161], v[182:185], v[122:125]
	v_mfma_f32_16x16x32_bf16 v[118:121], v[150:153], v[190:193], v[118:121]
	v_mfma_f32_16x16x32_bf16 v[114:117], v[158:161], v[190:193], v[114:117]
	v_mfma_f32_16x16x32_bf16 v[110:113], v[150:153], v[210:213], v[110:113]
	v_mfma_f32_16x16x32_bf16 v[106:109], v[158:161], v[210:213], v[106:109]
	v_mfma_f32_16x16x32_bf16 v[102:105], v[150:153], v[218:221], v[102:105]
	v_mfma_f32_16x16x32_bf16 v[98:101], v[158:161], v[218:221], v[98:101]
	v_mfma_f32_16x16x32_bf16 v[126:129], v[154:157], v[186:189], v[126:129]
	v_mfma_f32_16x16x32_bf16 v[122:125], v[162:165], v[186:189], v[122:125]
	v_mfma_f32_16x16x32_bf16 v[118:121], v[154:157], v[198:201], v[118:121]
	v_mfma_f32_16x16x32_bf16 v[114:117], v[162:165], v[198:201], v[114:117]
	v_mfma_f32_16x16x32_bf16 v[110:113], v[154:157], v[214:217], v[110:113]
	v_mfma_f32_16x16x32_bf16 v[106:109], v[162:165], v[214:217], v[106:109]
	v_mfma_f32_16x16x32_bf16 v[102:105], v[154:157], v[222:225], v[102:105]
	v_mfma_f32_16x16x32_bf16 v[98:101], v[162:165], v[222:225], v[98:101]
	s_setprio 0
	s_setprio 1
	v_mfma_f32_16x16x32_bf16 v[94:97], v[166:169], v[182:185], v[94:97]
	v_mfma_f32_16x16x32_bf16 v[90:93], v[174:177], v[182:185], v[90:93]
	v_mfma_f32_16x16x32_bf16 v[86:89], v[166:169], v[190:193], v[86:89]
	v_mfma_f32_16x16x32_bf16 v[82:85], v[174:177], v[190:193], v[82:85]
	v_mfma_f32_16x16x32_bf16 v[78:81], v[166:169], v[210:213], v[78:81]
	v_mfma_f32_16x16x32_bf16 v[74:77], v[174:177], v[210:213], v[74:77]
	v_mfma_f32_16x16x32_bf16 v[70:73], v[166:169], v[218:221], v[70:73]
	v_mfma_f32_16x16x32_bf16 v[66:69], v[174:177], v[218:221], v[66:69]
	v_mfma_f32_16x16x32_bf16 v[94:97], v[170:173], v[186:189], v[94:97]
	v_mfma_f32_16x16x32_bf16 v[90:93], v[178:181], v[186:189], v[90:93]
	v_mfma_f32_16x16x32_bf16 v[86:89], v[170:173], v[198:201], v[86:89]
	v_mfma_f32_16x16x32_bf16 v[82:85], v[178:181], v[198:201], v[82:85]
	v_mfma_f32_16x16x32_bf16 v[78:81], v[170:173], v[214:217], v[78:81]
	v_mfma_f32_16x16x32_bf16 v[74:77], v[178:181], v[214:217], v[74:77]
	v_mfma_f32_16x16x32_bf16 v[70:73], v[170:173], v[222:225], v[70:73]
	v_mfma_f32_16x16x32_bf16 v[66:69], v[178:181], v[222:225], v[66:69]
	s_setprio 0
	s_barrier
	s_add_i32 s23, s23, s33
	v_lshl_add_u64 v[202:203], v[202:203], 0, s[10:11]
	s_mov_b32 m0, s23
	ds_read_b128 v[182:185], v148 offset:49152
	ds_read_b128 v[186:189], v148 offset:50176
	ds_read_b128 v[190:193], v148 offset:51200
	ds_read_b128 v[198:201], v148 offset:52224
	ds_read_b128 v[210:213], v148 offset:53248
	ds_read_b128 v[214:217], v148 offset:54272
	ds_read_b128 v[218:221], v148 offset:55296
	ds_read_b128 v[222:225], v148 offset:56320
	global_load_lds_dwordx4 v[202:203], off
	s_add_i32 m0, s23, 0x2000
	s_add_u32 s34, s34, 0x80080
	v_lshl_add_u64 v[202:203], v[206:207], 0, s[10:11]
	s_addc_u32 s35, s35, 0
	s_add_i32 s23, s38, s33
	global_load_lds_dwordx4 v[202:203], off
	v_lshl_add_u64 v[202:203], s[34:35], 0, v[132:133]
	s_mov_b32 m0, s23
	s_nop 0
	global_load_lds_dwordx4 v[202:203], off
	v_lshl_add_u64 v[202:203], s[34:35], 0, v[136:137]
	s_add_i32 m0, s23, 0x2000
	s_nop 0
	global_load_lds_dwordx4 v[202:203], off
	v_lshl_add_u64 v[202:203], v[226:227], 0, s[10:11]
	s_mov_b32 m0, s51
	s_nop 0
	global_load_lds_dwordx4 v[202:203], off
	v_lshl_add_u64 v[202:203], v[228:229], 0, s[10:11]
	s_mov_b32 m0, s52
	s_nop 0
	global_load_lds_dwordx4 v[202:203], off
	s_waitcnt vmcnt(8)
	s_waitcnt lgkmcnt(0)
	s_barrier
	s_setprio 1
	s_waitcnt lgkmcnt(0)
	v_mfma_f32_16x16x32_bf16 v[62:65], v[150:153], v[182:185], v[62:65]
	v_mfma_f32_16x16x32_bf16 v[58:61], v[158:161], v[182:185], v[58:61]
	v_mfma_f32_16x16x32_bf16 v[54:57], v[150:153], v[190:193], v[54:57]
	v_mfma_f32_16x16x32_bf16 v[50:53], v[158:161], v[190:193], v[50:53]
	v_mfma_f32_16x16x32_bf16 v[46:49], v[150:153], v[210:213], v[46:49]
	v_mfma_f32_16x16x32_bf16 v[42:45], v[158:161], v[210:213], v[42:45]
	v_mfma_f32_16x16x32_bf16 v[38:41], v[150:153], v[218:221], v[38:41]
	v_mfma_f32_16x16x32_bf16 v[34:37], v[158:161], v[218:221], v[34:37]
	v_mfma_f32_16x16x32_bf16 v[62:65], v[154:157], v[186:189], v[62:65]
	v_mfma_f32_16x16x32_bf16 v[58:61], v[162:165], v[186:189], v[58:61]
	v_mfma_f32_16x16x32_bf16 v[54:57], v[154:157], v[198:201], v[54:57]
	v_mfma_f32_16x16x32_bf16 v[50:53], v[162:165], v[198:201], v[50:53]
	v_mfma_f32_16x16x32_bf16 v[46:49], v[154:157], v[214:217], v[46:49]
	v_mfma_f32_16x16x32_bf16 v[42:45], v[162:165], v[214:217], v[42:45]
	v_mfma_f32_16x16x32_bf16 v[38:41], v[154:157], v[222:225], v[38:41]
	v_mfma_f32_16x16x32_bf16 v[34:37], v[162:165], v[222:225], v[34:37]
	s_setprio 0
	s_setprio 1
	v_mfma_f32_16x16x32_bf16 v[30:33], v[166:169], v[182:185], v[30:33]
	v_mfma_f32_16x16x32_bf16 v[26:29], v[174:177], v[182:185], v[26:29]
	v_mfma_f32_16x16x32_bf16 v[22:25], v[166:169], v[190:193], v[22:25]
	v_mfma_f32_16x16x32_bf16 v[18:21], v[174:177], v[190:193], v[18:21]
	v_mfma_f32_16x16x32_bf16 v[14:17], v[166:169], v[210:213], v[14:17]
	v_mfma_f32_16x16x32_bf16 v[10:13], v[174:177], v[210:213], v[10:13]
	v_mfma_f32_16x16x32_bf16 v[6:9], v[166:169], v[218:221], v[6:9]
	v_mfma_f32_16x16x32_bf16 v[2:5], v[174:177], v[218:221], v[2:5]
	v_mfma_f32_16x16x32_bf16 v[30:33], v[170:173], v[186:189], v[30:33]
	v_mfma_f32_16x16x32_bf16 v[26:29], v[178:181], v[186:189], v[26:29]
	v_mfma_f32_16x16x32_bf16 v[22:25], v[170:173], v[198:201], v[22:25]
	v_mfma_f32_16x16x32_bf16 v[18:21], v[178:181], v[198:201], v[18:21]
	v_mfma_f32_16x16x32_bf16 v[14:17], v[170:173], v[214:217], v[14:17]
	v_mfma_f32_16x16x32_bf16 v[10:13], v[178:181], v[214:217], v[10:13]
	v_mfma_f32_16x16x32_bf16 v[6:9], v[170:173], v[222:225], v[6:9]
	v_mfma_f32_16x16x32_bf16 v[2:5], v[178:181], v[222:225], v[2:5]
	s_setprio 0
	s_barrier
	s_add_u32 s30, s30, 0x100
	s_addc_u32 s31, s31, 0
	s_add_u32 s19, s19, 0x100
	s_addc_u32 s21, s21, 0
	s_cmp_ge_i32 s29, s68
	s_mov_b32 s23, s29
	s_cbranch_scc0 .LBB0_1973
	s_branch .Lpeeldone_3

.Lpeeldone_3:
	ds_read_b128 v[150:153], v146
	ds_read_b128 v[154:157], v146 offset:1024
	ds_read_b128 v[158:161], v146 offset:2048
	ds_read_b128 v[162:165], v146 offset:3072
	ds_read_b128 v[166:169], v147
	ds_read_b128 v[170:173], v147 offset:1024
	ds_read_b128 v[174:177], v147 offset:2048
	ds_read_b128 v[178:181], v147 offset:3072
	ds_read_b128 v[182:185], v148
	ds_read_b128 v[186:189], v148 offset:1024
	ds_read_b128 v[190:193], v148 offset:2048
	ds_read_b128 v[198:201], v148 offset:3072
	ds_read_b128 v[210:213], v148 offset:4096
	ds_read_b128 v[214:217], v148 offset:5120
	ds_read_b128 v[218:221], v148 offset:6144
	ds_read_b128 v[222:225], v148 offset:7168
	s_and_b64 vcc, exec, s[16:17]
	s_cbranch_vccz .LBB0_1976
	s_barrier

.LBB0_2343:
	s_add_u32 s10, s82, 0x27100000
	s_addc_u32 s11, s83, 0
	s_add_u32 s51, s82, 0x2ac000
	s_addc_u32 s52, s83, 0
	s_lshl_b32 s0, s12, 5
	s_mov_b64 s[12:13], 0x80
	s_and_b32 s17, s0, 0x60
	s_add_i32 m0, s27, 0x18000
	v_lshl_add_u64 v[10:11], v[10:11], 0, s[12:13]
	s_lshl_b32 s15, s7, 13
	s_lshl_b32 s18, s17, 7
	s_waitcnt vmcnt(2)
	s_barrier
	global_load_lds_dwordx4 v[10:11], off
	v_lshl_add_u64 v[6:7], v[6:7], 0, s[12:13]
	s_add_i32 m0, s27, 0x1a000
	s_add_i32 s53, s27, 0x8000
	s_add_i32 s54, s27, 0xa000
	global_load_lds_dwordx4 v[6:7], off
	v_lshl_add_u64 v[6:7], v[8:9], 0, s[12:13]
	s_mov_b32 m0, s53
	s_add_u32 s0, s36, 0x80080
	global_load_lds_dwordx4 v[6:7], off
	v_lshl_add_u64 v[4:5], v[4:5], 0, s[12:13]
	s_mov_b32 m0, s54
	s_addc_u32 s1, s37, 0
	global_load_lds_dwordx4 v[4:5], off
	s_add_i32 m0, s27, 0x1c000
	v_lshl_add_u64 v[4:5], s[0:1], 0, v[148:149]
	global_load_lds_dwordx4 v[4:5], off
	v_lshl_add_u64 v[4:5], s[0:1], 0, v[152:153]
	s_add_i32 m0, s27, 0x1e000
	v_lshlrev_b32_e32 v3, 1, v15
	global_load_lds_dwordx4 v[4:5], off
	v_lshl_or_b32 v4, v205, 6, v3
	v_and_b32_e32 v5, 32, v196
	v_bitop3_b32 v4, v4, s15, v5 bitop3:0xde
	s_movk_i32 s0, 0x3c0
	v_readlane_b32 s15, v249, 0
	v_and_or_b32 v3, v209, s0, v3
	s_ashr_i32 s0, s15, 31
	v_bitop3_b32 v168, s18, v3, v5 bitop3:0xf6
	s_lshr_b32 s0, s0, 25
	v_mov_b32_e32 v3, v149
	s_add_i32 s0, s15, s0
	v_lshl_add_u64 v[154:155], s[78:79], 0, v[2:3]
	v_lshlrev_b32_e32 v2, 9, v0
	s_and_b32 s1, s0, 0xffffff80
	v_and_b32_e32 v2, 0x30000, v2
	v_lshlrev_b32_e32 v3, 12, v14
	s_sub_i32 s60, s15, s1
	s_ashr_i32 s0, s0, 7
	v_or3_b32 v2, v12, v2, v3
	s_addk_i32 s60, 0x100
	s_lshl_b32 s61, s0, 4
	v_add_u32_e32 v156, v2, v13
	v_lshlrev_b32_e32 v2, 5, v16
	s_waitcnt vmcnt(6)
	s_cmpk_lt_u32 s14, 0x100
	v_and_b32_e32 v2, 0x70000, v2
	v_lshl_or_b32 v1, s7, 6, v205
	s_mov_b32 s7, 0
	s_cselect_b64 s[14:15], -1, 0
	s_lshr_b32 s0, s16, 2
	v_or3_b32 v2, v12, v2, v3
	s_add_i32 s63, 0, 0x10000
	s_add_i32 s64, 0, 0x14000
	s_mov_b32 s55, 0x18000
	s_mov_b32 s56, 0x1a000
	s_mov_b32 s57, 0x8000
	s_mov_b32 s58, 0xa000
	s_mov_b32 s59, 0x1c000
	s_xor_b32 s62, s0, 1
	v_or_b32_e32 v169, s17, v15
	v_mov_b32_e32 v157, v149
	v_add_u32_e32 v158, v2, v13
	v_mov_b32_e32 v159, v149
	s_mov_b64 s[30:31], -1
	v_add_u32_e32 v170, s63, v168
	v_add_u32_e32 v171, s64, v168
	v_add_u32_e32 v172, 0, v4
	s_mov_b32 s65, 0xc000
	s_mov_b32 s66, 0xe000
	s_mov_b32 s17, s7
	s_barrier
	ds_read_b128 v[218:221], v172 offset:6144
	ds_read_b128 v[222:225], v172 offset:7168
	s_branch .LBB0_2346

.LBB0_2534:
	s_lshl_b32 s10, s10, 5
	s_and_b32 s16, s10, 0x60
	s_mov_b64 s[10:11], 0x80
	s_add_i32 m0, s27, 0x18000
	v_lshl_add_u64 v[10:11], v[10:11], 0, s[10:11]
	s_lshl_b32 s13, s7, 13
	s_lshl_b32 s17, s16, 7
	s_waitcnt vmcnt(2)
	s_barrier
	global_load_lds_dwordx4 v[10:11], off
	v_lshl_add_u64 v[6:7], v[6:7], 0, s[10:11]
	s_add_i32 m0, s27, 0x1a000
	s_add_i32 s51, s27, 0x8000
	s_add_i32 s52, s27, 0xa000
	global_load_lds_dwordx4 v[6:7], off
	v_lshl_add_u64 v[6:7], v[8:9], 0, s[10:11]
	s_mov_b32 m0, s51
	s_add_u32 s14, s34, 0x80080
	global_load_lds_dwordx4 v[6:7], off
	v_lshl_add_u64 v[4:5], v[4:5], 0, s[10:11]
	s_mov_b32 m0, s52
	s_addc_u32 s15, s35, 0
	global_load_lds_dwordx4 v[4:5], off
	s_add_i32 m0, s27, 0x1c000
	v_lshl_add_u64 v[4:5], s[14:15], 0, v[132:133]
	global_load_lds_dwordx4 v[4:5], off
	v_lshl_add_u64 v[4:5], s[14:15], 0, v[136:137]
	s_add_i32 m0, s27, 0x1e000
	v_lshlrev_b32_e32 v3, 1, v15
	global_load_lds_dwordx4 v[4:5], off
	v_lshl_or_b32 v1, s7, 6, v205
	v_lshl_or_b32 v4, v205, 6, v3
	v_and_b32_e32 v5, 32, v196
	s_movk_i32 s7, 0x3c0
	v_readlane_b32 s15, v249, 0
	v_bitop3_b32 v4, v4, s13, v5 bitop3:0xde
	v_and_or_b32 v3, v209, s7, v3
	s_ashr_i32 s13, s15, 31
	v_bitop3_b32 v146, s17, v3, v5 bitop3:0xf6
	s_lshr_b32 s13, s13, 26
	v_mov_b32_e32 v3, v133
	s_add_i32 s13, s15, s13
	v_lshl_add_u64 v[138:139], s[78:79], 0, v[2:3]
	v_lshlrev_b32_e32 v2, 9, v0
	s_ashr_i32 s14, s13, 6
	s_andn2_b32 s13, s13, 63
	v_and_b32_e32 v2, 0x30000, v2
	v_lshlrev_b32_e32 v3, 12, v14
	s_sub_i32 s58, s15, s13
	v_or3_b32 v2, v12, v2, v3
	s_addk_i32 s58, 0x800
	s_lshl_b32 s59, s14, 3
	v_add_u32_e32 v140, v2, v13
	v_lshlrev_b32_e32 v2, 5, v16
	s_waitcnt vmcnt(6)
	s_cmpk_lt_u32 s12, 0x100
	v_and_b32_e32 v2, 0x70000, v2
	s_mov_b32 s7, 0
	s_cselect_b64 s[12:13], -1, 0
	v_or3_b32 v2, v12, v2, v3
	s_add_i32 s60, 0, 0x10000
	s_add_i32 s61, 0, 0x14000
	s_mov_b32 s53, 0x18000
	s_mov_b32 s54, 0x1a000
	s_mov_b32 s55, 0x8000
	s_mov_b32 s56, 0xa000
	s_mov_b32 s57, 0x1c000
	v_or_b32_e32 v147, s16, v15
	v_mov_b32_e32 v141, v133
	v_add_u32_e32 v142, v2, v13
	v_mov_b32_e32 v143, v133
	v_add_u32_e32 v148, s60, v146
	v_add_u32_e32 v149, s61, v146
	v_add_u32_e32 v150, 0, v4
	s_mov_b32 s62, 0xc000
	s_mov_b32 s63, 0xe000
	s_movk_i32 s64, 0x2c00
	s_mov_b32 s25, s7
	s_barrier
	ds_read_b128 v[160:163], v148 offset:2048
	ds_read_b128 v[164:167], v148 offset:3072
	ds_read_b128 v[168:171], v149
	ds_read_b128 v[172:175], v149 offset:1024
	ds_read_b128 v[176:179], v149 offset:2048
	ds_read_b128 v[180:183], v149 offset:3072
	ds_read_b128 v[184:187], v150
	ds_read_b128 v[188:191], v150 offset:1024
	ds_read_b128 v[192:195], v150 offset:2048
	ds_read_b128 v[198:201], v150 offset:3072
	ds_read_b128 v[210:213], v150 offset:4096
	ds_read_b128 v[214:217], v150 offset:5120
	ds_read_b128 v[218:221], v150 offset:6144
	ds_read_b128 v[222:225], v150 offset:7168
	s_branch .LBB0_2537

.Lpeel_1:
	ds_read_b128 v[152:155], v148
	ds_read_b128 v[156:159], v148 offset:1024
	s_add_i32 s29, s19, 2
	s_add_u32 s34, s30, 0xfff80080
	s_addc_u32 s35, s31, -1
	s_cmp_eq_u32 s28, s19
	s_cselect_b32 s37, s21, s35
	s_cselect_b32 s36, s20, s34
	s_cselect_b32 s35, s23, s17
	s_cselect_b32 s34, s22, s15
	v_lshl_add_u64 v[144:145], s[30:31], 0, v[140:141]
	s_add_i32 m0, s27, 0xc000
	global_load_lds_dwordx4 v[144:145], off
	v_lshl_add_u64 v[144:145], s[30:31], 0, v[142:143]
	s_add_i32 m0, s27, 0xe000
	s_nop 0
	global_load_lds_dwordx4 v[144:145], off
	s_waitcnt vmcnt(8)
	s_waitcnt lgkmcnt(0)
	s_barrier
	s_setprio 1
	s_waitcnt lgkmcnt(0)
	v_mfma_f32_16x16x32_bf16 v[126:129], v[152:155], v[184:187], 0
	v_mfma_f32_16x16x32_bf16 v[122:125], v[160:163], v[184:187], 0
	v_mfma_f32_16x16x32_bf16 v[110:113], v[152:155], v[192:195], 0
	v_mfma_f32_16x16x32_bf16 v[106:109], v[160:163], v[192:195], 0
	v_mfma_f32_16x16x32_bf16 v[94:97], v[152:155], v[210:213], 0
	v_mfma_f32_16x16x32_bf16 v[90:93], v[160:163], v[210:213], 0
	v_mfma_f32_16x16x32_bf16 v[78:81], v[152:155], v[218:221], 0
	v_mfma_f32_16x16x32_bf16 v[74:77], v[160:163], v[218:221], 0
	v_mfma_f32_16x16x32_bf16 v[126:129], v[156:159], v[188:191], v[126:129]
	v_mfma_f32_16x16x32_bf16 v[122:125], v[164:167], v[188:191], v[122:125]
	v_mfma_f32_16x16x32_bf16 v[110:113], v[156:159], v[198:201], v[110:113]
	v_mfma_f32_16x16x32_bf16 v[106:109], v[164:167], v[198:201], v[106:109]
	v_mfma_f32_16x16x32_bf16 v[94:97], v[156:159], v[214:217], v[94:97]
	v_mfma_f32_16x16x32_bf16 v[90:93], v[164:167], v[214:217], v[90:93]
	v_mfma_f32_16x16x32_bf16 v[78:81], v[156:159], v[222:225], v[78:81]
	v_mfma_f32_16x16x32_bf16 v[74:77], v[164:167], v[222:225], v[74:77]
	s_setprio 0
	s_setprio 1
	v_mfma_f32_16x16x32_bf16 v[118:121], v[168:171], v[184:187], 0
	v_mfma_f32_16x16x32_bf16 v[114:117], v[176:179], v[184:187], 0
	v_mfma_f32_16x16x32_bf16 v[102:105], v[168:171], v[192:195], 0
	v_mfma_f32_16x16x32_bf16 v[98:101], v[176:179], v[192:195], 0
	v_mfma_f32_16x16x32_bf16 v[86:89], v[168:171], v[210:213], 0
	v_mfma_f32_16x16x32_bf16 v[82:85], v[176:179], v[210:213], 0
	v_mfma_f32_16x16x32_bf16 v[70:73], v[168:171], v[218:221], 0
	v_mfma_f32_16x16x32_bf16 v[66:69], v[176:179], v[218:221], 0
	v_mfma_f32_16x16x32_bf16 v[118:121], v[172:175], v[188:191], v[118:121]
	v_mfma_f32_16x16x32_bf16 v[114:117], v[180:183], v[188:191], v[114:117]
	v_mfma_f32_16x16x32_bf16 v[102:105], v[172:175], v[198:201], v[102:105]
	v_mfma_f32_16x16x32_bf16 v[98:101], v[180:183], v[198:201], v[98:101]
	v_mfma_f32_16x16x32_bf16 v[86:89], v[172:175], v[214:217], v[86:89]
	v_mfma_f32_16x16x32_bf16 v[82:85], v[180:183], v[214:217], v[82:85]
	v_mfma_f32_16x16x32_bf16 v[70:73], v[172:175], v[222:225], v[70:73]
	v_mfma_f32_16x16x32_bf16 v[66:69], v[180:183], v[222:225], v[66:69]
	s_setprio 0
	s_barrier
	s_add_i32 s19, s60, s33
	v_lshl_add_u64 v[144:145], s[34:35], 0, v[132:133]
	s_mov_b32 m0, s19
	ds_read_b128 v[184:187], v150 offset:16384
	ds_read_b128 v[188:191], v150 offset:17408
	ds_read_b128 v[192:195], v150 offset:18432
	ds_read_b128 v[198:201], v150 offset:19456
	ds_read_b128 v[210:213], v150 offset:20480
	ds_read_b128 v[214:217], v150 offset:21504
	ds_read_b128 v[218:221], v150 offset:22528
	ds_read_b128 v[222:225], v150 offset:23552
	global_load_lds_dwordx4 v[144:145], off
	s_add_i32 m0, s19, 0x2000
	s_add_u32 s38, s34, 0x80000
	v_lshl_add_u64 v[202:203], s[34:35], 0, v[136:137]
	s_addc_u32 s39, s35, 0
	s_add_i32 s19, s61, s33
	global_load_lds_dwordx4 v[202:203], off
	v_lshl_add_u64 v[206:207], s[38:39], 0, v[132:133]
	s_mov_b32 m0, s19
	v_lshl_add_u64 v[226:227], s[36:37], 0, v[134:135]
	global_load_lds_dwordx4 v[206:207], off
	v_lshl_add_u64 v[206:207], s[38:39], 0, v[136:137]
	s_add_i32 m0, s19, 0x2000
	s_nop 0
	global_load_lds_dwordx4 v[206:207], off
	v_lshl_add_u64 v[206:207], s[36:37], 0, v[130:131]
	s_mov_b32 m0, s27
	s_nop 0
	global_load_lds_dwordx4 v[206:207], off
	s_mov_b32 m0, s41
	s_nop 0
	global_load_lds_dwordx4 v[226:227], off
	s_waitcnt vmcnt(8)
	s_waitcnt lgkmcnt(0)
	s_barrier
	s_setprio 1
	s_waitcnt lgkmcnt(0)
	v_mfma_f32_16x16x32_bf16 v[62:65], v[152:155], v[184:187], 0
	v_mfma_f32_16x16x32_bf16 v[58:61], v[160:163], v[184:187], 0
	v_mfma_f32_16x16x32_bf16 v[46:49], v[152:155], v[192:195], 0
	v_mfma_f32_16x16x32_bf16 v[42:45], v[160:163], v[192:195], 0
	v_mfma_f32_16x16x32_bf16 v[30:33], v[152:155], v[210:213], 0
	v_mfma_f32_16x16x32_bf16 v[26:29], v[160:163], v[210:213], 0
	v_mfma_f32_16x16x32_bf16 v[14:17], v[152:155], v[218:221], 0
	v_mfma_f32_16x16x32_bf16 v[10:13], v[160:163], v[218:221], 0
	v_mfma_f32_16x16x32_bf16 v[62:65], v[156:159], v[188:191], v[62:65]
	v_mfma_f32_16x16x32_bf16 v[58:61], v[164:167], v[188:191], v[58:61]
	v_mfma_f32_16x16x32_bf16 v[46:49], v[156:159], v[198:201], v[46:49]
	v_mfma_f32_16x16x32_bf16 v[42:45], v[164:167], v[198:201], v[42:45]
	v_mfma_f32_16x16x32_bf16 v[30:33], v[156:159], v[214:217], v[30:33]
	v_mfma_f32_16x16x32_bf16 v[26:29], v[164:167], v[214:217], v[26:29]
	v_mfma_f32_16x16x32_bf16 v[14:17], v[156:159], v[222:225], v[14:17]
	v_mfma_f32_16x16x32_bf16 v[10:13], v[164:167], v[222:225], v[10:13]
	s_setprio 0
	s_setprio 1
	v_mfma_f32_16x16x32_bf16 v[54:57], v[168:171], v[184:187], 0
	v_mfma_f32_16x16x32_bf16 v[50:53], v[176:179], v[184:187], 0
	v_mfma_f32_16x16x32_bf16 v[38:41], v[168:171], v[192:195], 0
	v_mfma_f32_16x16x32_bf16 v[34:37], v[176:179], v[192:195], 0
	v_mfma_f32_16x16x32_bf16 v[22:25], v[168:171], v[210:213], 0
	v_mfma_f32_16x16x32_bf16 v[18:21], v[176:179], v[210:213], 0
	v_mfma_f32_16x16x32_bf16 v[6:9], v[168:171], v[218:221], 0
	v_mfma_f32_16x16x32_bf16 v[2:5], v[176:179], v[218:221], 0
	v_mfma_f32_16x16x32_bf16 v[54:57], v[172:175], v[188:191], v[54:57]
	v_mfma_f32_16x16x32_bf16 v[50:53], v[180:183], v[188:191], v[50:53]
	v_mfma_f32_16x16x32_bf16 v[38:41], v[172:175], v[198:201], v[38:41]
	v_mfma_f32_16x16x32_bf16 v[34:37], v[180:183], v[198:201], v[34:37]
	v_mfma_f32_16x16x32_bf16 v[22:25], v[172:175], v[214:217], v[22:25]
	v_mfma_f32_16x16x32_bf16 v[18:21], v[180:183], v[214:217], v[18:21]
	v_mfma_f32_16x16x32_bf16 v[6:9], v[172:175], v[222:225], v[6:9]
	v_mfma_f32_16x16x32_bf16 v[2:5], v[180:183], v[222:225], v[2:5]
	s_setprio 0
	s_barrier
	s_add_i32 s19, 0, 0x18000
	v_add_u32_e32 v151, s19, v146
	s_add_i32 s38, 0, 0x1c000
	ds_read_b128 v[152:155], v151
	ds_read_b128 v[156:159], v151 offset:1024
	ds_read_b128 v[160:163], v151 offset:2048
	ds_read_b128 v[164:167], v151 offset:3072
	v_add_u32_e32 v151, s38, v146
	ds_read_b128 v[168:171], v151
	ds_read_b128 v[172:175], v151 offset:1024
	ds_read_b128 v[176:179], v151 offset:2048
	ds_read_b128 v[180:183], v151 offset:3072
	s_add_u32 s36, s36, 0x80000
	s_addc_u32 s37, s37, 0
	s_mov_b32 m0, s42
	v_lshl_add_u64 v[228:229], s[36:37], 0, v[130:131]
	ds_read_b128 v[184:187], v150 offset:32768
	ds_read_b128 v[188:191], v150 offset:33792
	ds_read_b128 v[192:195], v150 offset:34816
	ds_read_b128 v[198:201], v150 offset:35840
	ds_read_b128 v[210:213], v150 offset:36864
	ds_read_b128 v[214:217], v150 offset:37888
	ds_read_b128 v[218:221], v150 offset:38912
	ds_read_b128 v[222:225], v150 offset:39936
	global_load_lds_dwordx4 v[228:229], off
	v_lshl_add_u64 v[228:229], s[36:37], 0, v[134:135]
	s_mov_b32 m0, s43
	s_nop 0
	global_load_lds_dwordx4 v[228:229], off
	s_waitcnt vmcnt(8)
	s_waitcnt lgkmcnt(0)
	s_barrier
	s_setprio 1
	s_waitcnt lgkmcnt(0)
	v_mfma_f32_16x16x32_bf16 v[126:129], v[152:155], v[184:187], v[126:129]
	v_mfma_f32_16x16x32_bf16 v[122:125], v[160:163], v[184:187], v[122:125]
	v_mfma_f32_16x16x32_bf16 v[110:113], v[152:155], v[192:195], v[110:113]
	v_mfma_f32_16x16x32_bf16 v[106:109], v[160:163], v[192:195], v[106:109]
	v_mfma_f32_16x16x32_bf16 v[94:97], v[152:155], v[210:213], v[94:97]
	v_mfma_f32_16x16x32_bf16 v[90:93], v[160:163], v[210:213], v[90:93]
	v_mfma_f32_16x16x32_bf16 v[78:81], v[152:155], v[218:221], v[78:81]
	v_mfma_f32_16x16x32_bf16 v[74:77], v[160:163], v[218:221], v[74:77]
	v_mfma_f32_16x16x32_bf16 v[126:129], v[156:159], v[188:191], v[126:129]
	v_mfma_f32_16x16x32_bf16 v[122:125], v[164:167], v[188:191], v[122:125]
	v_mfma_f32_16x16x32_bf16 v[110:113], v[156:159], v[198:201], v[110:113]
	v_mfma_f32_16x16x32_bf16 v[106:109], v[164:167], v[198:201], v[106:109]
	v_mfma_f32_16x16x32_bf16 v[94:97], v[156:159], v[214:217], v[94:97]
	v_mfma_f32_16x16x32_bf16 v[90:93], v[164:167], v[214:217], v[90:93]
	v_mfma_f32_16x16x32_bf16 v[78:81], v[156:159], v[222:225], v[78:81]
	v_mfma_f32_16x16x32_bf16 v[74:77], v[164:167], v[222:225], v[74:77]
	s_setprio 0
	s_setprio 1
	v_mfma_f32_16x16x32_bf16 v[118:121], v[168:171], v[184:187], v[118:121]
	v_mfma_f32_16x16x32_bf16 v[114:117], v[176:179], v[184:187], v[114:117]
	v_mfma_f32_16x16x32_bf16 v[102:105], v[168:171], v[192:195], v[102:105]
	v_mfma_f32_16x16x32_bf16 v[98:101], v[176:179], v[192:195], v[98:101]
	v_mfma_f32_16x16x32_bf16 v[86:89], v[168:171], v[210:213], v[86:89]
	v_mfma_f32_16x16x32_bf16 v[82:85], v[176:179], v[210:213], v[82:85]
	v_mfma_f32_16x16x32_bf16 v[70:73], v[168:171], v[218:221], v[70:73]
	v_mfma_f32_16x16x32_bf16 v[66:69], v[176:179], v[218:221], v[66:69]
	v_mfma_f32_16x16x32_bf16 v[118:121], v[172:175], v[188:191], v[118:121]
	v_mfma_f32_16x16x32_bf16 v[114:117], v[180:183], v[188:191], v[114:117]
	v_mfma_f32_16x16x32_bf16 v[102:105], v[172:175], v[198:201], v[102:105]
	v_mfma_f32_16x16x32_bf16 v[98:101], v[180:183], v[198:201], v[98:101]
	v_mfma_f32_16x16x32_bf16 v[86:89], v[172:175], v[214:217], v[86:89]
	v_mfma_f32_16x16x32_bf16 v[82:85], v[180:183], v[214:217], v[82:85]
	v_mfma_f32_16x16x32_bf16 v[70:73], v[172:175], v[222:225], v[70:73]
	v_mfma_f32_16x16x32_bf16 v[66:69], v[180:183], v[222:225], v[66:69]
	s_setprio 0
	s_barrier
	s_add_i32 s19, s19, s33
	v_lshl_add_u64 v[144:145], v[144:145], 0, s[10:11]
	s_mov_b32 m0, s19
	ds_read_b128 v[184:187], v150 offset:49152
	ds_read_b128 v[188:191], v150 offset:50176
	ds_read_b128 v[192:195], v150 offset:51200
	ds_read_b128 v[198:201], v150 offset:52224
	ds_read_b128 v[210:213], v150 offset:53248
	ds_read_b128 v[214:217], v150 offset:54272
	ds_read_b128 v[218:221], v150 offset:55296
	ds_read_b128 v[222:225], v150 offset:56320
	global_load_lds_dwordx4 v[144:145], off
	s_add_i32 m0, s19, 0x2000
	s_add_u32 s34, s34, 0x80080
	v_lshl_add_u64 v[144:145], v[202:203], 0, s[10:11]
	s_addc_u32 s35, s35, 0
	s_add_i32 s19, s38, s33
	global_load_lds_dwordx4 v[144:145], off
	v_lshl_add_u64 v[144:145], s[34:35], 0, v[132:133]
	s_mov_b32 m0, s19
	s_nop 0
	global_load_lds_dwordx4 v[144:145], off
	v_lshl_add_u64 v[144:145], s[34:35], 0, v[136:137]
	s_add_i32 m0, s19, 0x2000
	s_nop 0
	global_load_lds_dwordx4 v[144:145], off
	v_lshl_add_u64 v[144:145], v[206:207], 0, s[10:11]
	s_mov_b32 m0, s51
	s_nop 0
	global_load_lds_dwordx4 v[144:145], off
	v_lshl_add_u64 v[144:145], v[226:227], 0, s[10:11]
	s_mov_b32 m0, s52
	s_nop 0
	global_load_lds_dwordx4 v[144:145], off
	s_waitcnt vmcnt(8)
	s_waitcnt lgkmcnt(0)
	s_barrier
	s_setprio 1
	s_waitcnt lgkmcnt(0)
	v_mfma_f32_16x16x32_bf16 v[62:65], v[152:155], v[184:187], v[62:65]
	v_mfma_f32_16x16x32_bf16 v[58:61], v[160:163], v[184:187], v[58:61]
	v_mfma_f32_16x16x32_bf16 v[46:49], v[152:155], v[192:195], v[46:49]
	v_mfma_f32_16x16x32_bf16 v[42:45], v[160:163], v[192:195], v[42:45]
	v_mfma_f32_16x16x32_bf16 v[30:33], v[152:155], v[210:213], v[30:33]
	v_mfma_f32_16x16x32_bf16 v[26:29], v[160:163], v[210:213], v[26:29]
	v_mfma_f32_16x16x32_bf16 v[14:17], v[152:155], v[218:221], v[14:17]
	v_mfma_f32_16x16x32_bf16 v[10:13], v[160:163], v[218:221], v[10:13]
	v_mfma_f32_16x16x32_bf16 v[62:65], v[156:159], v[188:191], v[62:65]
	v_mfma_f32_16x16x32_bf16 v[58:61], v[164:167], v[188:191], v[58:61]
	v_mfma_f32_16x16x32_bf16 v[46:49], v[156:159], v[198:201], v[46:49]
	v_mfma_f32_16x16x32_bf16 v[42:45], v[164:167], v[198:201], v[42:45]
	v_mfma_f32_16x16x32_bf16 v[30:33], v[156:159], v[214:217], v[30:33]
	v_mfma_f32_16x16x32_bf16 v[26:29], v[164:167], v[214:217], v[26:29]
	v_mfma_f32_16x16x32_bf16 v[14:17], v[156:159], v[222:225], v[14:17]
	v_mfma_f32_16x16x32_bf16 v[10:13], v[164:167], v[222:225], v[10:13]
	s_setprio 0
	s_setprio 1
	v_mfma_f32_16x16x32_bf16 v[54:57], v[168:171], v[184:187], v[54:57]
	v_mfma_f32_16x16x32_bf16 v[50:53], v[176:179], v[184:187], v[50:53]
	v_mfma_f32_16x16x32_bf16 v[38:41], v[168:171], v[192:195], v[38:41]
	v_mfma_f32_16x16x32_bf16 v[34:37], v[176:179], v[192:195], v[34:37]
	v_mfma_f32_16x16x32_bf16 v[22:25], v[168:171], v[210:213], v[22:25]
	v_mfma_f32_16x16x32_bf16 v[18:21], v[176:179], v[210:213], v[18:21]
	v_mfma_f32_16x16x32_bf16 v[6:9], v[168:171], v[218:221], v[6:9]
	v_mfma_f32_16x16x32_bf16 v[2:5], v[176:179], v[218:221], v[2:5]
	v_mfma_f32_16x16x32_bf16 v[54:57], v[172:175], v[188:191], v[54:57]
	v_mfma_f32_16x16x32_bf16 v[50:53], v[180:183], v[188:191], v[50:53]
	v_mfma_f32_16x16x32_bf16 v[38:41], v[172:175], v[198:201], v[38:41]
	v_mfma_f32_16x16x32_bf16 v[34:37], v[180:183], v[198:201], v[34:37]
	v_mfma_f32_16x16x32_bf16 v[22:25], v[172:175], v[214:217], v[22:25]
	v_mfma_f32_16x16x32_bf16 v[18:21], v[180:183], v[214:217], v[18:21]
	v_mfma_f32_16x16x32_bf16 v[6:9], v[172:175], v[222:225], v[6:9]
	v_mfma_f32_16x16x32_bf16 v[2:5], v[180:183], v[222:225], v[2:5]
	s_setprio 0
	s_barrier
	s_add_u32 s30, s30, 0x100
	s_addc_u32 s31, s31, 0
	s_add_u32 s15, s15, 0x100
	s_addc_u32 s17, s17, 0
	s_cmp_ge_i32 s29, s68
	s_mov_b32 s19, s29
	s_cbranch_scc0 .LBB0_2547
	s_branch .Lpeeldone_1

.Lpeeldone_1:
	ds_read_b128 v[160:163], v148 offset:2048
	ds_read_b128 v[164:167], v148 offset:3072
	ds_read_b128 v[168:171], v149
	ds_read_b128 v[172:175], v149 offset:1024
	ds_read_b128 v[176:179], v149 offset:2048
	ds_read_b128 v[180:183], v149 offset:3072
	ds_read_b128 v[184:187], v150
	ds_read_b128 v[188:191], v150 offset:1024
	ds_read_b128 v[192:195], v150 offset:2048
	ds_read_b128 v[198:201], v150 offset:3072
	ds_read_b128 v[210:213], v150 offset:4096
	ds_read_b128 v[214:217], v150 offset:5120
	ds_read_b128 v[218:221], v150 offset:6144
	ds_read_b128 v[222:225], v150 offset:7168
	s_and_b64 vcc, exec, s[12:13]
	s_cbranch_vccnz .LBB0_2555
	s_cmp_gt_i32 s6, -1
	s_mov_b64 s[28:29], -1
	s_cbranch_scc1 .LBB0_2556
